# P4a on the 256-WG grid: merged = sB*((sA/sB)*GA + GB): GEMM1 epilogue scales the f32 accumulators in place (no Mo store), GEMM2 accumulates on top (no zero-init, no prev reload), GEMM2 epilogue applie
# speedup vs baseline: 1.0112x; 1.0112x over previous
; __device__ __forceinline__ unsigned cvt_pk_bf16(float lo, float hi) { unsigned r; asm volatile("v_cvt_pk_bf16_f32 %0, %1, %2" : "=v"(r) : "v"(lo), "v"(hi)); return r; }
; __device__ __forceinline__ float bflo(unsigned u) { return __uint_as_float(u << 16); }
; __device__ __forceinline__ float bfhi(unsigned u) { return __uint_as_float(u & 0xffff0000u); }
; __device__ __forceinline__ float sigm(float v) { return __builtin_amdgcn_rcpf(1.0f + __expf(-v)); }
; DI float bflo(unsigned u) { return __uint_as_float(u << 16); }
; DI float bfhi(unsigned u) { return __uint_as_float(u & 0xffff0000u); }
;     __device__ __forceinline__ void operator()(const f32x4 (&acc)[2][2][4][2], const Unit& u, int wr, int wc, int fr, int fq) const {
;         const int row0 = u.pm * BM + wr * 64 + fr; const int colt = u.pn * BM; const int t = colt / 512;
;         const bf16_t* gbase = G0 + (size_t)t * split_stride; const int col0 = colt + wc * 32 + 8 * fq, gcol0 = col0 - t * 512;
; #pragma unroll
;         for (int bj = 0; bj < 2; ++bj) {
;             const f32x4 b0 = *(const f32x4*)(gb + col0 + bj * HALF), b1 = *(const f32x4*)(gb + col0 + bj * HALF + 4);
; #pragma unroll
;             for (int ai = 0; ai < 2; ++ai)
; #pragma unroll
;                 for (int m = 0; m < 4; ++m) { const size_t row = (size_t)(row0 + ai * HALF + m * 16);
;                     const u32x4 g = *(const u32x4*)(gbase + row * 512 + gcol0 + bj * HALF);
;                     const f32x4 v0 = acc[ai][bj][m][0], v1 = acc[ai][bj][m][1];
;                     float r0 = v0[0] * sigm(bflo(g.x) + b0[0]), r1 = v0[1] * sigm(bfhi(g.x) + b0[1]), r2 = v0[2] * sigm(bflo(g.y) + b0[2]), r3 = v0[3] * sigm(bfhi(g.y) + b0[3]);
;                     float r4 = v1[0] * sigm(bflo(g.z) + b1[0]), r5 = v1[1] * sigm(bfhi(g.z) + b1[1]), r6 = v1[2] * sigm(bflo(g.w) + b1[2]), r7 = v1[3] * sigm(bfhi(g.w) + b1[3]);
;                     bf16_t* op = Mo + row * 1024 + col0 + bj * HALF;
;                     if (accum) { const u32x4 p = *(const u32x4*)op; r0 += bflo(p.x); r1 += bfhi(p.x); r2 += bflo(p.y); r3 += bfhi(p.y); r4 += bflo(p.z); r5 += bfhi(p.z); r6 += bflo(p.w); r7 += bfhi(p.w); }
;                     u32x4 w; w.x = cvt_pk_bf16(r0, r1); w.y = cvt_pk_bf16(r2, r3); w.z = cvt_pk_bf16(r4, r5); w.w = cvt_pk_bf16(r6, r7);
;                     *(u32x4*)op = w; }
.LBB0_880:
	v_readlane_b32 s100, v239, 56
	s_nop 0
	s_cmpk_eq_i32 s100, 0x100
	s_cbranch_scc1 .Lg1n_start
	s_lshr_b32 s2, s44, 31
	s_add_i32 s2, s44, s2
	s_ashr_i32 s24, s2, 1
	s_ashr_i32 s25, s24, 31
	s_lshl_b64 s[26:27], s[24:25], 24
	s_add_u32 s26, s36, s26
	s_addc_u32 s27, s37, s27
	v_lshl_or_b32 v154, s44, 8, v172
	s_lshl_b32 s2, s24, 9
	v_lshl_add_u32 v168, s22, 8, v1
	v_subrev_u32_e32 v114, s2, v154
	v_ashrrev_i32_e32 v115, 31, v114
	v_ashrrev_i32_e32 v169, 31, v168
	v_lshl_add_u64 v[170:171], v[114:115], 1, s[26:27]
	v_lshlrev_b64 v[114:115], 10, v[168:169]
	v_lshl_add_u64 v[158:159], v[170:171], 0, v[114:115]
	v_ashrrev_i32_e32 v155, 31, v154
	global_load_dwordx4 v[176:179], v[158:159], off
	v_lshl_add_u64 v[160:161], v[154:155], 2, s[78:79]
	global_load_dwordx4 v[118:121], v[160:161], off
	global_load_dwordx4 v[114:117], v[160:161], off offset:16
	v_lshlrev_b64 v[156:157], 11, v[168:169]
	v_or_b32_e32 v180, 16, v168
	v_lshlrev_b64 v[166:167], 1, v[154:155]
	v_ashrrev_i32_e32 v181, 31, v180
	v_lshl_add_u64 v[154:155], s[10:11], 0, v[156:157]
	v_lshlrev_b64 v[156:157], 10, v[180:181]
	v_lshl_add_u64 v[154:155], v[154:155], 0, v[166:167]
	v_lshl_add_u64 v[156:157], v[170:171], 0, v[156:157]
	s_andn2_b64 vcc, exec, s[6:7]
	s_mov_b64 s[6:7], -1
	v_mov_b32_e32 v250, v158
	v_mov_b32_e32 v251, v159
	s_mov_b64 s[98:99], 0x4000
	v_lshl_add_u64 v[248:249], v[250:251], 0, s[98:99]
	global_load_dwordx4 v[204:207], v[248:249], off
	s_mov_b64 s[98:99], 0x8000
	v_lshl_add_u64 v[248:249], v[250:251], 0, s[98:99]
	global_load_dwordx4 v[208:211], v[248:249], off
	s_mov_b64 s[98:99], 0xc000
	v_lshl_add_u64 v[248:249], v[250:251], 0, s[98:99]
	global_load_dwordx4 v[212:215], v[248:249], off
	s_mov_b64 s[98:99], 0x20000
	v_lshl_add_u64 v[248:249], v[250:251], 0, s[98:99]
	global_load_dwordx4 v[216:219], v[248:249], off
	s_mov_b64 s[98:99], 0x24000
	v_lshl_add_u64 v[248:249], v[250:251], 0, s[98:99]
	global_load_dwordx4 v[220:223], v[248:249], off
	s_mov_b64 s[98:99], 0x28000
	v_lshl_add_u64 v[248:249], v[250:251], 0, s[98:99]
	global_load_dwordx4 v[224:227], v[248:249], off
	s_mov_b64 s[98:99], 0x2c000
	v_lshl_add_u64 v[248:249], v[250:251], 0, s[98:99]
	global_load_dwordx4 v[188:191], v[248:249], off
	global_load_dwordx4 v[192:195], v[250:251], off offset:256
	s_mov_b64 s[98:99], 0x4000
	v_lshl_add_u64 v[248:249], v[250:251], 0, s[98:99]
	global_load_dwordx4 v[252:255], v[248:249], off offset:256
	global_load_dwordx4 v[240:243], v[160:161], off offset:512
	global_load_dwordx4 v[244:247], v[160:161], off offset:528
	s_waitcnt vmcnt(11)
	v_lshlrev_b32_e32 v184, 16, v179
	v_and_b32_e32 v179, 0xffff0000, v179
	v_lshlrev_b32_e32 v169, 16, v176
	v_and_b32_e32 v176, 0xffff0000, v176
	v_lshlrev_b32_e32 v182, 16, v177
	v_and_b32_e32 v177, 0xffff0000, v177
	v_lshlrev_b32_e32 v183, 16, v178
	v_and_b32_e32 v178, 0xffff0000, v178
	v_add_f32_e32 v179, v117, v179
	v_add_f32_e32 v169, v118, v169
	v_add_f32_e32 v176, v119, v176
	v_add_f32_e32 v182, v120, v182
	v_add_f32_e32 v177, v121, v177
	v_add_f32_e32 v183, v114, v183
	v_add_f32_e32 v178, v115, v178
	v_add_f32_e32 v184, v116, v184
	v_mul_f32_e32 v179, 0xbfb8aa3b, v179
	v_mul_f32_e32 v169, 0xbfb8aa3b, v169
	v_mul_f32_e32 v176, 0xbfb8aa3b, v176
	v_mul_f32_e32 v182, 0xbfb8aa3b, v182
	v_mul_f32_e32 v177, 0xbfb8aa3b, v177
	v_mul_f32_e32 v183, 0xbfb8aa3b, v183
	v_mul_f32_e32 v178, 0xbfb8aa3b, v178
	v_mul_f32_e32 v184, 0xbfb8aa3b, v184
	v_exp_f32_e32 v179, v179
	v_exp_f32_e32 v169, v169
	v_exp_f32_e32 v176, v176
	v_exp_f32_e32 v182, v182
	v_exp_f32_e32 v177, v177
	v_exp_f32_e32 v183, v183
	v_exp_f32_e32 v178, v178
	v_exp_f32_e32 v184, v184
	v_add_f32_e32 v179, 1.0, v179
	v_add_f32_e32 v169, 1.0, v169
	v_add_f32_e32 v176, 1.0, v176
	v_add_f32_e32 v182, 1.0, v182
	v_add_f32_e32 v177, 1.0, v177
	v_add_f32_e32 v183, 1.0, v183
	v_add_f32_e32 v178, 1.0, v178
	v_add_f32_e32 v184, 1.0, v184
	v_rcp_f32_e32 v179, v179
	v_rcp_f32_e32 v169, v169
	v_rcp_f32_e32 v176, v176
	v_rcp_f32_e32 v182, v182
	v_rcp_f32_e32 v177, v177
	v_rcp_f32_e32 v183, v183
	v_rcp_f32_e32 v178, v178
	v_rcp_f32_e32 v184, v184
	v_mul_f32_e32 v133, v133, v179
	v_mul_f32_e32 v134, v134, v169
	v_mul_f32_e32 v135, v135, v176
	v_mul_f32_e32 v136, v136, v182
	v_mul_f32_e32 v137, v137, v177
	v_mul_f32_e32 v169, v130, v183
	v_mul_f32_e32 v176, v131, v178
	v_mul_f32_e32 v177, v132, v184
	v_cvt_pk_bf16_f32 v130, v134, v135
	v_cvt_pk_bf16_f32 v131, v136, v137
	v_cvt_pk_bf16_f32 v132, v169, v176
	v_cvt_pk_bf16_f32 v133, v177, v133
	global_store_dwordx4 v[154:155], v[130:133], off
	s_nop 0
	v_or_b32_e32 v176, 32, v168
	v_lshlrev_b64 v[130:131], 11, v[180:181]
	v_ashrrev_i32_e32 v177, 31, v176
	v_lshl_add_u64 v[130:131], s[10:11], 0, v[130:131]
	v_lshlrev_b64 v[132:133], 10, v[176:177]
	v_lshl_add_u64 v[130:131], v[130:131], 0, v[166:167]
	v_lshl_add_u64 v[132:133], v[170:171], 0, v[132:133]
	s_waitcnt vmcnt(11)
; __device__ __forceinline__ unsigned cvt_pk_bf16(float lo, float hi) { unsigned r; asm volatile("v_cvt_pk_bf16_f32 %0, %1, %2" : "=v"(r) : "v"(lo), "v"(hi)); return r; }
; __device__ __forceinline__ float bflo(unsigned u) { return __uint_as_float(u << 16); }
; __device__ __forceinline__ float bfhi(unsigned u) { return __uint_as_float(u & 0xffff0000u); }
; __device__ __forceinline__ float sigm(float v) { return __builtin_amdgcn_rcpf(1.0f + __expf(-v)); }
; DI float bflo(unsigned u) { return __uint_as_float(u << 16); }
; DI float bfhi(unsigned u) { return __uint_as_float(u & 0xffff0000u); }
;     __device__ __forceinline__ void operator()(const f32x4 (&acc)[2][2][4][2], const Unit& u, int wr, int wc, int fr, int fq) const {
;     ...
;         for (int bj = 0; bj < 2; ++bj) {
;             const f32x4 b0 = *(const f32x4*)(gb + col0 + bj * HALF), b1 = *(const f32x4*)(gb + col0 + bj * HALF + 4);
; #pragma unroll
;             for (int ai = 0; ai < 2; ++ai)
; #pragma unroll
;                 for (int m = 0; m < 4; ++m) { const size_t row = (size_t)(row0 + ai * HALF + m * 16);
;                     const u32x4 g = *(const u32x4*)(gbase + row * 512 + gcol0 + bj * HALF);
;                     const f32x4 v0 = acc[ai][bj][m][0], v1 = acc[ai][bj][m][1];
;                     float r0 = v0[0] * sigm(bflo(g.x) + b0[0]), r1 = v0[1] * sigm(bfhi(g.x) + b0[1]), r2 = v0[2] * sigm(bflo(g.y) + b0[2]), r3 = v0[3] * sigm(bfhi(g.y) + b0[3]);
;                     float r4 = v1[0] * sigm(bflo(g.z) + b1[0]), r5 = v1[1] * sigm(bfhi(g.z) + b1[1]), r6 = v1[2] * sigm(bflo(g.w) + b1[2]), r7 = v1[3] * sigm(bfhi(g.w) + b1[3]);
;                     bf16_t* op = Mo + row * 1024 + col0 + bj * HALF;
;                     if (accum) { const u32x4 p = *(const u32x4*)op; r0 += bflo(p.x); r1 += bfhi(p.x); r2 += bflo(p.y); r3 += bfhi(p.y); r4 += bflo(p.z); r5 += bfhi(p.z); r6 += bflo(p.w); r7 += bfhi(p.w); }
;                     u32x4 w; w.x = cvt_pk_bf16(r0, r1); w.y = cvt_pk_bf16(r2, r3); w.z = cvt_pk_bf16(r4, r5); w.w = cvt_pk_bf16(r6, r7);
;                     *(u32x4*)op = w; }
	v_lshlrev_b32_e32 v180, 16, v207
	v_and_b32_e32 v137, 0xffff0000, v207
	v_lshlrev_b32_e32 v169, 16, v204
	v_and_b32_e32 v134, 0xffff0000, v204
	v_lshlrev_b32_e32 v178, 16, v205
	v_and_b32_e32 v135, 0xffff0000, v205
	v_lshlrev_b32_e32 v179, 16, v206
	v_and_b32_e32 v136, 0xffff0000, v206
	s_mov_b64 s[98:99], 0x8000
	v_lshl_add_u64 v[248:249], v[250:251], 0, s[98:99]
	global_load_dwordx4 v[204:207], v[248:249], off offset:256
	v_add_f32_e32 v137, v117, v137
	v_add_f32_e32 v169, v118, v169
	v_add_f32_e32 v134, v119, v134
	v_add_f32_e32 v178, v120, v178
	v_add_f32_e32 v135, v121, v135
	v_add_f32_e32 v179, v114, v179
	v_add_f32_e32 v136, v115, v136
	v_add_f32_e32 v180, v116, v180
	v_mul_f32_e32 v137, 0xbfb8aa3b, v137
	v_mul_f32_e32 v169, 0xbfb8aa3b, v169
	v_mul_f32_e32 v134, 0xbfb8aa3b, v134
	v_mul_f32_e32 v178, 0xbfb8aa3b, v178
	v_mul_f32_e32 v135, 0xbfb8aa3b, v135
	v_mul_f32_e32 v179, 0xbfb8aa3b, v179
	v_mul_f32_e32 v136, 0xbfb8aa3b, v136
	v_mul_f32_e32 v180, 0xbfb8aa3b, v180
	v_exp_f32_e32 v137, v137
	v_exp_f32_e32 v169, v169
	v_exp_f32_e32 v134, v134
	v_exp_f32_e32 v178, v178
	v_exp_f32_e32 v135, v135
	v_exp_f32_e32 v179, v179
	v_exp_f32_e32 v136, v136
	v_exp_f32_e32 v180, v180
	v_add_f32_e32 v137, 1.0, v137
	v_add_f32_e32 v169, 1.0, v169
	v_add_f32_e32 v134, 1.0, v134
	v_add_f32_e32 v178, 1.0, v178
	v_add_f32_e32 v135, 1.0, v135
	v_add_f32_e32 v179, 1.0, v179
	v_add_f32_e32 v136, 1.0, v136
	v_add_f32_e32 v180, 1.0, v180
	v_rcp_f32_e32 v137, v137
	v_rcp_f32_e32 v169, v169
	v_rcp_f32_e32 v134, v134
	v_rcp_f32_e32 v178, v178
	v_rcp_f32_e32 v135, v135
	v_rcp_f32_e32 v179, v179
	v_rcp_f32_e32 v136, v136
	v_rcp_f32_e32 v180, v180
	v_mul_f32_e32 v125, v125, v137
	v_mul_f32_e32 v126, v126, v169
	v_mul_f32_e32 v127, v127, v134
	v_mul_f32_e32 v128, v128, v178
	v_mul_f32_e32 v129, v129, v135
	v_mul_f32_e32 v134, v122, v179
	v_mul_f32_e32 v135, v123, v136
	v_mul_f32_e32 v136, v124, v180
	v_cvt_pk_bf16_f32 v122, v126, v127
	v_cvt_pk_bf16_f32 v123, v128, v129
	v_cvt_pk_bf16_f32 v124, v134, v135
	v_cvt_pk_bf16_f32 v125, v136, v125
	global_store_dwordx4 v[130:131], v[122:125], off
	s_nop 0
	v_or_b32_e32 v134, 48, v168
	v_lshlrev_b64 v[122:123], 11, v[176:177]
	v_ashrrev_i32_e32 v135, 31, v134
	v_lshl_add_u64 v[122:123], s[10:11], 0, v[122:123]
	v_lshlrev_b64 v[124:125], 10, v[134:135]
	v_lshl_add_u64 v[122:123], v[122:123], 0, v[166:167]
	v_lshl_add_u64 v[124:125], v[170:171], 0, v[124:125]
	s_waitcnt vmcnt(12)
	v_lshlrev_b32_e32 v176, 16, v211
	v_and_b32_e32 v129, 0xffff0000, v211
	v_lshlrev_b32_e32 v136, 16, v208
	v_and_b32_e32 v126, 0xffff0000, v208
	v_lshlrev_b32_e32 v137, 16, v209
	v_and_b32_e32 v127, 0xffff0000, v209
	v_lshlrev_b32_e32 v169, 16, v210
	v_and_b32_e32 v128, 0xffff0000, v210
	s_mov_b64 s[98:99], 0xc000
	v_lshl_add_u64 v[248:249], v[250:251], 0, s[98:99]
	global_load_dwordx4 v[208:211], v[248:249], off offset:256
	v_add_f32_e32 v129, v117, v129
	v_add_f32_e32 v136, v118, v136
	v_add_f32_e32 v126, v119, v126
	v_add_f32_e32 v137, v120, v137
	v_add_f32_e32 v127, v121, v127
	v_add_f32_e32 v169, v114, v169
	v_add_f32_e32 v128, v115, v128
	v_add_f32_e32 v176, v116, v176
	v_mul_f32_e32 v129, 0xbfb8aa3b, v129
	v_mul_f32_e32 v136, 0xbfb8aa3b, v136
	v_mul_f32_e32 v126, 0xbfb8aa3b, v126
	v_mul_f32_e32 v137, 0xbfb8aa3b, v137
	v_mul_f32_e32 v127, 0xbfb8aa3b, v127
	v_mul_f32_e32 v169, 0xbfb8aa3b, v169
	v_mul_f32_e32 v128, 0xbfb8aa3b, v128
	v_mul_f32_e32 v176, 0xbfb8aa3b, v176
	v_exp_f32_e32 v129, v129
	v_exp_f32_e32 v136, v136
	v_exp_f32_e32 v126, v126
	v_exp_f32_e32 v137, v137
	v_exp_f32_e32 v127, v127
	v_exp_f32_e32 v169, v169
	v_exp_f32_e32 v128, v128
	v_exp_f32_e32 v176, v176
	v_add_f32_e32 v129, 1.0, v129
	v_add_f32_e32 v136, 1.0, v136
	v_add_f32_e32 v126, 1.0, v126
	v_add_f32_e32 v137, 1.0, v137
	v_add_f32_e32 v127, 1.0, v127
	v_add_f32_e32 v169, 1.0, v169
	v_add_f32_e32 v128, 1.0, v128
	v_add_f32_e32 v176, 1.0, v176
	v_rcp_f32_e32 v129, v129
	v_rcp_f32_e32 v136, v136
	v_rcp_f32_e32 v126, v126
	v_rcp_f32_e32 v137, v137
	v_rcp_f32_e32 v127, v127
	v_rcp_f32_e32 v169, v169
	v_rcp_f32_e32 v128, v128
	v_rcp_f32_e32 v176, v176
	v_mul_f32_e32 v109, v109, v129
	v_mul_f32_e32 v110, v110, v136
	v_mul_f32_e32 v111, v111, v126
	v_mul_f32_e32 v112, v112, v137
	v_mul_f32_e32 v113, v113, v127
	v_mul_f32_e32 v126, v106, v169
	v_mul_f32_e32 v127, v107, v128
	v_mul_f32_e32 v128, v108, v176
	v_cvt_pk_bf16_f32 v106, v110, v111
	v_cvt_pk_bf16_f32 v107, v112, v113
	v_cvt_pk_bf16_f32 v108, v126, v127
	v_cvt_pk_bf16_f32 v109, v128, v109
	global_store_dwordx4 v[122:123], v[106:109], off
	s_nop 0
	v_add_u32_e32 v126, 0x80, v168
	v_lshlrev_b64 v[106:107], 11, v[134:135]
	v_ashrrev_i32_e32 v127, 31, v126
	v_lshl_add_u64 v[106:107], s[10:11], 0, v[106:107]
	v_lshlrev_b64 v[108:109], 10, v[126:127]
	v_lshl_add_u64 v[106:107], v[106:107], 0, v[166:167]
	v_lshl_add_u64 v[108:109], v[170:171], 0, v[108:109]
	s_waitcnt vmcnt(13)
; __device__ __forceinline__ unsigned cvt_pk_bf16(float lo, float hi) { unsigned r; asm volatile("v_cvt_pk_bf16_f32 %0, %1, %2" : "=v"(r) : "v"(lo), "v"(hi)); return r; }
; __device__ __forceinline__ float bflo(unsigned u) { return __uint_as_float(u << 16); }
; __device__ __forceinline__ float bfhi(unsigned u) { return __uint_as_float(u & 0xffff0000u); }
; __device__ __forceinline__ float sigm(float v) { return __builtin_amdgcn_rcpf(1.0f + __expf(-v)); }
; DI float bflo(unsigned u) { return __uint_as_float(u << 16); }
; DI float bfhi(unsigned u) { return __uint_as_float(u & 0xffff0000u); }
;     __device__ __forceinline__ void operator()(const f32x4 (&acc)[2][2][4][2], const Unit& u, int wr, int wc, int fr, int fq) const {
;     ...
;         for (int bj = 0; bj < 2; ++bj) {
;             const f32x4 b0 = *(const f32x4*)(gb + col0 + bj * HALF), b1 = *(const f32x4*)(gb + col0 + bj * HALF + 4);
; #pragma unroll
;             for (int ai = 0; ai < 2; ++ai)
; #pragma unroll
;                 for (int m = 0; m < 4; ++m) { const size_t row = (size_t)(row0 + ai * HALF + m * 16);
;                     const u32x4 g = *(const u32x4*)(gbase + row * 512 + gcol0 + bj * HALF);
;                     const f32x4 v0 = acc[ai][bj][m][0], v1 = acc[ai][bj][m][1];
;                     float r0 = v0[0] * sigm(bflo(g.x) + b0[0]), r1 = v0[1] * sigm(bfhi(g.x) + b0[1]), r2 = v0[2] * sigm(bflo(g.y) + b0[2]), r3 = v0[3] * sigm(bfhi(g.y) + b0[3]);
;                     float r4 = v1[0] * sigm(bflo(g.z) + b1[0]), r5 = v1[1] * sigm(bfhi(g.z) + b1[1]), r6 = v1[2] * sigm(bflo(g.w) + b1[2]), r7 = v1[3] * sigm(bfhi(g.w) + b1[3]);
;                     bf16_t* op = Mo + row * 1024 + col0 + bj * HALF;
;                     if (accum) { const u32x4 p = *(const u32x4*)op; r0 += bflo(p.x); r1 += bfhi(p.x); r2 += bflo(p.y); r3 += bfhi(p.y); r4 += bflo(p.z); r5 += bfhi(p.z); r6 += bflo(p.w); r7 += bfhi(p.w); }
;                     u32x4 w; w.x = cvt_pk_bf16(r0, r1); w.y = cvt_pk_bf16(r2, r3); w.z = cvt_pk_bf16(r4, r5); w.w = cvt_pk_bf16(r6, r7);
;                     *(u32x4*)op = w; }
	v_lshlrev_b32_e32 v135, 16, v215
	v_and_b32_e32 v113, 0xffff0000, v215
	v_lshlrev_b32_e32 v128, 16, v212
	v_and_b32_e32 v110, 0xffff0000, v212
	v_lshlrev_b32_e32 v129, 16, v213
	v_and_b32_e32 v111, 0xffff0000, v213
	v_lshlrev_b32_e32 v134, 16, v214
	v_and_b32_e32 v112, 0xffff0000, v214
	s_mov_b64 s[98:99], 0x20000
	v_lshl_add_u64 v[248:249], v[250:251], 0, s[98:99]
	global_load_dwordx4 v[212:215], v[248:249], off offset:256
	v_add_f32_e32 v113, v117, v113
	v_add_f32_e32 v128, v118, v128
	v_add_f32_e32 v110, v119, v110
	v_add_f32_e32 v129, v120, v129
	v_add_f32_e32 v111, v121, v111
	v_add_f32_e32 v134, v114, v134
	v_add_f32_e32 v112, v115, v112
	v_add_f32_e32 v135, v116, v135
	v_mul_f32_e32 v113, 0xbfb8aa3b, v113
	v_mul_f32_e32 v128, 0xbfb8aa3b, v128
	v_mul_f32_e32 v110, 0xbfb8aa3b, v110
	v_mul_f32_e32 v129, 0xbfb8aa3b, v129
	v_mul_f32_e32 v111, 0xbfb8aa3b, v111
	v_mul_f32_e32 v134, 0xbfb8aa3b, v134
	v_mul_f32_e32 v112, 0xbfb8aa3b, v112
	v_mul_f32_e32 v135, 0xbfb8aa3b, v135
	v_exp_f32_e32 v113, v113
	v_exp_f32_e32 v128, v128
	v_exp_f32_e32 v110, v110
	v_exp_f32_e32 v129, v129
	v_exp_f32_e32 v111, v111
	v_exp_f32_e32 v134, v134
	v_exp_f32_e32 v112, v112
	v_exp_f32_e32 v135, v135
	v_add_f32_e32 v113, 1.0, v113
	v_add_f32_e32 v128, 1.0, v128
	v_add_f32_e32 v110, 1.0, v110
	v_add_f32_e32 v129, 1.0, v129
	v_add_f32_e32 v111, 1.0, v111
	v_add_f32_e32 v134, 1.0, v134
	v_add_f32_e32 v112, 1.0, v112
	v_add_f32_e32 v135, 1.0, v135
	v_rcp_f32_e32 v113, v113
	v_rcp_f32_e32 v128, v128
	v_rcp_f32_e32 v110, v110
	v_rcp_f32_e32 v129, v129
	v_rcp_f32_e32 v111, v111
	v_rcp_f32_e32 v134, v134
	v_rcp_f32_e32 v112, v112
	v_rcp_f32_e32 v135, v135
	v_mul_f32_e32 v101, v101, v113
	v_mul_f32_e32 v102, v102, v128
	v_mul_f32_e32 v103, v103, v110
	v_mul_f32_e32 v104, v104, v129
	v_mul_f32_e32 v105, v105, v111
	v_mul_f32_e32 v110, v98, v134
	v_mul_f32_e32 v111, v99, v112
	v_mul_f32_e32 v112, v100, v135
	v_cvt_pk_bf16_f32 v98, v102, v103
	v_cvt_pk_bf16_f32 v99, v104, v105
	v_cvt_pk_bf16_f32 v100, v110, v111
	v_cvt_pk_bf16_f32 v101, v112, v101
	global_store_dwordx4 v[106:107], v[98:101], off
	s_nop 0
	v_add_u32_e32 v110, 0x90, v168
	v_lshlrev_b64 v[98:99], 11, v[126:127]
	v_ashrrev_i32_e32 v111, 31, v110
	v_lshl_add_u64 v[98:99], s[10:11], 0, v[98:99]
	v_lshlrev_b64 v[100:101], 10, v[110:111]
	v_lshl_add_u64 v[98:99], v[98:99], 0, v[166:167]
	v_lshl_add_u64 v[100:101], v[170:171], 0, v[100:101]
	s_waitcnt vmcnt(14)
	v_lshlrev_b32_e32 v127, 16, v219
	v_and_b32_e32 v105, 0xffff0000, v219
	v_lshlrev_b32_e32 v112, 16, v216
	v_and_b32_e32 v102, 0xffff0000, v216
	v_lshlrev_b32_e32 v113, 16, v217
	v_and_b32_e32 v103, 0xffff0000, v217
	v_lshlrev_b32_e32 v126, 16, v218
	v_and_b32_e32 v104, 0xffff0000, v218
	s_mov_b64 s[98:99], 0x24000
	v_lshl_add_u64 v[248:249], v[250:251], 0, s[98:99]
	global_load_dwordx4 v[216:219], v[248:249], off offset:256
	v_add_f32_e32 v105, v117, v105
	v_add_f32_e32 v112, v118, v112
	v_add_f32_e32 v102, v119, v102
	v_add_f32_e32 v113, v120, v113
	v_add_f32_e32 v103, v121, v103
	v_add_f32_e32 v126, v114, v126
	v_add_f32_e32 v104, v115, v104
	v_add_f32_e32 v127, v116, v127
	v_mul_f32_e32 v105, 0xbfb8aa3b, v105
	v_mul_f32_e32 v112, 0xbfb8aa3b, v112
	v_mul_f32_e32 v102, 0xbfb8aa3b, v102
	v_mul_f32_e32 v113, 0xbfb8aa3b, v113
	v_mul_f32_e32 v103, 0xbfb8aa3b, v103
	v_mul_f32_e32 v126, 0xbfb8aa3b, v126
	v_mul_f32_e32 v104, 0xbfb8aa3b, v104
	v_mul_f32_e32 v127, 0xbfb8aa3b, v127
	v_exp_f32_e32 v105, v105
	v_exp_f32_e32 v112, v112
	v_exp_f32_e32 v102, v102
	v_exp_f32_e32 v113, v113
	v_exp_f32_e32 v103, v103
	v_exp_f32_e32 v126, v126
	v_exp_f32_e32 v104, v104
	v_exp_f32_e32 v127, v127
	v_add_f32_e32 v105, 1.0, v105
	v_add_f32_e32 v112, 1.0, v112
	v_add_f32_e32 v102, 1.0, v102
	v_add_f32_e32 v113, 1.0, v113
	v_add_f32_e32 v103, 1.0, v103
	v_add_f32_e32 v126, 1.0, v126
	v_add_f32_e32 v104, 1.0, v104
	v_add_f32_e32 v127, 1.0, v127
	v_rcp_f32_e32 v105, v105
	v_rcp_f32_e32 v112, v112
	v_rcp_f32_e32 v102, v102
	v_rcp_f32_e32 v113, v113
	v_rcp_f32_e32 v103, v103
	v_rcp_f32_e32 v126, v126
	v_rcp_f32_e32 v104, v104
	v_rcp_f32_e32 v127, v127
	v_mul_f32_e32 v93, v93, v105
	v_mul_f32_e32 v94, v94, v112
	v_mul_f32_e32 v95, v95, v102
	v_mul_f32_e32 v96, v96, v113
	v_mul_f32_e32 v97, v97, v103
	v_mul_f32_e32 v102, v90, v126
	v_mul_f32_e32 v103, v91, v104
	v_mul_f32_e32 v104, v92, v127
	v_cvt_pk_bf16_f32 v90, v94, v95
	v_cvt_pk_bf16_f32 v91, v96, v97
	v_cvt_pk_bf16_f32 v92, v102, v103
	v_cvt_pk_bf16_f32 v93, v104, v93
	global_store_dwordx4 v[98:99], v[90:93], off
	s_nop 0
	v_add_u32_e32 v102, 0xa0, v168
	v_lshlrev_b64 v[90:91], 11, v[110:111]
	v_ashrrev_i32_e32 v103, 31, v102
	v_lshl_add_u64 v[90:91], s[10:11], 0, v[90:91]
	v_lshlrev_b64 v[92:93], 10, v[102:103]
	v_lshl_add_u64 v[90:91], v[90:91], 0, v[166:167]
	v_lshl_add_u64 v[92:93], v[170:171], 0, v[92:93]
	s_waitcnt vmcnt(15)
; __device__ __forceinline__ unsigned cvt_pk_bf16(float lo, float hi) { unsigned r; asm volatile("v_cvt_pk_bf16_f32 %0, %1, %2" : "=v"(r) : "v"(lo), "v"(hi)); return r; }
; __device__ __forceinline__ float bflo(unsigned u) { return __uint_as_float(u << 16); }
; __device__ __forceinline__ float bfhi(unsigned u) { return __uint_as_float(u & 0xffff0000u); }
; __device__ __forceinline__ float sigm(float v) { return __builtin_amdgcn_rcpf(1.0f + __expf(-v)); }
; DI float bflo(unsigned u) { return __uint_as_float(u << 16); }
; DI float bfhi(unsigned u) { return __uint_as_float(u & 0xffff0000u); }
;     __device__ __forceinline__ void operator()(const f32x4 (&acc)[2][2][4][2], const Unit& u, int wr, int wc, int fr, int fq) const {
;     ...
;         for (int bj = 0; bj < 2; ++bj) {
;             const f32x4 b0 = *(const f32x4*)(gb + col0 + bj * HALF), b1 = *(const f32x4*)(gb + col0 + bj * HALF + 4);
; #pragma unroll
;             for (int ai = 0; ai < 2; ++ai)
; #pragma unroll
;                 for (int m = 0; m < 4; ++m) { const size_t row = (size_t)(row0 + ai * HALF + m * 16);
;                     const u32x4 g = *(const u32x4*)(gbase + row * 512 + gcol0 + bj * HALF);
;                     const f32x4 v0 = acc[ai][bj][m][0], v1 = acc[ai][bj][m][1];
;                     float r0 = v0[0] * sigm(bflo(g.x) + b0[0]), r1 = v0[1] * sigm(bfhi(g.x) + b0[1]), r2 = v0[2] * sigm(bflo(g.y) + b0[2]), r3 = v0[3] * sigm(bfhi(g.y) + b0[3]);
;                     float r4 = v1[0] * sigm(bflo(g.z) + b1[0]), r5 = v1[1] * sigm(bfhi(g.z) + b1[1]), r6 = v1[2] * sigm(bflo(g.w) + b1[2]), r7 = v1[3] * sigm(bfhi(g.w) + b1[3]);
;                     bf16_t* op = Mo + row * 1024 + col0 + bj * HALF;
;                     if (accum) { const u32x4 p = *(const u32x4*)op; r0 += bflo(p.x); r1 += bfhi(p.x); r2 += bflo(p.y); r3 += bfhi(p.y); r4 += bflo(p.z); r5 += bfhi(p.z); r6 += bflo(p.w); r7 += bfhi(p.w); }
;                     u32x4 w; w.x = cvt_pk_bf16(r0, r1); w.y = cvt_pk_bf16(r2, r3); w.z = cvt_pk_bf16(r4, r5); w.w = cvt_pk_bf16(r6, r7);
;                     *(u32x4*)op = w; }
	v_lshlrev_b32_e32 v111, 16, v223
	v_and_b32_e32 v97, 0xffff0000, v223
	v_lshlrev_b32_e32 v104, 16, v220
	v_and_b32_e32 v94, 0xffff0000, v220
	v_lshlrev_b32_e32 v105, 16, v221
	v_and_b32_e32 v95, 0xffff0000, v221
	v_lshlrev_b32_e32 v110, 16, v222
	v_and_b32_e32 v96, 0xffff0000, v222
	s_mov_b64 s[98:99], 0x28000
	v_lshl_add_u64 v[248:249], v[250:251], 0, s[98:99]
	global_load_dwordx4 v[220:223], v[248:249], off offset:256
	v_add_f32_e32 v97, v117, v97
	v_add_f32_e32 v104, v118, v104
	v_add_f32_e32 v94, v119, v94
	v_add_f32_e32 v105, v120, v105
	v_add_f32_e32 v95, v121, v95
	v_add_f32_e32 v110, v114, v110
	v_add_f32_e32 v96, v115, v96
	v_add_f32_e32 v111, v116, v111
	v_mul_f32_e32 v97, 0xbfb8aa3b, v97
	v_mul_f32_e32 v104, 0xbfb8aa3b, v104
	v_mul_f32_e32 v94, 0xbfb8aa3b, v94
	v_mul_f32_e32 v105, 0xbfb8aa3b, v105
	v_mul_f32_e32 v95, 0xbfb8aa3b, v95
	v_mul_f32_e32 v110, 0xbfb8aa3b, v110
	v_mul_f32_e32 v96, 0xbfb8aa3b, v96
	v_mul_f32_e32 v111, 0xbfb8aa3b, v111
	v_exp_f32_e32 v97, v97
	v_exp_f32_e32 v104, v104
	v_exp_f32_e32 v94, v94
	v_exp_f32_e32 v105, v105
	v_exp_f32_e32 v95, v95
	v_exp_f32_e32 v110, v110
	v_exp_f32_e32 v96, v96
	v_exp_f32_e32 v111, v111
	v_add_f32_e32 v97, 1.0, v97
	v_add_f32_e32 v104, 1.0, v104
	v_add_f32_e32 v94, 1.0, v94
	v_add_f32_e32 v105, 1.0, v105
	v_add_f32_e32 v95, 1.0, v95
	v_add_f32_e32 v110, 1.0, v110
	v_add_f32_e32 v96, 1.0, v96
	v_add_f32_e32 v111, 1.0, v111
	v_rcp_f32_e32 v97, v97
	v_rcp_f32_e32 v104, v104
	v_rcp_f32_e32 v94, v94
	v_rcp_f32_e32 v105, v105
	v_rcp_f32_e32 v95, v95
	v_rcp_f32_e32 v110, v110
	v_rcp_f32_e32 v96, v96
	v_rcp_f32_e32 v111, v111
	v_mul_f32_e32 v85, v85, v97
	v_mul_f32_e32 v86, v86, v104
	v_mul_f32_e32 v87, v87, v94
	v_mul_f32_e32 v88, v88, v105
	v_mul_f32_e32 v89, v89, v95
	v_mul_f32_e32 v94, v82, v110
	v_mul_f32_e32 v95, v83, v96
	v_mul_f32_e32 v96, v84, v111
	v_cvt_pk_bf16_f32 v82, v86, v87
	v_cvt_pk_bf16_f32 v83, v88, v89
	v_cvt_pk_bf16_f32 v84, v94, v95
	v_cvt_pk_bf16_f32 v85, v96, v85
	global_store_dwordx4 v[90:91], v[82:85], off
	s_nop 0
	v_add_u32_e32 v94, 0xb0, v168
	v_lshlrev_b64 v[82:83], 11, v[102:103]
	v_ashrrev_i32_e32 v95, 31, v94
	v_lshl_add_u64 v[82:83], s[10:11], 0, v[82:83]
	v_lshlrev_b64 v[84:85], 10, v[94:95]
	v_lshl_add_u64 v[82:83], v[82:83], 0, v[166:167]
	v_lshl_add_u64 v[84:85], v[170:171], 0, v[84:85]
	s_waitcnt vmcnt(16)
	v_lshlrev_b32_e32 v103, 16, v227
	v_and_b32_e32 v89, 0xffff0000, v227
	v_lshlrev_b32_e32 v96, 16, v224
	v_and_b32_e32 v86, 0xffff0000, v224
	v_lshlrev_b32_e32 v97, 16, v225
	v_and_b32_e32 v87, 0xffff0000, v225
	v_lshlrev_b32_e32 v102, 16, v226
	v_and_b32_e32 v88, 0xffff0000, v226
	s_mov_b64 s[98:99], 0x2c000
	v_lshl_add_u64 v[248:249], v[250:251], 0, s[98:99]
	global_load_dwordx4 v[224:227], v[248:249], off offset:256
	v_add_f32_e32 v89, v117, v89
	v_add_f32_e32 v96, v118, v96
	v_add_f32_e32 v86, v119, v86
	v_add_f32_e32 v97, v120, v97
	v_add_f32_e32 v87, v121, v87
	v_add_f32_e32 v102, v114, v102
	v_add_f32_e32 v88, v115, v88
	v_add_f32_e32 v103, v116, v103
	v_mul_f32_e32 v89, 0xbfb8aa3b, v89
	v_mul_f32_e32 v96, 0xbfb8aa3b, v96
	v_mul_f32_e32 v86, 0xbfb8aa3b, v86
	v_mul_f32_e32 v97, 0xbfb8aa3b, v97
	v_mul_f32_e32 v87, 0xbfb8aa3b, v87
	v_mul_f32_e32 v102, 0xbfb8aa3b, v102
	v_mul_f32_e32 v88, 0xbfb8aa3b, v88
	v_mul_f32_e32 v103, 0xbfb8aa3b, v103
	v_exp_f32_e32 v89, v89
	v_exp_f32_e32 v96, v96
	v_exp_f32_e32 v86, v86
	v_exp_f32_e32 v97, v97
	v_exp_f32_e32 v87, v87
	v_exp_f32_e32 v102, v102
	v_exp_f32_e32 v88, v88
	v_exp_f32_e32 v103, v103
	v_add_f32_e32 v89, 1.0, v89
	v_add_f32_e32 v96, 1.0, v96
	v_add_f32_e32 v86, 1.0, v86
	v_add_f32_e32 v97, 1.0, v97
	v_add_f32_e32 v87, 1.0, v87
	v_add_f32_e32 v102, 1.0, v102
	v_add_f32_e32 v88, 1.0, v88
	v_add_f32_e32 v103, 1.0, v103
	v_rcp_f32_e32 v89, v89
	v_rcp_f32_e32 v96, v96
	v_rcp_f32_e32 v86, v86
	v_rcp_f32_e32 v97, v97
	v_rcp_f32_e32 v87, v87
	v_rcp_f32_e32 v102, v102
	v_rcp_f32_e32 v88, v88
	v_rcp_f32_e32 v103, v103
	v_mul_f32_e32 v77, v77, v89
	v_mul_f32_e32 v78, v78, v96
	v_mul_f32_e32 v79, v79, v86
	v_mul_f32_e32 v80, v80, v97
	v_mul_f32_e32 v81, v81, v87
	v_mul_f32_e32 v86, v74, v102
	v_mul_f32_e32 v87, v75, v88
	v_mul_f32_e32 v88, v76, v103
	v_cvt_pk_bf16_f32 v74, v78, v79
	v_cvt_pk_bf16_f32 v75, v80, v81
	v_cvt_pk_bf16_f32 v76, v86, v87
	v_cvt_pk_bf16_f32 v77, v88, v77
	global_store_dwordx4 v[82:83], v[74:77], off
	s_nop 0
	s_waitcnt vmcnt(17)
	v_lshlrev_b32_e32 v87, 16, v191
	v_and_b32_e32 v79, 0xffff0000, v191
	v_lshlrev_b32_e32 v80, 16, v188
	v_and_b32_e32 v76, 0xffff0000, v188
	v_lshlrev_b32_e32 v81, 16, v189
	v_and_b32_e32 v77, 0xffff0000, v189
	v_lshlrev_b32_e32 v86, 16, v190
	v_and_b32_e32 v78, 0xffff0000, v190
	v_add_f32_e32 v79, v117, v79
	v_add_f32_e32 v80, v118, v80
	v_add_f32_e32 v76, v119, v76
	v_add_f32_e32 v81, v120, v81
	v_add_f32_e32 v77, v121, v77
	v_add_f32_e32 v86, v114, v86
	v_add_f32_e32 v78, v115, v78
	v_add_f32_e32 v87, v116, v87
	v_mul_f32_e32 v79, 0xbfb8aa3b, v79
	v_mul_f32_e32 v80, 0xbfb8aa3b, v80
	v_mul_f32_e32 v76, 0xbfb8aa3b, v76
	v_mul_f32_e32 v81, 0xbfb8aa3b, v81
	v_mul_f32_e32 v77, 0xbfb8aa3b, v77
	v_mul_f32_e32 v86, 0xbfb8aa3b, v86
	v_mul_f32_e32 v78, 0xbfb8aa3b, v78
	v_mul_f32_e32 v87, 0xbfb8aa3b, v87
	v_exp_f32_e32 v79, v79
	v_exp_f32_e32 v80, v80
	v_exp_f32_e32 v76, v76
	v_exp_f32_e32 v81, v81
	v_exp_f32_e32 v77, v77
	v_exp_f32_e32 v86, v86
	v_exp_f32_e32 v78, v78
	v_exp_f32_e32 v87, v87
	v_add_f32_e32 v79, 1.0, v79
	v_add_f32_e32 v80, 1.0, v80
	v_add_f32_e32 v76, 1.0, v76
	v_add_f32_e32 v81, 1.0, v81
	v_add_f32_e32 v77, 1.0, v77
	v_add_f32_e32 v86, 1.0, v86
	v_add_f32_e32 v78, 1.0, v78
	v_add_f32_e32 v87, 1.0, v87
	v_rcp_f32_e32 v79, v79
	v_rcp_f32_e32 v80, v80
	v_rcp_f32_e32 v76, v76
	v_rcp_f32_e32 v81, v81
	v_rcp_f32_e32 v77, v77
	v_rcp_f32_e32 v86, v86
	v_rcp_f32_e32 v78, v78
	v_rcp_f32_e32 v87, v87
	v_lshlrev_b64 v[74:75], 11, v[94:95]
	v_lshl_add_u64 v[74:75], s[10:11], 0, v[74:75]
	v_lshl_add_u64 v[74:75], v[74:75], 0, v[166:167]
	v_mul_f32_e32 v69, v69, v79
	v_mul_f32_e32 v70, v70, v80
	v_mul_f32_e32 v71, v71, v76
	v_mul_f32_e32 v72, v72, v81
	v_mul_f32_e32 v73, v73, v77
	v_mul_f32_e32 v76, v66, v86
	v_mul_f32_e32 v77, v67, v78
	v_mul_f32_e32 v78, v68, v87
	v_cvt_pk_bf16_f32 v66, v70, v71
	v_cvt_pk_bf16_f32 v67, v72, v73
	v_cvt_pk_bf16_f32 v68, v76, v77
	v_cvt_pk_bf16_f32 v69, v78, v69
	global_store_dwordx4 v[74:75], v[66:69], off
	s_nop 0
	v_mov_b32_e32 v70, v240
	v_mov_b32_e32 v71, v241
	v_mov_b32_e32 v72, v242
	v_mov_b32_e32 v73, v243
	s_nop 0
	v_mov_b32_e32 v66, v244
	v_mov_b32_e32 v67, v245
	v_mov_b32_e32 v68, v246
	v_mov_b32_e32 v69, v247
	s_waitcnt vmcnt(14)
; __device__ __forceinline__ unsigned cvt_pk_bf16(float lo, float hi) { unsigned r; asm volatile("v_cvt_pk_bf16_f32 %0, %1, %2" : "=v"(r) : "v"(lo), "v"(hi)); return r; }
; __device__ __forceinline__ float bflo(unsigned u) { return __uint_as_float(u << 16); }
; __device__ __forceinline__ float bfhi(unsigned u) { return __uint_as_float(u & 0xffff0000u); }
; __device__ __forceinline__ float sigm(float v) { return __builtin_amdgcn_rcpf(1.0f + __expf(-v)); }
; DI float bflo(unsigned u) { return __uint_as_float(u << 16); }
; DI float bfhi(unsigned u) { return __uint_as_float(u & 0xffff0000u); }
;     __device__ __forceinline__ void operator()(const f32x4 (&acc)[2][2][4][2], const Unit& u, int wr, int wc, int fr, int fq) const {
;     ...
;         for (int bj = 0; bj < 2; ++bj) {
;             const f32x4 b0 = *(const f32x4*)(gb + col0 + bj * HALF), b1 = *(const f32x4*)(gb + col0 + bj * HALF + 4);
; #pragma unroll
;             for (int ai = 0; ai < 2; ++ai)
; #pragma unroll
;                 for (int m = 0; m < 4; ++m) { const size_t row = (size_t)(row0 + ai * HALF + m * 16);
;                     const u32x4 g = *(const u32x4*)(gbase + row * 512 + gcol0 + bj * HALF);
;                     const f32x4 v0 = acc[ai][bj][m][0], v1 = acc[ai][bj][m][1];
;                     float r0 = v0[0] * sigm(bflo(g.x) + b0[0]), r1 = v0[1] * sigm(bfhi(g.x) + b0[1]), r2 = v0[2] * sigm(bflo(g.y) + b0[2]), r3 = v0[3] * sigm(bfhi(g.y) + b0[3]);
;                     float r4 = v1[0] * sigm(bflo(g.z) + b1[0]), r5 = v1[1] * sigm(bfhi(g.z) + b1[1]), r6 = v1[2] * sigm(bflo(g.w) + b1[2]), r7 = v1[3] * sigm(bfhi(g.w) + b1[3]);
;                     bf16_t* op = Mo + row * 1024 + col0 + bj * HALF;
;                     if (accum) { const u32x4 p = *(const u32x4*)op; r0 += bflo(p.x); r1 += bfhi(p.x); r2 += bflo(p.y); r3 += bfhi(p.y); r4 += bflo(p.z); r5 += bfhi(p.z); r6 += bflo(p.w); r7 += bfhi(p.w); }
;                     u32x4 w; w.x = cvt_pk_bf16(r0, r1); w.y = cvt_pk_bf16(r2, r3); w.z = cvt_pk_bf16(r4, r5); w.w = cvt_pk_bf16(r6, r7);
;                     *(u32x4*)op = w; }
	v_lshlrev_b32_e32 v87, 16, v195
	v_and_b32_e32 v79, 0xffff0000, v195
	v_lshlrev_b32_e32 v80, 16, v192
	v_and_b32_e32 v76, 0xffff0000, v192
	v_lshlrev_b32_e32 v81, 16, v193
	v_and_b32_e32 v77, 0xffff0000, v193
	v_lshlrev_b32_e32 v86, 16, v194
	v_and_b32_e32 v78, 0xffff0000, v194
	s_nop 0
	v_add_f32_e32 v79, v69, v79
	v_add_f32_e32 v80, v70, v80
	v_add_f32_e32 v76, v71, v76
	v_add_f32_e32 v81, v72, v81
	v_add_f32_e32 v77, v73, v77
	v_add_f32_e32 v86, v66, v86
	v_add_f32_e32 v78, v67, v78
	v_add_f32_e32 v87, v68, v87
	v_mul_f32_e32 v79, 0xbfb8aa3b, v79
	v_mul_f32_e32 v80, 0xbfb8aa3b, v80
	v_mul_f32_e32 v76, 0xbfb8aa3b, v76
	v_mul_f32_e32 v81, 0xbfb8aa3b, v81
	v_mul_f32_e32 v77, 0xbfb8aa3b, v77
	v_mul_f32_e32 v86, 0xbfb8aa3b, v86
	v_mul_f32_e32 v78, 0xbfb8aa3b, v78
	v_mul_f32_e32 v87, 0xbfb8aa3b, v87
	v_exp_f32_e32 v79, v79
	v_exp_f32_e32 v80, v80
	v_exp_f32_e32 v76, v76
	v_exp_f32_e32 v81, v81
	v_exp_f32_e32 v77, v77
	v_exp_f32_e32 v86, v86
	v_exp_f32_e32 v78, v78
	v_exp_f32_e32 v87, v87
	v_add_f32_e32 v79, 1.0, v79
	v_add_f32_e32 v80, 1.0, v80
	v_add_f32_e32 v76, 1.0, v76
	v_add_f32_e32 v81, 1.0, v81
	v_add_f32_e32 v77, 1.0, v77
	v_add_f32_e32 v86, 1.0, v86
	v_add_f32_e32 v78, 1.0, v78
	v_add_f32_e32 v87, 1.0, v87
	v_rcp_f32_e32 v79, v79
	v_rcp_f32_e32 v80, v80
	v_rcp_f32_e32 v76, v76
	v_rcp_f32_e32 v81, v81
	v_rcp_f32_e32 v77, v77
	v_rcp_f32_e32 v86, v86
	v_rcp_f32_e32 v78, v78
	v_rcp_f32_e32 v87, v87
	v_mul_f32_e32 v61, v61, v79
	v_mul_f32_e32 v62, v62, v80
	v_mul_f32_e32 v63, v63, v76
	v_mul_f32_e32 v64, v64, v81
	v_mul_f32_e32 v65, v65, v77
	v_mul_f32_e32 v76, v58, v86
	v_mul_f32_e32 v77, v59, v78
	v_mul_f32_e32 v78, v60, v87
	v_cvt_pk_bf16_f32 v58, v62, v63
	v_cvt_pk_bf16_f32 v59, v64, v65
	v_cvt_pk_bf16_f32 v60, v76, v77
	v_cvt_pk_bf16_f32 v61, v78, v61
	global_store_dwordx4 v[154:155], v[58:61], off offset:256
	s_nop 0
	s_waitcnt vmcnt(17)
	v_lshlrev_b32_e32 v65, 16, v255
	v_and_b32_e32 v61, 0xffff0000, v255
	v_lshlrev_b32_e32 v62, 16, v252
	v_and_b32_e32 v58, 0xffff0000, v252
	v_lshlrev_b32_e32 v63, 16, v253
	v_and_b32_e32 v59, 0xffff0000, v253
	v_lshlrev_b32_e32 v64, 16, v254
	v_and_b32_e32 v60, 0xffff0000, v254
	v_add_f32_e32 v61, v69, v61
	v_add_f32_e32 v62, v70, v62
	v_add_f32_e32 v58, v71, v58
	v_add_f32_e32 v63, v72, v63
	v_add_f32_e32 v59, v73, v59
	v_add_f32_e32 v64, v66, v64
	v_add_f32_e32 v60, v67, v60
	v_add_f32_e32 v65, v68, v65
	v_mul_f32_e32 v61, 0xbfb8aa3b, v61
	v_mul_f32_e32 v62, 0xbfb8aa3b, v62
	v_mul_f32_e32 v58, 0xbfb8aa3b, v58
	v_mul_f32_e32 v63, 0xbfb8aa3b, v63
	v_mul_f32_e32 v59, 0xbfb8aa3b, v59
	v_mul_f32_e32 v64, 0xbfb8aa3b, v64
	v_mul_f32_e32 v60, 0xbfb8aa3b, v60
	v_mul_f32_e32 v65, 0xbfb8aa3b, v65
	v_exp_f32_e32 v61, v61
	v_exp_f32_e32 v62, v62
	v_exp_f32_e32 v58, v58
	v_exp_f32_e32 v63, v63
	v_exp_f32_e32 v59, v59
	v_exp_f32_e32 v64, v64
	v_exp_f32_e32 v60, v60
	v_exp_f32_e32 v65, v65
	v_add_f32_e32 v61, 1.0, v61
	v_add_f32_e32 v62, 1.0, v62
	v_add_f32_e32 v58, 1.0, v58
	v_add_f32_e32 v63, 1.0, v63
	v_add_f32_e32 v59, 1.0, v59
	v_add_f32_e32 v64, 1.0, v64
	v_add_f32_e32 v60, 1.0, v60
	v_add_f32_e32 v65, 1.0, v65
	v_rcp_f32_e32 v61, v61
	v_rcp_f32_e32 v62, v62
	v_rcp_f32_e32 v58, v58
	v_rcp_f32_e32 v63, v63
	v_rcp_f32_e32 v59, v59
	v_rcp_f32_e32 v64, v64
	v_rcp_f32_e32 v60, v60
	v_rcp_f32_e32 v65, v65
	v_mul_f32_e32 v53, v53, v61
	v_mul_f32_e32 v54, v54, v62
	v_mul_f32_e32 v55, v55, v58
	v_mul_f32_e32 v56, v56, v63
	v_mul_f32_e32 v57, v57, v59
	v_mul_f32_e32 v58, v50, v64
	v_mul_f32_e32 v59, v51, v60
	v_mul_f32_e32 v60, v52, v65
	v_cvt_pk_bf16_f32 v50, v54, v55
	v_cvt_pk_bf16_f32 v51, v56, v57
	v_cvt_pk_bf16_f32 v52, v58, v59
	v_cvt_pk_bf16_f32 v53, v60, v53
	global_store_dwordx4 v[130:131], v[50:53], off offset:256
	s_nop 0
	s_waitcnt vmcnt(14)
	v_lshlrev_b32_e32 v57, 16, v207
	v_and_b32_e32 v53, 0xffff0000, v207
	v_lshlrev_b32_e32 v54, 16, v204
	v_and_b32_e32 v50, 0xffff0000, v204
	v_lshlrev_b32_e32 v55, 16, v205
	v_and_b32_e32 v51, 0xffff0000, v205
	v_lshlrev_b32_e32 v56, 16, v206
	v_and_b32_e32 v52, 0xffff0000, v206
	v_add_f32_e32 v53, v69, v53
	v_add_f32_e32 v54, v70, v54
	v_add_f32_e32 v50, v71, v50
	v_add_f32_e32 v55, v72, v55
	v_add_f32_e32 v51, v73, v51
	v_add_f32_e32 v56, v66, v56
	v_add_f32_e32 v52, v67, v52
	v_add_f32_e32 v57, v68, v57
	v_mul_f32_e32 v53, 0xbfb8aa3b, v53
	v_mul_f32_e32 v54, 0xbfb8aa3b, v54
	v_mul_f32_e32 v50, 0xbfb8aa3b, v50
	v_mul_f32_e32 v55, 0xbfb8aa3b, v55
	v_mul_f32_e32 v51, 0xbfb8aa3b, v51
	v_mul_f32_e32 v56, 0xbfb8aa3b, v56
	v_mul_f32_e32 v52, 0xbfb8aa3b, v52
	v_mul_f32_e32 v57, 0xbfb8aa3b, v57
	v_exp_f32_e32 v53, v53
	v_exp_f32_e32 v54, v54
	v_exp_f32_e32 v50, v50
	v_exp_f32_e32 v55, v55
	v_exp_f32_e32 v51, v51
	v_exp_f32_e32 v56, v56
	v_exp_f32_e32 v52, v52
	v_exp_f32_e32 v57, v57
	v_add_f32_e32 v53, 1.0, v53
	v_add_f32_e32 v54, 1.0, v54
	v_add_f32_e32 v50, 1.0, v50
	v_add_f32_e32 v55, 1.0, v55
	v_add_f32_e32 v51, 1.0, v51
	v_add_f32_e32 v56, 1.0, v56
	v_add_f32_e32 v52, 1.0, v52
	v_add_f32_e32 v57, 1.0, v57
	v_rcp_f32_e32 v53, v53
	v_rcp_f32_e32 v54, v54
	v_rcp_f32_e32 v50, v50
	v_rcp_f32_e32 v55, v55
	v_rcp_f32_e32 v51, v51
	v_rcp_f32_e32 v56, v56
	v_rcp_f32_e32 v52, v52
	v_rcp_f32_e32 v57, v57
	v_mul_f32_e32 v45, v45, v53
	v_mul_f32_e32 v46, v46, v54
	v_mul_f32_e32 v47, v47, v50
	v_mul_f32_e32 v48, v48, v55
	v_mul_f32_e32 v49, v49, v51
	v_mul_f32_e32 v50, v42, v56
	v_mul_f32_e32 v51, v43, v52
	v_mul_f32_e32 v52, v44, v57
	v_cvt_pk_bf16_f32 v42, v46, v47
	v_cvt_pk_bf16_f32 v43, v48, v49
	v_cvt_pk_bf16_f32 v44, v50, v51
	v_cvt_pk_bf16_f32 v45, v52, v45
	global_store_dwordx4 v[122:123], v[42:45], off offset:256
	s_nop 0
	s_waitcnt vmcnt(13)
; __device__ __forceinline__ unsigned cvt_pk_bf16(float lo, float hi) { unsigned r; asm volatile("v_cvt_pk_bf16_f32 %0, %1, %2" : "=v"(r) : "v"(lo), "v"(hi)); return r; }
; __device__ __forceinline__ float bflo(unsigned u) { return __uint_as_float(u << 16); }
; __device__ __forceinline__ float bfhi(unsigned u) { return __uint_as_float(u & 0xffff0000u); }
; __device__ __forceinline__ float sigm(float v) { return __builtin_amdgcn_rcpf(1.0f + __expf(-v)); }
; DI float bflo(unsigned u) { return __uint_as_float(u << 16); }
; DI float bfhi(unsigned u) { return __uint_as_float(u & 0xffff0000u); }
;     __device__ __forceinline__ void operator()(const f32x4 (&acc)[2][2][4][2], const Unit& u, int wr, int wc, int fr, int fq) const {
;     ...
;                 for (int m = 0; m < 4; ++m) { const size_t row = (size_t)(row0 + ai * HALF + m * 16);
;                     const u32x4 g = *(const u32x4*)(gbase + row * 512 + gcol0 + bj * HALF);
;                     const f32x4 v0 = acc[ai][bj][m][0], v1 = acc[ai][bj][m][1];
;                     float r0 = v0[0] * sigm(bflo(g.x) + b0[0]), r1 = v0[1] * sigm(bfhi(g.x) + b0[1]), r2 = v0[2] * sigm(bflo(g.y) + b0[2]), r3 = v0[3] * sigm(bfhi(g.y) + b0[3]);
;                     float r4 = v1[0] * sigm(bflo(g.z) + b1[0]), r5 = v1[1] * sigm(bfhi(g.z) + b1[1]), r6 = v1[2] * sigm(bflo(g.w) + b1[2]), r7 = v1[3] * sigm(bfhi(g.w) + b1[3]);
;                     bf16_t* op = Mo + row * 1024 + col0 + bj * HALF;
;                     if (accum) { const u32x4 p = *(const u32x4*)op; r0 += bflo(p.x); r1 += bfhi(p.x); r2 += bflo(p.y); r3 += bfhi(p.y); r4 += bflo(p.z); r5 += bfhi(p.z); r6 += bflo(p.w); r7 += bfhi(p.w); }
;                     u32x4 w; w.x = cvt_pk_bf16(r0, r1); w.y = cvt_pk_bf16(r2, r3); w.z = cvt_pk_bf16(r4, r5); w.w = cvt_pk_bf16(r6, r7);
;                     *(u32x4*)op = w; }
	v_lshlrev_b32_e32 v49, 16, v211
	v_and_b32_e32 v45, 0xffff0000, v211
	v_lshlrev_b32_e32 v46, 16, v208
	v_and_b32_e32 v42, 0xffff0000, v208
	v_lshlrev_b32_e32 v47, 16, v209
	v_and_b32_e32 v43, 0xffff0000, v209
	v_lshlrev_b32_e32 v48, 16, v210
	v_and_b32_e32 v44, 0xffff0000, v210
	v_add_f32_e32 v45, v69, v45
	v_add_f32_e32 v46, v70, v46
	v_add_f32_e32 v42, v71, v42
	v_add_f32_e32 v47, v72, v47
	v_add_f32_e32 v43, v73, v43
	v_add_f32_e32 v48, v66, v48
	v_add_f32_e32 v44, v67, v44
	v_add_f32_e32 v49, v68, v49
	v_mul_f32_e32 v45, 0xbfb8aa3b, v45
	v_mul_f32_e32 v46, 0xbfb8aa3b, v46
	v_mul_f32_e32 v42, 0xbfb8aa3b, v42
	v_mul_f32_e32 v47, 0xbfb8aa3b, v47
	v_mul_f32_e32 v43, 0xbfb8aa3b, v43
	v_mul_f32_e32 v48, 0xbfb8aa3b, v48
	v_mul_f32_e32 v44, 0xbfb8aa3b, v44
	v_mul_f32_e32 v49, 0xbfb8aa3b, v49
	v_exp_f32_e32 v45, v45
	v_exp_f32_e32 v46, v46
	v_exp_f32_e32 v42, v42
	v_exp_f32_e32 v47, v47
	v_exp_f32_e32 v43, v43
	v_exp_f32_e32 v48, v48
	v_exp_f32_e32 v44, v44
	v_exp_f32_e32 v49, v49
	v_add_f32_e32 v45, 1.0, v45
	v_add_f32_e32 v46, 1.0, v46
	v_add_f32_e32 v42, 1.0, v42
	v_add_f32_e32 v47, 1.0, v47
	v_add_f32_e32 v43, 1.0, v43
	v_add_f32_e32 v48, 1.0, v48
	v_add_f32_e32 v44, 1.0, v44
	v_add_f32_e32 v49, 1.0, v49
	v_rcp_f32_e32 v45, v45
	v_rcp_f32_e32 v46, v46
	v_rcp_f32_e32 v42, v42
	v_rcp_f32_e32 v47, v47
	v_rcp_f32_e32 v43, v43
	v_rcp_f32_e32 v48, v48
	v_rcp_f32_e32 v44, v44
	v_rcp_f32_e32 v49, v49
	v_mul_f32_e32 v37, v37, v45
	v_mul_f32_e32 v38, v38, v46
	v_mul_f32_e32 v39, v39, v42
	v_mul_f32_e32 v40, v40, v47
	v_mul_f32_e32 v41, v41, v43
	v_mul_f32_e32 v42, v34, v48
	v_mul_f32_e32 v43, v35, v44
	v_mul_f32_e32 v44, v36, v49
	v_cvt_pk_bf16_f32 v34, v38, v39
	v_cvt_pk_bf16_f32 v35, v40, v41
	v_cvt_pk_bf16_f32 v36, v42, v43
	v_cvt_pk_bf16_f32 v37, v44, v37
	global_store_dwordx4 v[106:107], v[34:37], off offset:256
	s_nop 0
	s_waitcnt vmcnt(12)
	v_lshlrev_b32_e32 v41, 16, v215
	v_and_b32_e32 v37, 0xffff0000, v215
	v_lshlrev_b32_e32 v38, 16, v212
	v_and_b32_e32 v34, 0xffff0000, v212
	v_lshlrev_b32_e32 v39, 16, v213
	v_and_b32_e32 v35, 0xffff0000, v213
	v_lshlrev_b32_e32 v40, 16, v214
	v_and_b32_e32 v36, 0xffff0000, v214
	v_add_f32_e32 v37, v69, v37
	v_add_f32_e32 v38, v70, v38
	v_add_f32_e32 v34, v71, v34
	v_add_f32_e32 v39, v72, v39
	v_add_f32_e32 v35, v73, v35
	v_add_f32_e32 v40, v66, v40
	v_add_f32_e32 v36, v67, v36
	v_add_f32_e32 v41, v68, v41
	v_mul_f32_e32 v37, 0xbfb8aa3b, v37
	v_mul_f32_e32 v38, 0xbfb8aa3b, v38
	v_mul_f32_e32 v34, 0xbfb8aa3b, v34
	v_mul_f32_e32 v39, 0xbfb8aa3b, v39
	v_mul_f32_e32 v35, 0xbfb8aa3b, v35
	v_mul_f32_e32 v40, 0xbfb8aa3b, v40
	v_mul_f32_e32 v36, 0xbfb8aa3b, v36
	v_mul_f32_e32 v41, 0xbfb8aa3b, v41
	v_exp_f32_e32 v37, v37
	v_exp_f32_e32 v38, v38
	v_exp_f32_e32 v34, v34
	v_exp_f32_e32 v39, v39
	v_exp_f32_e32 v35, v35
	v_exp_f32_e32 v40, v40
	v_exp_f32_e32 v36, v36
	v_exp_f32_e32 v41, v41
	v_add_f32_e32 v37, 1.0, v37
	v_add_f32_e32 v38, 1.0, v38
	v_add_f32_e32 v34, 1.0, v34
	v_add_f32_e32 v39, 1.0, v39
	v_add_f32_e32 v35, 1.0, v35
	v_add_f32_e32 v40, 1.0, v40
	v_add_f32_e32 v36, 1.0, v36
	v_add_f32_e32 v41, 1.0, v41
	v_rcp_f32_e32 v37, v37
	v_rcp_f32_e32 v38, v38
	v_rcp_f32_e32 v34, v34
	v_rcp_f32_e32 v39, v39
	v_rcp_f32_e32 v35, v35
	v_rcp_f32_e32 v40, v40
	v_rcp_f32_e32 v36, v36
	v_rcp_f32_e32 v41, v41
	v_mul_f32_e32 v29, v29, v37
	v_mul_f32_e32 v30, v30, v38
	v_mul_f32_e32 v31, v31, v34
	v_mul_f32_e32 v32, v32, v39
	v_mul_f32_e32 v33, v33, v35
	v_mul_f32_e32 v34, v26, v40
	v_mul_f32_e32 v35, v27, v36
	v_mul_f32_e32 v36, v28, v41
	v_cvt_pk_bf16_f32 v26, v30, v31
	v_cvt_pk_bf16_f32 v27, v32, v33
	v_cvt_pk_bf16_f32 v28, v34, v35
	v_cvt_pk_bf16_f32 v29, v36, v29
	global_store_dwordx4 v[98:99], v[26:29], off offset:256
	s_nop 0
	s_waitcnt vmcnt(11)
	v_lshlrev_b32_e32 v33, 16, v219
	v_and_b32_e32 v29, 0xffff0000, v219
	v_lshlrev_b32_e32 v30, 16, v216
	v_and_b32_e32 v26, 0xffff0000, v216
	v_lshlrev_b32_e32 v31, 16, v217
	v_and_b32_e32 v27, 0xffff0000, v217
	v_lshlrev_b32_e32 v32, 16, v218
	v_and_b32_e32 v28, 0xffff0000, v218
	v_add_f32_e32 v29, v69, v29
	v_add_f32_e32 v30, v70, v30
	v_add_f32_e32 v26, v71, v26
	v_add_f32_e32 v31, v72, v31
	v_add_f32_e32 v27, v73, v27
	v_add_f32_e32 v32, v66, v32
	v_add_f32_e32 v28, v67, v28
	v_add_f32_e32 v33, v68, v33
	v_mul_f32_e32 v29, 0xbfb8aa3b, v29
	v_mul_f32_e32 v30, 0xbfb8aa3b, v30
	v_mul_f32_e32 v26, 0xbfb8aa3b, v26
	v_mul_f32_e32 v31, 0xbfb8aa3b, v31
	v_mul_f32_e32 v27, 0xbfb8aa3b, v27
	v_mul_f32_e32 v32, 0xbfb8aa3b, v32
	v_mul_f32_e32 v28, 0xbfb8aa3b, v28
	v_mul_f32_e32 v33, 0xbfb8aa3b, v33
	v_exp_f32_e32 v29, v29
	v_exp_f32_e32 v30, v30
	v_exp_f32_e32 v26, v26
	v_exp_f32_e32 v31, v31
	v_exp_f32_e32 v27, v27
	v_exp_f32_e32 v32, v32
	v_exp_f32_e32 v28, v28
	v_exp_f32_e32 v33, v33
	v_add_f32_e32 v29, 1.0, v29
	v_add_f32_e32 v30, 1.0, v30
	v_add_f32_e32 v26, 1.0, v26
	v_add_f32_e32 v31, 1.0, v31
	v_add_f32_e32 v27, 1.0, v27
	v_add_f32_e32 v32, 1.0, v32
	v_add_f32_e32 v28, 1.0, v28
	v_add_f32_e32 v33, 1.0, v33
	v_rcp_f32_e32 v29, v29
	v_rcp_f32_e32 v30, v30
	v_rcp_f32_e32 v26, v26
	v_rcp_f32_e32 v31, v31
	v_rcp_f32_e32 v27, v27
	v_rcp_f32_e32 v32, v32
	v_rcp_f32_e32 v28, v28
	v_rcp_f32_e32 v33, v33
	v_mul_f32_e32 v21, v21, v29
	v_mul_f32_e32 v22, v22, v30
	v_mul_f32_e32 v23, v23, v26
	v_mul_f32_e32 v24, v24, v31
	v_mul_f32_e32 v25, v25, v27
	v_mul_f32_e32 v26, v18, v32
	v_mul_f32_e32 v27, v19, v28
	v_mul_f32_e32 v28, v20, v33
	v_cvt_pk_bf16_f32 v18, v22, v23
	v_cvt_pk_bf16_f32 v19, v24, v25
	v_cvt_pk_bf16_f32 v20, v26, v27
	v_cvt_pk_bf16_f32 v21, v28, v21
	global_store_dwordx4 v[90:91], v[18:21], off offset:256
	s_nop 0
	s_waitcnt vmcnt(10)
; __device__ __forceinline__ float bflo(unsigned u) { return __uint_as_float(u << 16); }
; __device__ __forceinline__ float bfhi(unsigned u) { return __uint_as_float(u & 0xffff0000u); }
; __device__ __forceinline__ float sigm(float v) { return __builtin_amdgcn_rcpf(1.0f + __expf(-v)); }
; DI float bflo(unsigned u) { return __uint_as_float(u << 16); }
; DI float bfhi(unsigned u) { return __uint_as_float(u & 0xffff0000u); }
;     __device__ __forceinline__ void operator()(const f32x4 (&acc)[2][2][4][2], const Unit& u, int wr, int wc, int fr, int fq) const {
;         const int row0 = u.pm * BM + wr * 64 + fr; const int colt = u.pn * BM; const int t = colt / 512;
;         const bf16_t* gbase = G0 + (size_t)t * split_stride; const int col0 = colt + wc * 32 + 8 * fq, gcol0 = col0 - t * 512;
; #pragma unroll
;         for (int bj = 0; bj < 2; ++bj) {
;             const f32x4 b0 = *(const f32x4*)(gb + col0 + bj * HALF), b1 = *(const f32x4*)(gb + col0 + bj * HALF + 4);
; #pragma unroll
;             for (int ai = 0; ai < 2; ++ai)
; #pragma unroll
;                 for (int m = 0; m < 4; ++m) { const size_t row = (size_t)(row0 + ai * HALF + m * 16);
;                     const u32x4 g = *(const u32x4*)(gbase + row * 512 + gcol0 + bj * HALF);
;                     const f32x4 v0 = acc[ai][bj][m][0], v1 = acc[ai][bj][m][1];
;                     float r0 = v0[0] * sigm(bflo(g.x) + b0[0]), r1 = v0[1] * sigm(bfhi(g.x) + b0[1]), r2 = v0[2] * sigm(bflo(g.y) + b0[2]), r3 = v0[3] * sigm(bfhi(g.y) + b0[3]);
;                     float r4 = v1[0] * sigm(bflo(g.z) + b1[0]), r5 = v1[1] * sigm(bfhi(g.z) + b1[1]), r6 = v1[2] * sigm(bflo(g.w) + b1[2]), r7 = v1[3] * sigm(bfhi(g.w) + b1[3]);
	v_lshlrev_b32_e32 v25, 16, v223
	v_and_b32_e32 v21, 0xffff0000, v223
	v_lshlrev_b32_e32 v22, 16, v220
	v_and_b32_e32 v18, 0xffff0000, v220
	v_lshlrev_b32_e32 v23, 16, v221
	v_and_b32_e32 v19, 0xffff0000, v221
	v_lshlrev_b32_e32 v24, 16, v222
	v_and_b32_e32 v20, 0xffff0000, v222
	v_add_f32_e32 v21, v69, v21
	v_add_f32_e32 v22, v70, v22
	v_add_f32_e32 v18, v71, v18
	v_add_f32_e32 v23, v72, v23
	v_add_f32_e32 v19, v73, v19
	v_add_f32_e32 v24, v66, v24
	v_add_f32_e32 v20, v67, v20
	v_add_f32_e32 v25, v68, v25
	v_mul_f32_e32 v21, 0xbfb8aa3b, v21
	v_mul_f32_e32 v22, 0xbfb8aa3b, v22
	v_mul_f32_e32 v18, 0xbfb8aa3b, v18
	v_mul_f32_e32 v23, 0xbfb8aa3b, v23
	v_mul_f32_e32 v19, 0xbfb8aa3b, v19
	v_mul_f32_e32 v24, 0xbfb8aa3b, v24
	v_mul_f32_e32 v20, 0xbfb8aa3b, v20
	v_mul_f32_e32 v25, 0xbfb8aa3b, v25
	v_exp_f32_e32 v21, v21
	v_exp_f32_e32 v22, v22
	v_exp_f32_e32 v18, v18
	v_exp_f32_e32 v23, v23
	v_exp_f32_e32 v19, v19
	v_exp_f32_e32 v24, v24
	v_exp_f32_e32 v20, v20
	v_exp_f32_e32 v25, v25
	v_add_f32_e32 v21, 1.0, v21
	v_add_f32_e32 v22, 1.0, v22
	v_add_f32_e32 v18, 1.0, v18
	v_add_f32_e32 v23, 1.0, v23
	v_add_f32_e32 v19, 1.0, v19
	v_add_f32_e32 v24, 1.0, v24
	v_add_f32_e32 v20, 1.0, v20
	v_add_f32_e32 v25, 1.0, v25
	v_rcp_f32_e32 v21, v21
	v_rcp_f32_e32 v22, v22
	v_rcp_f32_e32 v18, v18
	v_rcp_f32_e32 v23, v23
	v_rcp_f32_e32 v19, v19
	v_rcp_f32_e32 v24, v24
	v_rcp_f32_e32 v20, v20
	v_rcp_f32_e32 v25, v25
	v_mul_f32_e32 v13, v13, v21
	v_mul_f32_e32 v14, v14, v22
	v_mul_f32_e32 v15, v15, v18
	v_mul_f32_e32 v16, v16, v23
	v_mul_f32_e32 v17, v17, v19
	v_mul_f32_e32 v18, v10, v24
	v_mul_f32_e32 v19, v11, v20
	v_mul_f32_e32 v20, v12, v25
	v_cvt_pk_bf16_f32 v10, v14, v15
	v_cvt_pk_bf16_f32 v11, v16, v17
	v_cvt_pk_bf16_f32 v12, v18, v19
	v_cvt_pk_bf16_f32 v13, v20, v13
	global_store_dwordx4 v[82:83], v[10:13], off offset:256
	s_nop 0
	s_waitcnt vmcnt(9)
	v_lshlrev_b32_e32 v17, 16, v227
	v_and_b32_e32 v13, 0xffff0000, v227
	v_lshlrev_b32_e32 v14, 16, v224
	v_and_b32_e32 v10, 0xffff0000, v224
	v_lshlrev_b32_e32 v15, 16, v225
	v_and_b32_e32 v11, 0xffff0000, v225
	v_lshlrev_b32_e32 v16, 16, v226
	v_and_b32_e32 v12, 0xffff0000, v226
	v_add_f32_e32 v13, v69, v13
	v_add_f32_e32 v14, v70, v14
	v_add_f32_e32 v10, v71, v10
	v_add_f32_e32 v15, v72, v15
	v_add_f32_e32 v11, v73, v11
	v_add_f32_e32 v16, v66, v16
	v_add_f32_e32 v12, v67, v12
	v_add_f32_e32 v17, v68, v17
	v_mul_f32_e32 v13, 0xbfb8aa3b, v13
	v_mul_f32_e32 v14, 0xbfb8aa3b, v14
	v_mul_f32_e32 v10, 0xbfb8aa3b, v10
	v_mul_f32_e32 v15, 0xbfb8aa3b, v15
	v_mul_f32_e32 v11, 0xbfb8aa3b, v11
	v_mul_f32_e32 v16, 0xbfb8aa3b, v16
	v_mul_f32_e32 v12, 0xbfb8aa3b, v12
	v_mul_f32_e32 v17, 0xbfb8aa3b, v17
	v_exp_f32_e32 v13, v13
	v_exp_f32_e32 v14, v14
	v_exp_f32_e32 v10, v10
	v_exp_f32_e32 v15, v15
	v_exp_f32_e32 v11, v11
	v_exp_f32_e32 v16, v16
	v_exp_f32_e32 v12, v12
	v_exp_f32_e32 v17, v17
	v_add_f32_e32 v13, 1.0, v13
	v_add_f32_e32 v14, 1.0, v14
	v_add_f32_e32 v10, 1.0, v10
	v_add_f32_e32 v15, 1.0, v15
	v_add_f32_e32 v11, 1.0, v11
	v_add_f32_e32 v16, 1.0, v16
	v_add_f32_e32 v12, 1.0, v12
	v_add_f32_e32 v17, 1.0, v17
	v_rcp_f32_e32 v13, v13
	v_rcp_f32_e32 v14, v14
	v_rcp_f32_e32 v10, v10
	v_rcp_f32_e32 v15, v15
	v_rcp_f32_e32 v11, v11
	v_rcp_f32_e32 v16, v16
	v_rcp_f32_e32 v12, v12
	v_rcp_f32_e32 v17, v17
	v_mul_f32_e32 v5, v5, v13
	v_mul_f32_e32 v6, v6, v14
	v_mul_f32_e32 v7, v7, v10
	v_mul_f32_e32 v8, v8, v15
	v_mul_f32_e32 v9, v9, v11
	v_mul_f32_e32 v10, v2, v16
	v_mul_f32_e32 v11, v3, v12
	v_mul_f32_e32 v12, v4, v17
	v_cvt_pk_bf16_f32 v2, v6, v7
	v_cvt_pk_bf16_f32 v3, v8, v9
	v_cvt_pk_bf16_f32 v4, v10, v11
	v_cvt_pk_bf16_f32 v5, v12, v5
	global_store_dwordx4 v[74:75], v[2:5], off offset:256
.Lg1_exit:
	s_cbranch_vccnz .LBB0_869
	s_andn2_b64 vcc, exec, s[0:1]
	s_cbranch_vccnz .LBB0_868
	s_barrier
	s_branch .LBB0_868
.Lg1n_start:
	s_lshr_b32 s2, s44, 31
	s_add_i32 s2, s44, s2
	s_ashr_i32 s24, s2, 1
	s_ashr_i32 s25, s24, 31
	s_lshl_b64 s[26:27], s[24:25], 24
	s_add_u32 s26, s36, s26
	s_addc_u32 s27, s37, s27
	v_lshl_or_b32 v154, s44, 8, v172
	s_lshl_b32 s2, s24, 9
	v_lshl_add_u32 v168, s22, 8, v1
	v_subrev_u32_e32 v114, s2, v154
	v_ashrrev_i32_e32 v115, 31, v114
	v_ashrrev_i32_e32 v169, 31, v168
	v_lshl_add_u64 v[170:171], v[114:115], 1, s[26:27]
	v_lshlrev_b64 v[114:115], 10, v[168:169]
	v_lshl_add_u64 v[158:159], v[170:171], 0, v[114:115]
	v_ashrrev_i32_e32 v155, 31, v154
	v_lshl_add_u64 v[160:161], v[154:155], 2, s[78:79]
	v_lshlrev_b64 v[156:157], 11, v[168:169]
	v_or_b32_e32 v180, 16, v168
	v_lshlrev_b64 v[166:167], 1, v[154:155]
	v_ashrrev_i32_e32 v181, 31, v180
	v_lshl_add_u64 v[154:155], s[10:11], 0, v[156:157]
	v_lshlrev_b64 v[156:157], 10, v[180:181]
	v_lshl_add_u64 v[154:155], v[154:155], 0, v[166:167]
	v_lshl_add_u64 v[156:157], v[170:171], 0, v[156:157]
	s_andn2_b64 vcc, exec, s[6:7]
	s_mov_b64 s[6:7], -1
	v_mov_b32_e32 v250, v158
	v_mov_b32_e32 v251, v159
	v_mov_b32_e32 v252, v160
	v_mov_b32_e32 v253, v161
	v_mov_b32_e32 v246, 0xbfb8aa3b
	v_mov_b32_e32 v247, 0xbfb8aa3b
	v_mov_b32_e32 v248, 0x5d800000
	v_mov_b32_e32 v249, 0x5d800000
	v_mov_b32_e32 v244, 1.0
	v_mov_b32_e32 v245, 1.0
	global_load_dwordx4 v[114:117], v[252:253], off
	global_load_dwordx4 v[118:121], v[252:253], off offset:16
	s_mov_b64 s[98:99], 0x1000
	v_lshl_add_u64 v[254:255], v[252:253], 0, s[98:99]
	global_load_dwordx4 v[154:157], v[254:255], off
	global_load_dwordx4 v[158:161], v[254:255], off offset:16
	s_mov_b64 s[98:99], 0x200
	v_lshl_add_u64 v[254:255], v[252:253], 0, s[98:99]
	global_load_dwordx4 v[176:179], v[254:255], off
	global_load_dwordx4 v[180:183], v[254:255], off offset:16
	s_mov_b64 s[98:99], 0x1200
	v_lshl_add_u64 v[254:255], v[252:253], 0, s[98:99]
	global_load_dwordx4 v[184:187], v[254:255], off
	global_load_dwordx4 v[188:191], v[254:255], off offset:16
	global_load_dwordx4 v[204:207], v[250:251], off
	s_mov_b64 s[98:99], 0x2000000
	v_lshl_add_u64 v[254:255], v[250:251], 0, s[98:99]
	global_load_dwordx4 v[208:211], v[254:255], off
	s_mov_b64 s[98:99], 0x4000
	v_lshl_add_u64 v[254:255], v[250:251], 0, s[98:99]
	global_load_dwordx4 v[212:215], v[254:255], off
	s_mov_b64 s[98:99], 0x2004000
	v_lshl_add_u64 v[254:255], v[250:251], 0, s[98:99]
	global_load_dwordx4 v[216:219], v[254:255], off
	s_mov_b64 s[98:99], 0x8000
	v_lshl_add_u64 v[254:255], v[250:251], 0, s[98:99]
	global_load_dwordx4 v[220:223], v[254:255], off
	s_mov_b64 s[98:99], 0x2008000
	v_lshl_add_u64 v[254:255], v[250:251], 0, s[98:99]
	global_load_dwordx4 v[224:227], v[254:255], off
	s_mov_b64 s[98:99], 0xc000
	v_lshl_add_u64 v[254:255], v[250:251], 0, s[98:99]
	global_load_dwordx4 v[192:195], v[254:255], off
	s_mov_b64 s[98:99], 0x200c000
	v_lshl_add_u64 v[254:255], v[250:251], 0, s[98:99]
	global_load_dwordx4 v[166:169], v[254:255], off
	s_waitcnt vmcnt(6)
; __device__ __forceinline__ float bflo(unsigned u) { return __uint_as_float(u << 16); }
; __device__ __forceinline__ float bfhi(unsigned u) { return __uint_as_float(u & 0xffff0000u); }
; __device__ __forceinline__ float sigm(float v) { return __builtin_amdgcn_rcpf(1.0f + __expf(-v)); }
; DI float bflo(unsigned u) { return __uint_as_float(u << 16); }
; DI float bfhi(unsigned u) { return __uint_as_float(u & 0xffff0000u); }
;     __device__ __forceinline__ void operator()(const f32x4 (&acc)[2][2][4][2], const Unit& u, int wr, int wc, int fr, int fq) const {
;     ...
;         for (int bj = 0; bj < 2; ++bj) {
;             const f32x4 b0 = *(const f32x4*)(gb + col0 + bj * HALF), b1 = *(const f32x4*)(gb + col0 + bj * HALF + 4);
; #pragma unroll
;             for (int ai = 0; ai < 2; ++ai)
; #pragma unroll
;                 for (int m = 0; m < 4; ++m) { const size_t row = (size_t)(row0 + ai * HALF + m * 16);
;                     const u32x4 g = *(const u32x4*)(gbase + row * 512 + gcol0 + bj * HALF);
;                     const f32x4 v0 = acc[ai][bj][m][0], v1 = acc[ai][bj][m][1];
;                     float r0 = v0[0] * sigm(bflo(g.x) + b0[0]), r1 = v0[1] * sigm(bfhi(g.x) + b0[1]), r2 = v0[2] * sigm(bflo(g.y) + b0[2]), r3 = v0[3] * sigm(bfhi(g.y) + b0[3]);
;                     float r4 = v1[0] * sigm(bflo(g.z) + b1[0]), r5 = v1[1] * sigm(bfhi(g.z) + b1[1]), r6 = v1[2] * sigm(bflo(g.w) + b1[2]), r7 = v1[3] * sigm(bfhi(g.w) + b1[3]);
	v_lshlrev_b32_e32 v240, 16, v204
	v_and_b32_e32 v241, 0xffff0000, v204
	v_lshlrev_b32_e32 v242, 16, v208
	v_and_b32_e32 v243, 0xffff0000, v208
	v_pk_add_f32 v[240:241], v[240:241], v[114:115]
	v_pk_add_f32 v[242:243], v[242:243], v[154:155]
	v_pk_mul_f32 v[240:241], v[240:241], v[246:247]
	v_pk_mul_f32 v[242:243], v[242:243], v[246:247]
	v_exp_f32_e32 v242, v242
	v_exp_f32_e32 v243, v243
	v_exp_f32_e32 v240, v240
	v_exp_f32_e32 v241, v241
	v_min_f32_e32 v242, v242, v248
	v_min_f32_e32 v243, v243, v248
	v_pk_add_f32 v[240:241], v[240:241], v[244:245]
	v_pk_add_f32 v[242:243], v[242:243], v[244:245]
	v_rcp_f32_e32 v240, v240
	v_rcp_f32_e32 v241, v241
	s_nop 0
	v_pk_mul_f32 v[242:243], v[242:243], v[240:241]
	v_pk_mul_f32 v[134:135], v[134:135], v[242:243]
	v_lshlrev_b32_e32 v240, 16, v205
	v_and_b32_e32 v241, 0xffff0000, v205
	v_lshlrev_b32_e32 v242, 16, v209
	v_and_b32_e32 v243, 0xffff0000, v209
	v_pk_add_f32 v[240:241], v[240:241], v[116:117]
	v_pk_add_f32 v[242:243], v[242:243], v[156:157]
	v_pk_mul_f32 v[240:241], v[240:241], v[246:247]
	v_pk_mul_f32 v[242:243], v[242:243], v[246:247]
	v_exp_f32_e32 v242, v242
	v_exp_f32_e32 v243, v243
	v_exp_f32_e32 v240, v240
	v_exp_f32_e32 v241, v241
	v_min_f32_e32 v242, v242, v248
	v_min_f32_e32 v243, v243, v248
	v_pk_add_f32 v[240:241], v[240:241], v[244:245]
	v_pk_add_f32 v[242:243], v[242:243], v[244:245]
	v_rcp_f32_e32 v240, v240
	v_rcp_f32_e32 v241, v241
	s_nop 0
	v_pk_mul_f32 v[242:243], v[242:243], v[240:241]
	v_pk_mul_f32 v[136:137], v[136:137], v[242:243]
	v_lshlrev_b32_e32 v240, 16, v206
	v_and_b32_e32 v241, 0xffff0000, v206
	v_lshlrev_b32_e32 v242, 16, v210
	v_and_b32_e32 v243, 0xffff0000, v210
	v_pk_add_f32 v[240:241], v[240:241], v[118:119]
	v_pk_add_f32 v[242:243], v[242:243], v[158:159]
	v_pk_mul_f32 v[240:241], v[240:241], v[246:247]
	v_pk_mul_f32 v[242:243], v[242:243], v[246:247]
	v_exp_f32_e32 v242, v242
	v_exp_f32_e32 v243, v243
	v_exp_f32_e32 v240, v240
	v_exp_f32_e32 v241, v241
	v_min_f32_e32 v242, v242, v248
	v_min_f32_e32 v243, v243, v248
	v_pk_add_f32 v[240:241], v[240:241], v[244:245]
	v_pk_add_f32 v[242:243], v[242:243], v[244:245]
	v_rcp_f32_e32 v240, v240
	v_rcp_f32_e32 v241, v241
	s_nop 0
	v_pk_mul_f32 v[242:243], v[242:243], v[240:241]
	v_pk_mul_f32 v[130:131], v[130:131], v[242:243]
	v_lshlrev_b32_e32 v240, 16, v207
	v_and_b32_e32 v241, 0xffff0000, v207
	v_lshlrev_b32_e32 v242, 16, v211
	v_and_b32_e32 v243, 0xffff0000, v211
	s_mov_b64 s[98:99], 0x20000
	v_lshl_add_u64 v[254:255], v[250:251], 0, s[98:99]
	global_load_dwordx4 v[204:207], v[254:255], off
	s_mov_b64 s[98:99], 0x2020000
	v_lshl_add_u64 v[254:255], v[250:251], 0, s[98:99]
	global_load_dwordx4 v[208:211], v[254:255], off
	v_pk_add_f32 v[240:241], v[240:241], v[120:121]
	v_pk_add_f32 v[242:243], v[242:243], v[160:161]
	v_pk_mul_f32 v[240:241], v[240:241], v[246:247]
	v_pk_mul_f32 v[242:243], v[242:243], v[246:247]
	v_exp_f32_e32 v242, v242
	v_exp_f32_e32 v243, v243
	v_exp_f32_e32 v240, v240
	v_exp_f32_e32 v241, v241
	v_min_f32_e32 v242, v242, v248
	v_min_f32_e32 v243, v243, v248
	v_pk_add_f32 v[240:241], v[240:241], v[244:245]
	v_pk_add_f32 v[242:243], v[242:243], v[244:245]
	v_rcp_f32_e32 v240, v240
	v_rcp_f32_e32 v241, v241
	s_nop 0
	v_pk_mul_f32 v[242:243], v[242:243], v[240:241]
	v_pk_mul_f32 v[132:133], v[132:133], v[242:243]
	s_waitcnt vmcnt(6)
	v_lshlrev_b32_e32 v240, 16, v212
	v_and_b32_e32 v241, 0xffff0000, v212
	v_lshlrev_b32_e32 v242, 16, v216
	v_and_b32_e32 v243, 0xffff0000, v216
	v_pk_add_f32 v[240:241], v[240:241], v[114:115]
	v_pk_add_f32 v[242:243], v[242:243], v[154:155]
	v_pk_mul_f32 v[240:241], v[240:241], v[246:247]
	v_pk_mul_f32 v[242:243], v[242:243], v[246:247]
	v_exp_f32_e32 v242, v242
	v_exp_f32_e32 v243, v243
	v_exp_f32_e32 v240, v240
	v_exp_f32_e32 v241, v241
	v_min_f32_e32 v242, v242, v248
	v_min_f32_e32 v243, v243, v248
	v_pk_add_f32 v[240:241], v[240:241], v[244:245]
	v_pk_add_f32 v[242:243], v[242:243], v[244:245]
	v_rcp_f32_e32 v240, v240
	v_rcp_f32_e32 v241, v241
	s_nop 0
	v_pk_mul_f32 v[242:243], v[242:243], v[240:241]
	v_pk_mul_f32 v[126:127], v[126:127], v[242:243]
	v_lshlrev_b32_e32 v240, 16, v213
	v_and_b32_e32 v241, 0xffff0000, v213
	v_lshlrev_b32_e32 v242, 16, v217
	v_and_b32_e32 v243, 0xffff0000, v217
	v_pk_add_f32 v[240:241], v[240:241], v[116:117]
	v_pk_add_f32 v[242:243], v[242:243], v[156:157]
	v_pk_mul_f32 v[240:241], v[240:241], v[246:247]
	v_pk_mul_f32 v[242:243], v[242:243], v[246:247]
	v_exp_f32_e32 v242, v242
	v_exp_f32_e32 v243, v243
	v_exp_f32_e32 v240, v240
	v_exp_f32_e32 v241, v241
	v_min_f32_e32 v242, v242, v248
	v_min_f32_e32 v243, v243, v248
	v_pk_add_f32 v[240:241], v[240:241], v[244:245]
	v_pk_add_f32 v[242:243], v[242:243], v[244:245]
	v_rcp_f32_e32 v240, v240
	v_rcp_f32_e32 v241, v241
	s_nop 0
	v_pk_mul_f32 v[242:243], v[242:243], v[240:241]
	v_pk_mul_f32 v[128:129], v[128:129], v[242:243]
	v_lshlrev_b32_e32 v240, 16, v214
	v_and_b32_e32 v241, 0xffff0000, v214
	v_lshlrev_b32_e32 v242, 16, v218
	v_and_b32_e32 v243, 0xffff0000, v218
	v_pk_add_f32 v[240:241], v[240:241], v[118:119]
	v_pk_add_f32 v[242:243], v[242:243], v[158:159]
	v_pk_mul_f32 v[240:241], v[240:241], v[246:247]
	v_pk_mul_f32 v[242:243], v[242:243], v[246:247]
	v_exp_f32_e32 v242, v242
	v_exp_f32_e32 v243, v243
	v_exp_f32_e32 v240, v240
	v_exp_f32_e32 v241, v241
	v_min_f32_e32 v242, v242, v248
	v_min_f32_e32 v243, v243, v248
	v_pk_add_f32 v[240:241], v[240:241], v[244:245]
	v_pk_add_f32 v[242:243], v[242:243], v[244:245]
	v_rcp_f32_e32 v240, v240
	v_rcp_f32_e32 v241, v241
	s_nop 0
	v_pk_mul_f32 v[242:243], v[242:243], v[240:241]
	v_pk_mul_f32 v[122:123], v[122:123], v[242:243]
	v_lshlrev_b32_e32 v240, 16, v215
	v_and_b32_e32 v241, 0xffff0000, v215
	v_lshlrev_b32_e32 v242, 16, v219
	v_and_b32_e32 v243, 0xffff0000, v219
	s_mov_b64 s[98:99], 0x24000
	v_lshl_add_u64 v[254:255], v[250:251], 0, s[98:99]
	global_load_dwordx4 v[212:215], v[254:255], off
	s_mov_b64 s[98:99], 0x2024000
	v_lshl_add_u64 v[254:255], v[250:251], 0, s[98:99]
	global_load_dwordx4 v[216:219], v[254:255], off
	v_pk_add_f32 v[240:241], v[240:241], v[120:121]
	v_pk_add_f32 v[242:243], v[242:243], v[160:161]
	v_pk_mul_f32 v[240:241], v[240:241], v[246:247]
	v_pk_mul_f32 v[242:243], v[242:243], v[246:247]
	v_exp_f32_e32 v242, v242
	v_exp_f32_e32 v243, v243
	v_exp_f32_e32 v240, v240
	v_exp_f32_e32 v241, v241
	v_min_f32_e32 v242, v242, v248
	v_min_f32_e32 v243, v243, v248
	v_pk_add_f32 v[240:241], v[240:241], v[244:245]
	v_pk_add_f32 v[242:243], v[242:243], v[244:245]
	v_rcp_f32_e32 v240, v240
	v_rcp_f32_e32 v241, v241
	s_nop 0
	v_pk_mul_f32 v[242:243], v[242:243], v[240:241]
	v_pk_mul_f32 v[124:125], v[124:125], v[242:243]
	s_waitcnt vmcnt(6)
; __device__ __forceinline__ float bflo(unsigned u) { return __uint_as_float(u << 16); }
; __device__ __forceinline__ float bfhi(unsigned u) { return __uint_as_float(u & 0xffff0000u); }
; __device__ __forceinline__ float sigm(float v) { return __builtin_amdgcn_rcpf(1.0f + __expf(-v)); }
; DI float bflo(unsigned u) { return __uint_as_float(u << 16); }
; DI float bfhi(unsigned u) { return __uint_as_float(u & 0xffff0000u); }
;     __device__ __forceinline__ void operator()(const f32x4 (&acc)[2][2][4][2], const Unit& u, int wr, int wc, int fr, int fq) const {
;     ...
;         for (int bj = 0; bj < 2; ++bj) {
;             const f32x4 b0 = *(const f32x4*)(gb + col0 + bj * HALF), b1 = *(const f32x4*)(gb + col0 + bj * HALF + 4);
; #pragma unroll
;             for (int ai = 0; ai < 2; ++ai)
; #pragma unroll
;                 for (int m = 0; m < 4; ++m) { const size_t row = (size_t)(row0 + ai * HALF + m * 16);
;                     const u32x4 g = *(const u32x4*)(gbase + row * 512 + gcol0 + bj * HALF);
;                     const f32x4 v0 = acc[ai][bj][m][0], v1 = acc[ai][bj][m][1];
;                     float r0 = v0[0] * sigm(bflo(g.x) + b0[0]), r1 = v0[1] * sigm(bfhi(g.x) + b0[1]), r2 = v0[2] * sigm(bflo(g.y) + b0[2]), r3 = v0[3] * sigm(bfhi(g.y) + b0[3]);
;                     float r4 = v1[0] * sigm(bflo(g.z) + b1[0]), r5 = v1[1] * sigm(bfhi(g.z) + b1[1]), r6 = v1[2] * sigm(bflo(g.w) + b1[2]), r7 = v1[3] * sigm(bfhi(g.w) + b1[3]);
	v_lshlrev_b32_e32 v240, 16, v220
	v_and_b32_e32 v241, 0xffff0000, v220
	v_lshlrev_b32_e32 v242, 16, v224
	v_and_b32_e32 v243, 0xffff0000, v224
	v_pk_add_f32 v[240:241], v[240:241], v[114:115]
	v_pk_add_f32 v[242:243], v[242:243], v[154:155]
	v_pk_mul_f32 v[240:241], v[240:241], v[246:247]
	v_pk_mul_f32 v[242:243], v[242:243], v[246:247]
	v_exp_f32_e32 v242, v242
	v_exp_f32_e32 v243, v243
	v_exp_f32_e32 v240, v240
	v_exp_f32_e32 v241, v241
	v_min_f32_e32 v242, v242, v248
	v_min_f32_e32 v243, v243, v248
	v_pk_add_f32 v[240:241], v[240:241], v[244:245]
	v_pk_add_f32 v[242:243], v[242:243], v[244:245]
	v_rcp_f32_e32 v240, v240
	v_rcp_f32_e32 v241, v241
	s_nop 0
	v_pk_mul_f32 v[242:243], v[242:243], v[240:241]
	v_pk_mul_f32 v[110:111], v[110:111], v[242:243]
	v_lshlrev_b32_e32 v240, 16, v221
	v_and_b32_e32 v241, 0xffff0000, v221
	v_lshlrev_b32_e32 v242, 16, v225
	v_and_b32_e32 v243, 0xffff0000, v225
	v_pk_add_f32 v[240:241], v[240:241], v[116:117]
	v_pk_add_f32 v[242:243], v[242:243], v[156:157]
	v_pk_mul_f32 v[240:241], v[240:241], v[246:247]
	v_pk_mul_f32 v[242:243], v[242:243], v[246:247]
	v_exp_f32_e32 v242, v242
	v_exp_f32_e32 v243, v243
	v_exp_f32_e32 v240, v240
	v_exp_f32_e32 v241, v241
	v_min_f32_e32 v242, v242, v248
	v_min_f32_e32 v243, v243, v248
	v_pk_add_f32 v[240:241], v[240:241], v[244:245]
	v_pk_add_f32 v[242:243], v[242:243], v[244:245]
	v_rcp_f32_e32 v240, v240
	v_rcp_f32_e32 v241, v241
	s_nop 0
	v_pk_mul_f32 v[242:243], v[242:243], v[240:241]
	v_pk_mul_f32 v[112:113], v[112:113], v[242:243]
	v_lshlrev_b32_e32 v240, 16, v222
	v_and_b32_e32 v241, 0xffff0000, v222
	v_lshlrev_b32_e32 v242, 16, v226
	v_and_b32_e32 v243, 0xffff0000, v226
	v_pk_add_f32 v[240:241], v[240:241], v[118:119]
	v_pk_add_f32 v[242:243], v[242:243], v[158:159]
	v_pk_mul_f32 v[240:241], v[240:241], v[246:247]
	v_pk_mul_f32 v[242:243], v[242:243], v[246:247]
	v_exp_f32_e32 v242, v242
	v_exp_f32_e32 v243, v243
	v_exp_f32_e32 v240, v240
	v_exp_f32_e32 v241, v241
	v_min_f32_e32 v242, v242, v248
	v_min_f32_e32 v243, v243, v248
	v_pk_add_f32 v[240:241], v[240:241], v[244:245]
	v_pk_add_f32 v[242:243], v[242:243], v[244:245]
	v_rcp_f32_e32 v240, v240
	v_rcp_f32_e32 v241, v241
	s_nop 0
	v_pk_mul_f32 v[242:243], v[242:243], v[240:241]
	v_pk_mul_f32 v[106:107], v[106:107], v[242:243]
	v_lshlrev_b32_e32 v240, 16, v223
	v_and_b32_e32 v241, 0xffff0000, v223
	v_lshlrev_b32_e32 v242, 16, v227
	v_and_b32_e32 v243, 0xffff0000, v227
	s_mov_b64 s[98:99], 0x28000
	v_lshl_add_u64 v[254:255], v[250:251], 0, s[98:99]
	global_load_dwordx4 v[220:223], v[254:255], off
	s_mov_b64 s[98:99], 0x2028000
	v_lshl_add_u64 v[254:255], v[250:251], 0, s[98:99]
	global_load_dwordx4 v[224:227], v[254:255], off
	v_pk_add_f32 v[240:241], v[240:241], v[120:121]
	v_pk_add_f32 v[242:243], v[242:243], v[160:161]
	v_pk_mul_f32 v[240:241], v[240:241], v[246:247]
	v_pk_mul_f32 v[242:243], v[242:243], v[246:247]
	v_exp_f32_e32 v242, v242
	v_exp_f32_e32 v243, v243
	v_exp_f32_e32 v240, v240
	v_exp_f32_e32 v241, v241
	v_min_f32_e32 v242, v242, v248
	v_min_f32_e32 v243, v243, v248
	v_pk_add_f32 v[240:241], v[240:241], v[244:245]
	v_pk_add_f32 v[242:243], v[242:243], v[244:245]
	v_rcp_f32_e32 v240, v240
	v_rcp_f32_e32 v241, v241
	s_nop 0
	v_pk_mul_f32 v[242:243], v[242:243], v[240:241]
	v_pk_mul_f32 v[108:109], v[108:109], v[242:243]
	s_waitcnt vmcnt(6)
	v_lshlrev_b32_e32 v240, 16, v192
	v_and_b32_e32 v241, 0xffff0000, v192
	v_lshlrev_b32_e32 v242, 16, v166
	v_and_b32_e32 v243, 0xffff0000, v166
	v_pk_add_f32 v[240:241], v[240:241], v[114:115]
	v_pk_add_f32 v[242:243], v[242:243], v[154:155]
	v_pk_mul_f32 v[240:241], v[240:241], v[246:247]
	v_pk_mul_f32 v[242:243], v[242:243], v[246:247]
	v_exp_f32_e32 v242, v242
	v_exp_f32_e32 v243, v243
	v_exp_f32_e32 v240, v240
	v_exp_f32_e32 v241, v241
	v_min_f32_e32 v242, v242, v248
	v_min_f32_e32 v243, v243, v248
	v_pk_add_f32 v[240:241], v[240:241], v[244:245]
	v_pk_add_f32 v[242:243], v[242:243], v[244:245]
	v_rcp_f32_e32 v240, v240
	v_rcp_f32_e32 v241, v241
	s_nop 0
	v_pk_mul_f32 v[242:243], v[242:243], v[240:241]
	v_pk_mul_f32 v[102:103], v[102:103], v[242:243]
	v_lshlrev_b32_e32 v240, 16, v193
	v_and_b32_e32 v241, 0xffff0000, v193
	v_lshlrev_b32_e32 v242, 16, v167
	v_and_b32_e32 v243, 0xffff0000, v167
	v_pk_add_f32 v[240:241], v[240:241], v[116:117]
	v_pk_add_f32 v[242:243], v[242:243], v[156:157]
	v_pk_mul_f32 v[240:241], v[240:241], v[246:247]
	v_pk_mul_f32 v[242:243], v[242:243], v[246:247]
	v_exp_f32_e32 v242, v242
	v_exp_f32_e32 v243, v243
	v_exp_f32_e32 v240, v240
	v_exp_f32_e32 v241, v241
	v_min_f32_e32 v242, v242, v248
	v_min_f32_e32 v243, v243, v248
	v_pk_add_f32 v[240:241], v[240:241], v[244:245]
	v_pk_add_f32 v[242:243], v[242:243], v[244:245]
	v_rcp_f32_e32 v240, v240
	v_rcp_f32_e32 v241, v241
	s_nop 0
	v_pk_mul_f32 v[242:243], v[242:243], v[240:241]
	v_pk_mul_f32 v[104:105], v[104:105], v[242:243]
	v_lshlrev_b32_e32 v240, 16, v194
	v_and_b32_e32 v241, 0xffff0000, v194
	v_lshlrev_b32_e32 v242, 16, v168
	v_and_b32_e32 v243, 0xffff0000, v168
	v_pk_add_f32 v[240:241], v[240:241], v[118:119]
	v_pk_add_f32 v[242:243], v[242:243], v[158:159]
	v_pk_mul_f32 v[240:241], v[240:241], v[246:247]
	v_pk_mul_f32 v[242:243], v[242:243], v[246:247]
	v_exp_f32_e32 v242, v242
	v_exp_f32_e32 v243, v243
	v_exp_f32_e32 v240, v240
	v_exp_f32_e32 v241, v241
	v_min_f32_e32 v242, v242, v248
	v_min_f32_e32 v243, v243, v248
	v_pk_add_f32 v[240:241], v[240:241], v[244:245]
	v_pk_add_f32 v[242:243], v[242:243], v[244:245]
	v_rcp_f32_e32 v240, v240
	v_rcp_f32_e32 v241, v241
	s_nop 0
	v_pk_mul_f32 v[242:243], v[242:243], v[240:241]
	v_pk_mul_f32 v[98:99], v[98:99], v[242:243]
	v_lshlrev_b32_e32 v240, 16, v195
	v_and_b32_e32 v241, 0xffff0000, v195
	v_lshlrev_b32_e32 v242, 16, v169
	v_and_b32_e32 v243, 0xffff0000, v169
	s_mov_b64 s[98:99], 0x2c000
	v_lshl_add_u64 v[254:255], v[250:251], 0, s[98:99]
	global_load_dwordx4 v[192:195], v[254:255], off
	s_mov_b64 s[98:99], 0x202c000
	v_lshl_add_u64 v[254:255], v[250:251], 0, s[98:99]
	global_load_dwordx4 v[166:169], v[254:255], off
	v_pk_add_f32 v[240:241], v[240:241], v[120:121]
	v_pk_add_f32 v[242:243], v[242:243], v[160:161]
	v_pk_mul_f32 v[240:241], v[240:241], v[246:247]
	v_pk_mul_f32 v[242:243], v[242:243], v[246:247]
	v_exp_f32_e32 v242, v242
	v_exp_f32_e32 v243, v243
	v_exp_f32_e32 v240, v240
	v_exp_f32_e32 v241, v241
	v_min_f32_e32 v242, v242, v248
	v_min_f32_e32 v243, v243, v248
	v_pk_add_f32 v[240:241], v[240:241], v[244:245]
	v_pk_add_f32 v[242:243], v[242:243], v[244:245]
	v_rcp_f32_e32 v240, v240
	v_rcp_f32_e32 v241, v241
	s_nop 0
	v_pk_mul_f32 v[242:243], v[242:243], v[240:241]
	v_pk_mul_f32 v[100:101], v[100:101], v[242:243]
	s_waitcnt vmcnt(6)
; __device__ __forceinline__ float bflo(unsigned u) { return __uint_as_float(u << 16); }
; __device__ __forceinline__ float bfhi(unsigned u) { return __uint_as_float(u & 0xffff0000u); }
; __device__ __forceinline__ float sigm(float v) { return __builtin_amdgcn_rcpf(1.0f + __expf(-v)); }
; DI float bflo(unsigned u) { return __uint_as_float(u << 16); }
; DI float bfhi(unsigned u) { return __uint_as_float(u & 0xffff0000u); }
;     __device__ __forceinline__ void operator()(const f32x4 (&acc)[2][2][4][2], const Unit& u, int wr, int wc, int fr, int fq) const {
;     ...
;         for (int bj = 0; bj < 2; ++bj) {
;             const f32x4 b0 = *(const f32x4*)(gb + col0 + bj * HALF), b1 = *(const f32x4*)(gb + col0 + bj * HALF + 4);
; #pragma unroll
;             for (int ai = 0; ai < 2; ++ai)
; #pragma unroll
;                 for (int m = 0; m < 4; ++m) { const size_t row = (size_t)(row0 + ai * HALF + m * 16);
;                     const u32x4 g = *(const u32x4*)(gbase + row * 512 + gcol0 + bj * HALF);
;                     const f32x4 v0 = acc[ai][bj][m][0], v1 = acc[ai][bj][m][1];
;                     float r0 = v0[0] * sigm(bflo(g.x) + b0[0]), r1 = v0[1] * sigm(bfhi(g.x) + b0[1]), r2 = v0[2] * sigm(bflo(g.y) + b0[2]), r3 = v0[3] * sigm(bfhi(g.y) + b0[3]);
;                     float r4 = v1[0] * sigm(bflo(g.z) + b1[0]), r5 = v1[1] * sigm(bfhi(g.z) + b1[1]), r6 = v1[2] * sigm(bflo(g.w) + b1[2]), r7 = v1[3] * sigm(bfhi(g.w) + b1[3]);
	v_lshlrev_b32_e32 v240, 16, v204
	v_and_b32_e32 v241, 0xffff0000, v204
	v_lshlrev_b32_e32 v242, 16, v208
	v_and_b32_e32 v243, 0xffff0000, v208
	v_pk_add_f32 v[240:241], v[240:241], v[114:115]
	v_pk_add_f32 v[242:243], v[242:243], v[154:155]
	v_pk_mul_f32 v[240:241], v[240:241], v[246:247]
	v_pk_mul_f32 v[242:243], v[242:243], v[246:247]
	v_exp_f32_e32 v242, v242
	v_exp_f32_e32 v243, v243
	v_exp_f32_e32 v240, v240
	v_exp_f32_e32 v241, v241
	v_min_f32_e32 v242, v242, v248
	v_min_f32_e32 v243, v243, v248
	v_pk_add_f32 v[240:241], v[240:241], v[244:245]
	v_pk_add_f32 v[242:243], v[242:243], v[244:245]
	v_rcp_f32_e32 v240, v240
	v_rcp_f32_e32 v241, v241
	s_nop 0
	v_pk_mul_f32 v[242:243], v[242:243], v[240:241]
	v_pk_mul_f32 v[94:95], v[94:95], v[242:243]
	v_lshlrev_b32_e32 v240, 16, v205
	v_and_b32_e32 v241, 0xffff0000, v205
	v_lshlrev_b32_e32 v242, 16, v209
	v_and_b32_e32 v243, 0xffff0000, v209
	v_pk_add_f32 v[240:241], v[240:241], v[116:117]
	v_pk_add_f32 v[242:243], v[242:243], v[156:157]
	v_pk_mul_f32 v[240:241], v[240:241], v[246:247]
	v_pk_mul_f32 v[242:243], v[242:243], v[246:247]
	v_exp_f32_e32 v242, v242
	v_exp_f32_e32 v243, v243
	v_exp_f32_e32 v240, v240
	v_exp_f32_e32 v241, v241
	v_min_f32_e32 v242, v242, v248
	v_min_f32_e32 v243, v243, v248
	v_pk_add_f32 v[240:241], v[240:241], v[244:245]
	v_pk_add_f32 v[242:243], v[242:243], v[244:245]
	v_rcp_f32_e32 v240, v240
	v_rcp_f32_e32 v241, v241
	s_nop 0
	v_pk_mul_f32 v[242:243], v[242:243], v[240:241]
	v_pk_mul_f32 v[96:97], v[96:97], v[242:243]
	v_lshlrev_b32_e32 v240, 16, v206
	v_and_b32_e32 v241, 0xffff0000, v206
	v_lshlrev_b32_e32 v242, 16, v210
	v_and_b32_e32 v243, 0xffff0000, v210
	v_pk_add_f32 v[240:241], v[240:241], v[118:119]
	v_pk_add_f32 v[242:243], v[242:243], v[158:159]
	v_pk_mul_f32 v[240:241], v[240:241], v[246:247]
	v_pk_mul_f32 v[242:243], v[242:243], v[246:247]
	v_exp_f32_e32 v242, v242
	v_exp_f32_e32 v243, v243
	v_exp_f32_e32 v240, v240
	v_exp_f32_e32 v241, v241
	v_min_f32_e32 v242, v242, v248
	v_min_f32_e32 v243, v243, v248
	v_pk_add_f32 v[240:241], v[240:241], v[244:245]
	v_pk_add_f32 v[242:243], v[242:243], v[244:245]
	v_rcp_f32_e32 v240, v240
	v_rcp_f32_e32 v241, v241
	s_nop 0
	v_pk_mul_f32 v[242:243], v[242:243], v[240:241]
	v_pk_mul_f32 v[90:91], v[90:91], v[242:243]
	v_lshlrev_b32_e32 v240, 16, v207
	v_and_b32_e32 v241, 0xffff0000, v207
	v_lshlrev_b32_e32 v242, 16, v211
	v_and_b32_e32 v243, 0xffff0000, v211
	global_load_dwordx4 v[204:207], v[250:251], off offset:256
	s_mov_b64 s[98:99], 0x2000000
	v_lshl_add_u64 v[254:255], v[250:251], 0, s[98:99]
	global_load_dwordx4 v[208:211], v[254:255], off offset:256
	v_pk_add_f32 v[240:241], v[240:241], v[120:121]
	v_pk_add_f32 v[242:243], v[242:243], v[160:161]
	v_pk_mul_f32 v[240:241], v[240:241], v[246:247]
	v_pk_mul_f32 v[242:243], v[242:243], v[246:247]
	v_exp_f32_e32 v242, v242
	v_exp_f32_e32 v243, v243
	v_exp_f32_e32 v240, v240
	v_exp_f32_e32 v241, v241
	v_min_f32_e32 v242, v242, v248
	v_min_f32_e32 v243, v243, v248
	v_pk_add_f32 v[240:241], v[240:241], v[244:245]
	v_pk_add_f32 v[242:243], v[242:243], v[244:245]
	v_rcp_f32_e32 v240, v240
	v_rcp_f32_e32 v241, v241
	s_nop 0
	v_pk_mul_f32 v[242:243], v[242:243], v[240:241]
	v_pk_mul_f32 v[92:93], v[92:93], v[242:243]
	s_waitcnt vmcnt(6)
	v_lshlrev_b32_e32 v240, 16, v212
	v_and_b32_e32 v241, 0xffff0000, v212
	v_lshlrev_b32_e32 v242, 16, v216
	v_and_b32_e32 v243, 0xffff0000, v216
	v_pk_add_f32 v[240:241], v[240:241], v[114:115]
	v_pk_add_f32 v[242:243], v[242:243], v[154:155]
	v_pk_mul_f32 v[240:241], v[240:241], v[246:247]
	v_pk_mul_f32 v[242:243], v[242:243], v[246:247]
	v_exp_f32_e32 v242, v242
	v_exp_f32_e32 v243, v243
	v_exp_f32_e32 v240, v240
	v_exp_f32_e32 v241, v241
	v_min_f32_e32 v242, v242, v248
	v_min_f32_e32 v243, v243, v248
	v_pk_add_f32 v[240:241], v[240:241], v[244:245]
	v_pk_add_f32 v[242:243], v[242:243], v[244:245]
	v_rcp_f32_e32 v240, v240
	v_rcp_f32_e32 v241, v241
	s_nop 0
	v_pk_mul_f32 v[242:243], v[242:243], v[240:241]
	v_pk_mul_f32 v[86:87], v[86:87], v[242:243]
	v_lshlrev_b32_e32 v240, 16, v213
	v_and_b32_e32 v241, 0xffff0000, v213
	v_lshlrev_b32_e32 v242, 16, v217
	v_and_b32_e32 v243, 0xffff0000, v217
	v_pk_add_f32 v[240:241], v[240:241], v[116:117]
	v_pk_add_f32 v[242:243], v[242:243], v[156:157]
	v_pk_mul_f32 v[240:241], v[240:241], v[246:247]
	v_pk_mul_f32 v[242:243], v[242:243], v[246:247]
	v_exp_f32_e32 v242, v242
	v_exp_f32_e32 v243, v243
	v_exp_f32_e32 v240, v240
	v_exp_f32_e32 v241, v241
	v_min_f32_e32 v242, v242, v248
	v_min_f32_e32 v243, v243, v248
	v_pk_add_f32 v[240:241], v[240:241], v[244:245]
	v_pk_add_f32 v[242:243], v[242:243], v[244:245]
	v_rcp_f32_e32 v240, v240
	v_rcp_f32_e32 v241, v241
	s_nop 0
	v_pk_mul_f32 v[242:243], v[242:243], v[240:241]
	v_pk_mul_f32 v[88:89], v[88:89], v[242:243]
	v_lshlrev_b32_e32 v240, 16, v214
	v_and_b32_e32 v241, 0xffff0000, v214
	v_lshlrev_b32_e32 v242, 16, v218
	v_and_b32_e32 v243, 0xffff0000, v218
	v_pk_add_f32 v[240:241], v[240:241], v[118:119]
	v_pk_add_f32 v[242:243], v[242:243], v[158:159]
	v_pk_mul_f32 v[240:241], v[240:241], v[246:247]
	v_pk_mul_f32 v[242:243], v[242:243], v[246:247]
	v_exp_f32_e32 v242, v242
	v_exp_f32_e32 v243, v243
	v_exp_f32_e32 v240, v240
	v_exp_f32_e32 v241, v241
	v_min_f32_e32 v242, v242, v248
	v_min_f32_e32 v243, v243, v248
	v_pk_add_f32 v[240:241], v[240:241], v[244:245]
	v_pk_add_f32 v[242:243], v[242:243], v[244:245]
	v_rcp_f32_e32 v240, v240
	v_rcp_f32_e32 v241, v241
	s_nop 0
	v_pk_mul_f32 v[242:243], v[242:243], v[240:241]
	v_pk_mul_f32 v[82:83], v[82:83], v[242:243]
	v_lshlrev_b32_e32 v240, 16, v215
	v_and_b32_e32 v241, 0xffff0000, v215
	v_lshlrev_b32_e32 v242, 16, v219
	v_and_b32_e32 v243, 0xffff0000, v219
	s_mov_b64 s[98:99], 0x4000
	v_lshl_add_u64 v[254:255], v[250:251], 0, s[98:99]
	global_load_dwordx4 v[212:215], v[254:255], off offset:256
	s_mov_b64 s[98:99], 0x2004000
	v_lshl_add_u64 v[254:255], v[250:251], 0, s[98:99]
	global_load_dwordx4 v[216:219], v[254:255], off offset:256
	v_pk_add_f32 v[240:241], v[240:241], v[120:121]
	v_pk_add_f32 v[242:243], v[242:243], v[160:161]
	v_pk_mul_f32 v[240:241], v[240:241], v[246:247]
	v_pk_mul_f32 v[242:243], v[242:243], v[246:247]
	v_exp_f32_e32 v242, v242
	v_exp_f32_e32 v243, v243
	v_exp_f32_e32 v240, v240
	v_exp_f32_e32 v241, v241
	v_min_f32_e32 v242, v242, v248
	v_min_f32_e32 v243, v243, v248
	v_pk_add_f32 v[240:241], v[240:241], v[244:245]
	v_pk_add_f32 v[242:243], v[242:243], v[244:245]
	v_rcp_f32_e32 v240, v240
	v_rcp_f32_e32 v241, v241
	s_nop 0
	v_pk_mul_f32 v[242:243], v[242:243], v[240:241]
	v_pk_mul_f32 v[84:85], v[84:85], v[242:243]
	s_waitcnt vmcnt(6)
; __device__ __forceinline__ float bflo(unsigned u) { return __uint_as_float(u << 16); }
; __device__ __forceinline__ float bfhi(unsigned u) { return __uint_as_float(u & 0xffff0000u); }
; __device__ __forceinline__ float sigm(float v) { return __builtin_amdgcn_rcpf(1.0f + __expf(-v)); }
; DI float bflo(unsigned u) { return __uint_as_float(u << 16); }
; DI float bfhi(unsigned u) { return __uint_as_float(u & 0xffff0000u); }
;     __device__ __forceinline__ void operator()(const f32x4 (&acc)[2][2][4][2], const Unit& u, int wr, int wc, int fr, int fq) const {
;     ...
;         for (int bj = 0; bj < 2; ++bj) {
;             const f32x4 b0 = *(const f32x4*)(gb + col0 + bj * HALF), b1 = *(const f32x4*)(gb + col0 + bj * HALF + 4);
; #pragma unroll
;             for (int ai = 0; ai < 2; ++ai)
; #pragma unroll
;                 for (int m = 0; m < 4; ++m) { const size_t row = (size_t)(row0 + ai * HALF + m * 16);
;                     const u32x4 g = *(const u32x4*)(gbase + row * 512 + gcol0 + bj * HALF);
;                     const f32x4 v0 = acc[ai][bj][m][0], v1 = acc[ai][bj][m][1];
;                     float r0 = v0[0] * sigm(bflo(g.x) + b0[0]), r1 = v0[1] * sigm(bfhi(g.x) + b0[1]), r2 = v0[2] * sigm(bflo(g.y) + b0[2]), r3 = v0[3] * sigm(bfhi(g.y) + b0[3]);
;                     float r4 = v1[0] * sigm(bflo(g.z) + b1[0]), r5 = v1[1] * sigm(bfhi(g.z) + b1[1]), r6 = v1[2] * sigm(bflo(g.w) + b1[2]), r7 = v1[3] * sigm(bfhi(g.w) + b1[3]);
	v_lshlrev_b32_e32 v240, 16, v220
	v_and_b32_e32 v241, 0xffff0000, v220
	v_lshlrev_b32_e32 v242, 16, v224
	v_and_b32_e32 v243, 0xffff0000, v224
	v_pk_add_f32 v[240:241], v[240:241], v[114:115]
	v_pk_add_f32 v[242:243], v[242:243], v[154:155]
	v_pk_mul_f32 v[240:241], v[240:241], v[246:247]
	v_pk_mul_f32 v[242:243], v[242:243], v[246:247]
	v_exp_f32_e32 v242, v242
	v_exp_f32_e32 v243, v243
	v_exp_f32_e32 v240, v240
	v_exp_f32_e32 v241, v241
	v_min_f32_e32 v242, v242, v248
	v_min_f32_e32 v243, v243, v248
	v_pk_add_f32 v[240:241], v[240:241], v[244:245]
	v_pk_add_f32 v[242:243], v[242:243], v[244:245]
	v_rcp_f32_e32 v240, v240
	v_rcp_f32_e32 v241, v241
	s_nop 0
	v_pk_mul_f32 v[242:243], v[242:243], v[240:241]
	v_pk_mul_f32 v[78:79], v[78:79], v[242:243]
	v_lshlrev_b32_e32 v240, 16, v221
	v_and_b32_e32 v241, 0xffff0000, v221
	v_lshlrev_b32_e32 v242, 16, v225
	v_and_b32_e32 v243, 0xffff0000, v225
	v_pk_add_f32 v[240:241], v[240:241], v[116:117]
	v_pk_add_f32 v[242:243], v[242:243], v[156:157]
	v_pk_mul_f32 v[240:241], v[240:241], v[246:247]
	v_pk_mul_f32 v[242:243], v[242:243], v[246:247]
	v_exp_f32_e32 v242, v242
	v_exp_f32_e32 v243, v243
	v_exp_f32_e32 v240, v240
	v_exp_f32_e32 v241, v241
	v_min_f32_e32 v242, v242, v248
	v_min_f32_e32 v243, v243, v248
	v_pk_add_f32 v[240:241], v[240:241], v[244:245]
	v_pk_add_f32 v[242:243], v[242:243], v[244:245]
	v_rcp_f32_e32 v240, v240
	v_rcp_f32_e32 v241, v241
	s_nop 0
	v_pk_mul_f32 v[242:243], v[242:243], v[240:241]
	v_pk_mul_f32 v[80:81], v[80:81], v[242:243]
	v_lshlrev_b32_e32 v240, 16, v222
	v_and_b32_e32 v241, 0xffff0000, v222
	v_lshlrev_b32_e32 v242, 16, v226
	v_and_b32_e32 v243, 0xffff0000, v226
	v_pk_add_f32 v[240:241], v[240:241], v[118:119]
	v_pk_add_f32 v[242:243], v[242:243], v[158:159]
	v_pk_mul_f32 v[240:241], v[240:241], v[246:247]
	v_pk_mul_f32 v[242:243], v[242:243], v[246:247]
	v_exp_f32_e32 v242, v242
	v_exp_f32_e32 v243, v243
	v_exp_f32_e32 v240, v240
	v_exp_f32_e32 v241, v241
	v_min_f32_e32 v242, v242, v248
	v_min_f32_e32 v243, v243, v248
	v_pk_add_f32 v[240:241], v[240:241], v[244:245]
	v_pk_add_f32 v[242:243], v[242:243], v[244:245]
	v_rcp_f32_e32 v240, v240
	v_rcp_f32_e32 v241, v241
	s_nop 0
	v_pk_mul_f32 v[242:243], v[242:243], v[240:241]
	v_pk_mul_f32 v[74:75], v[74:75], v[242:243]
	v_lshlrev_b32_e32 v240, 16, v223
	v_and_b32_e32 v241, 0xffff0000, v223
	v_lshlrev_b32_e32 v242, 16, v227
	v_and_b32_e32 v243, 0xffff0000, v227
	s_mov_b64 s[98:99], 0x8000
	v_lshl_add_u64 v[254:255], v[250:251], 0, s[98:99]
	global_load_dwordx4 v[220:223], v[254:255], off offset:256
	s_mov_b64 s[98:99], 0x2008000
	v_lshl_add_u64 v[254:255], v[250:251], 0, s[98:99]
	global_load_dwordx4 v[224:227], v[254:255], off offset:256
	v_pk_add_f32 v[240:241], v[240:241], v[120:121]
	v_pk_add_f32 v[242:243], v[242:243], v[160:161]
	v_pk_mul_f32 v[240:241], v[240:241], v[246:247]
	v_pk_mul_f32 v[242:243], v[242:243], v[246:247]
	v_exp_f32_e32 v242, v242
	v_exp_f32_e32 v243, v243
	v_exp_f32_e32 v240, v240
	v_exp_f32_e32 v241, v241
	v_min_f32_e32 v242, v242, v248
	v_min_f32_e32 v243, v243, v248
	v_pk_add_f32 v[240:241], v[240:241], v[244:245]
	v_pk_add_f32 v[242:243], v[242:243], v[244:245]
	v_rcp_f32_e32 v240, v240
	v_rcp_f32_e32 v241, v241
	s_nop 0
	v_pk_mul_f32 v[242:243], v[242:243], v[240:241]
	v_pk_mul_f32 v[76:77], v[76:77], v[242:243]
	s_waitcnt vmcnt(6)
	v_lshlrev_b32_e32 v240, 16, v192
	v_and_b32_e32 v241, 0xffff0000, v192
	v_lshlrev_b32_e32 v242, 16, v166
	v_and_b32_e32 v243, 0xffff0000, v166
	v_pk_add_f32 v[240:241], v[240:241], v[114:115]
	v_pk_add_f32 v[242:243], v[242:243], v[154:155]
	v_pk_mul_f32 v[240:241], v[240:241], v[246:247]
	v_pk_mul_f32 v[242:243], v[242:243], v[246:247]
	v_exp_f32_e32 v242, v242
	v_exp_f32_e32 v243, v243
	v_exp_f32_e32 v240, v240
	v_exp_f32_e32 v241, v241
	v_min_f32_e32 v242, v242, v248
	v_min_f32_e32 v243, v243, v248
	v_pk_add_f32 v[240:241], v[240:241], v[244:245]
	v_pk_add_f32 v[242:243], v[242:243], v[244:245]
	v_rcp_f32_e32 v240, v240
	v_rcp_f32_e32 v241, v241
	s_nop 0
	v_pk_mul_f32 v[242:243], v[242:243], v[240:241]
	v_pk_mul_f32 v[70:71], v[70:71], v[242:243]
	v_lshlrev_b32_e32 v240, 16, v193
	v_and_b32_e32 v241, 0xffff0000, v193
	v_lshlrev_b32_e32 v242, 16, v167
	v_and_b32_e32 v243, 0xffff0000, v167
	v_pk_add_f32 v[240:241], v[240:241], v[116:117]
	v_pk_add_f32 v[242:243], v[242:243], v[156:157]
	v_pk_mul_f32 v[240:241], v[240:241], v[246:247]
	v_pk_mul_f32 v[242:243], v[242:243], v[246:247]
	v_exp_f32_e32 v242, v242
	v_exp_f32_e32 v243, v243
	v_exp_f32_e32 v240, v240
	v_exp_f32_e32 v241, v241
	v_min_f32_e32 v242, v242, v248
	v_min_f32_e32 v243, v243, v248
	v_pk_add_f32 v[240:241], v[240:241], v[244:245]
	v_pk_add_f32 v[242:243], v[242:243], v[244:245]
	v_rcp_f32_e32 v240, v240
	v_rcp_f32_e32 v241, v241
	s_nop 0
	v_pk_mul_f32 v[242:243], v[242:243], v[240:241]
	v_pk_mul_f32 v[72:73], v[72:73], v[242:243]
	v_lshlrev_b32_e32 v240, 16, v194
	v_and_b32_e32 v241, 0xffff0000, v194
	v_lshlrev_b32_e32 v242, 16, v168
	v_and_b32_e32 v243, 0xffff0000, v168
	v_pk_add_f32 v[240:241], v[240:241], v[118:119]
	v_pk_add_f32 v[242:243], v[242:243], v[158:159]
	v_pk_mul_f32 v[240:241], v[240:241], v[246:247]
	v_pk_mul_f32 v[242:243], v[242:243], v[246:247]
	v_exp_f32_e32 v242, v242
	v_exp_f32_e32 v243, v243
	v_exp_f32_e32 v240, v240
	v_exp_f32_e32 v241, v241
	v_min_f32_e32 v242, v242, v248
	v_min_f32_e32 v243, v243, v248
	v_pk_add_f32 v[240:241], v[240:241], v[244:245]
	v_pk_add_f32 v[242:243], v[242:243], v[244:245]
	v_rcp_f32_e32 v240, v240
	v_rcp_f32_e32 v241, v241
	s_nop 0
	v_pk_mul_f32 v[242:243], v[242:243], v[240:241]
	v_pk_mul_f32 v[66:67], v[66:67], v[242:243]
	v_lshlrev_b32_e32 v240, 16, v195
	v_and_b32_e32 v241, 0xffff0000, v195
	v_lshlrev_b32_e32 v242, 16, v169
	v_and_b32_e32 v243, 0xffff0000, v169
	s_mov_b64 s[98:99], 0xc000
	v_lshl_add_u64 v[254:255], v[250:251], 0, s[98:99]
	global_load_dwordx4 v[192:195], v[254:255], off offset:256
	s_mov_b64 s[98:99], 0x200c000
	v_lshl_add_u64 v[254:255], v[250:251], 0, s[98:99]
	global_load_dwordx4 v[166:169], v[254:255], off offset:256
	v_pk_add_f32 v[240:241], v[240:241], v[120:121]
	v_pk_add_f32 v[242:243], v[242:243], v[160:161]
	v_pk_mul_f32 v[240:241], v[240:241], v[246:247]
	v_pk_mul_f32 v[242:243], v[242:243], v[246:247]
	v_exp_f32_e32 v242, v242
	v_exp_f32_e32 v243, v243
	v_exp_f32_e32 v240, v240
	v_exp_f32_e32 v241, v241
	v_min_f32_e32 v242, v242, v248
	v_min_f32_e32 v243, v243, v248
	v_pk_add_f32 v[240:241], v[240:241], v[244:245]
	v_pk_add_f32 v[242:243], v[242:243], v[244:245]
	v_rcp_f32_e32 v240, v240
	v_rcp_f32_e32 v241, v241
	s_nop 0
	v_pk_mul_f32 v[242:243], v[242:243], v[240:241]
	v_pk_mul_f32 v[68:69], v[68:69], v[242:243]
	s_waitcnt vmcnt(6)
; __device__ __forceinline__ float bflo(unsigned u) { return __uint_as_float(u << 16); }
; __device__ __forceinline__ float bfhi(unsigned u) { return __uint_as_float(u & 0xffff0000u); }
; __device__ __forceinline__ float sigm(float v) { return __builtin_amdgcn_rcpf(1.0f + __expf(-v)); }
; DI float bflo(unsigned u) { return __uint_as_float(u << 16); }
; DI float bfhi(unsigned u) { return __uint_as_float(u & 0xffff0000u); }
;     __device__ __forceinline__ void operator()(const f32x4 (&acc)[2][2][4][2], const Unit& u, int wr, int wc, int fr, int fq) const {
;     ...
;         for (int bj = 0; bj < 2; ++bj) {
;             const f32x4 b0 = *(const f32x4*)(gb + col0 + bj * HALF), b1 = *(const f32x4*)(gb + col0 + bj * HALF + 4);
; #pragma unroll
;             for (int ai = 0; ai < 2; ++ai)
; #pragma unroll
;                 for (int m = 0; m < 4; ++m) { const size_t row = (size_t)(row0 + ai * HALF + m * 16);
;                     const u32x4 g = *(const u32x4*)(gbase + row * 512 + gcol0 + bj * HALF);
;                     const f32x4 v0 = acc[ai][bj][m][0], v1 = acc[ai][bj][m][1];
;                     float r0 = v0[0] * sigm(bflo(g.x) + b0[0]), r1 = v0[1] * sigm(bfhi(g.x) + b0[1]), r2 = v0[2] * sigm(bflo(g.y) + b0[2]), r3 = v0[3] * sigm(bfhi(g.y) + b0[3]);
;                     float r4 = v1[0] * sigm(bflo(g.z) + b1[0]), r5 = v1[1] * sigm(bfhi(g.z) + b1[1]), r6 = v1[2] * sigm(bflo(g.w) + b1[2]), r7 = v1[3] * sigm(bfhi(g.w) + b1[3]);
	v_lshlrev_b32_e32 v240, 16, v204
	v_and_b32_e32 v241, 0xffff0000, v204
	v_lshlrev_b32_e32 v242, 16, v208
	v_and_b32_e32 v243, 0xffff0000, v208
	v_pk_add_f32 v[240:241], v[240:241], v[176:177]
	v_pk_add_f32 v[242:243], v[242:243], v[184:185]
	v_pk_mul_f32 v[240:241], v[240:241], v[246:247]
	v_pk_mul_f32 v[242:243], v[242:243], v[246:247]
	v_exp_f32_e32 v242, v242
	v_exp_f32_e32 v243, v243
	v_exp_f32_e32 v240, v240
	v_exp_f32_e32 v241, v241
	v_min_f32_e32 v242, v242, v248
	v_min_f32_e32 v243, v243, v248
	v_pk_add_f32 v[240:241], v[240:241], v[244:245]
	v_pk_add_f32 v[242:243], v[242:243], v[244:245]
	v_rcp_f32_e32 v240, v240
	v_rcp_f32_e32 v241, v241
	s_nop 0
	v_pk_mul_f32 v[242:243], v[242:243], v[240:241]
	v_pk_mul_f32 v[62:63], v[62:63], v[242:243]
	v_lshlrev_b32_e32 v240, 16, v205
	v_and_b32_e32 v241, 0xffff0000, v205
	v_lshlrev_b32_e32 v242, 16, v209
	v_and_b32_e32 v243, 0xffff0000, v209
	v_pk_add_f32 v[240:241], v[240:241], v[178:179]
	v_pk_add_f32 v[242:243], v[242:243], v[186:187]
	v_pk_mul_f32 v[240:241], v[240:241], v[246:247]
	v_pk_mul_f32 v[242:243], v[242:243], v[246:247]
	v_exp_f32_e32 v242, v242
	v_exp_f32_e32 v243, v243
	v_exp_f32_e32 v240, v240
	v_exp_f32_e32 v241, v241
	v_min_f32_e32 v242, v242, v248
	v_min_f32_e32 v243, v243, v248
	v_pk_add_f32 v[240:241], v[240:241], v[244:245]
	v_pk_add_f32 v[242:243], v[242:243], v[244:245]
	v_rcp_f32_e32 v240, v240
	v_rcp_f32_e32 v241, v241
	s_nop 0
	v_pk_mul_f32 v[242:243], v[242:243], v[240:241]
	v_pk_mul_f32 v[64:65], v[64:65], v[242:243]
	v_lshlrev_b32_e32 v240, 16, v206
	v_and_b32_e32 v241, 0xffff0000, v206
	v_lshlrev_b32_e32 v242, 16, v210
	v_and_b32_e32 v243, 0xffff0000, v210
	v_pk_add_f32 v[240:241], v[240:241], v[180:181]
	v_pk_add_f32 v[242:243], v[242:243], v[188:189]
	v_pk_mul_f32 v[240:241], v[240:241], v[246:247]
	v_pk_mul_f32 v[242:243], v[242:243], v[246:247]
	v_exp_f32_e32 v242, v242
	v_exp_f32_e32 v243, v243
	v_exp_f32_e32 v240, v240
	v_exp_f32_e32 v241, v241
	v_min_f32_e32 v242, v242, v248
	v_min_f32_e32 v243, v243, v248
	v_pk_add_f32 v[240:241], v[240:241], v[244:245]
	v_pk_add_f32 v[242:243], v[242:243], v[244:245]
	v_rcp_f32_e32 v240, v240
	v_rcp_f32_e32 v241, v241
	s_nop 0
	v_pk_mul_f32 v[242:243], v[242:243], v[240:241]
	v_pk_mul_f32 v[58:59], v[58:59], v[242:243]
	v_lshlrev_b32_e32 v240, 16, v207
	v_and_b32_e32 v241, 0xffff0000, v207
	v_lshlrev_b32_e32 v242, 16, v211
	v_and_b32_e32 v243, 0xffff0000, v211
	s_mov_b64 s[98:99], 0x20000
	v_lshl_add_u64 v[254:255], v[250:251], 0, s[98:99]
	global_load_dwordx4 v[204:207], v[254:255], off offset:256
	s_mov_b64 s[98:99], 0x2020000
	v_lshl_add_u64 v[254:255], v[250:251], 0, s[98:99]
	global_load_dwordx4 v[208:211], v[254:255], off offset:256
	v_pk_add_f32 v[240:241], v[240:241], v[182:183]
	v_pk_add_f32 v[242:243], v[242:243], v[190:191]
	v_pk_mul_f32 v[240:241], v[240:241], v[246:247]
	v_pk_mul_f32 v[242:243], v[242:243], v[246:247]
	v_exp_f32_e32 v242, v242
	v_exp_f32_e32 v243, v243
	v_exp_f32_e32 v240, v240
	v_exp_f32_e32 v241, v241
	v_min_f32_e32 v242, v242, v248
	v_min_f32_e32 v243, v243, v248
	v_pk_add_f32 v[240:241], v[240:241], v[244:245]
	v_pk_add_f32 v[242:243], v[242:243], v[244:245]
	v_rcp_f32_e32 v240, v240
	v_rcp_f32_e32 v241, v241
	s_nop 0
	v_pk_mul_f32 v[242:243], v[242:243], v[240:241]
	v_pk_mul_f32 v[60:61], v[60:61], v[242:243]
	s_waitcnt vmcnt(6)
	v_lshlrev_b32_e32 v240, 16, v212
	v_and_b32_e32 v241, 0xffff0000, v212
	v_lshlrev_b32_e32 v242, 16, v216
	v_and_b32_e32 v243, 0xffff0000, v216
	v_pk_add_f32 v[240:241], v[240:241], v[176:177]
	v_pk_add_f32 v[242:243], v[242:243], v[184:185]
	v_pk_mul_f32 v[240:241], v[240:241], v[246:247]
	v_pk_mul_f32 v[242:243], v[242:243], v[246:247]
	v_exp_f32_e32 v242, v242
	v_exp_f32_e32 v243, v243
	v_exp_f32_e32 v240, v240
	v_exp_f32_e32 v241, v241
	v_min_f32_e32 v242, v242, v248
	v_min_f32_e32 v243, v243, v248
	v_pk_add_f32 v[240:241], v[240:241], v[244:245]
	v_pk_add_f32 v[242:243], v[242:243], v[244:245]
	v_rcp_f32_e32 v240, v240
	v_rcp_f32_e32 v241, v241
	s_nop 0
	v_pk_mul_f32 v[242:243], v[242:243], v[240:241]
	v_pk_mul_f32 v[54:55], v[54:55], v[242:243]
	v_lshlrev_b32_e32 v240, 16, v213
	v_and_b32_e32 v241, 0xffff0000, v213
	v_lshlrev_b32_e32 v242, 16, v217
	v_and_b32_e32 v243, 0xffff0000, v217
	v_pk_add_f32 v[240:241], v[240:241], v[178:179]
	v_pk_add_f32 v[242:243], v[242:243], v[186:187]
	v_pk_mul_f32 v[240:241], v[240:241], v[246:247]
	v_pk_mul_f32 v[242:243], v[242:243], v[246:247]
	v_exp_f32_e32 v242, v242
	v_exp_f32_e32 v243, v243
	v_exp_f32_e32 v240, v240
	v_exp_f32_e32 v241, v241
	v_min_f32_e32 v242, v242, v248
	v_min_f32_e32 v243, v243, v248
	v_pk_add_f32 v[240:241], v[240:241], v[244:245]
	v_pk_add_f32 v[242:243], v[242:243], v[244:245]
	v_rcp_f32_e32 v240, v240
	v_rcp_f32_e32 v241, v241
	s_nop 0
	v_pk_mul_f32 v[242:243], v[242:243], v[240:241]
	v_pk_mul_f32 v[56:57], v[56:57], v[242:243]
	v_lshlrev_b32_e32 v240, 16, v214
	v_and_b32_e32 v241, 0xffff0000, v214
	v_lshlrev_b32_e32 v242, 16, v218
	v_and_b32_e32 v243, 0xffff0000, v218
	v_pk_add_f32 v[240:241], v[240:241], v[180:181]
	v_pk_add_f32 v[242:243], v[242:243], v[188:189]
	v_pk_mul_f32 v[240:241], v[240:241], v[246:247]
	v_pk_mul_f32 v[242:243], v[242:243], v[246:247]
	v_exp_f32_e32 v242, v242
	v_exp_f32_e32 v243, v243
	v_exp_f32_e32 v240, v240
	v_exp_f32_e32 v241, v241
	v_min_f32_e32 v242, v242, v248
	v_min_f32_e32 v243, v243, v248
	v_pk_add_f32 v[240:241], v[240:241], v[244:245]
	v_pk_add_f32 v[242:243], v[242:243], v[244:245]
	v_rcp_f32_e32 v240, v240
	v_rcp_f32_e32 v241, v241
	s_nop 0
	v_pk_mul_f32 v[242:243], v[242:243], v[240:241]
	v_pk_mul_f32 v[50:51], v[50:51], v[242:243]
	v_lshlrev_b32_e32 v240, 16, v215
	v_and_b32_e32 v241, 0xffff0000, v215
	v_lshlrev_b32_e32 v242, 16, v219
	v_and_b32_e32 v243, 0xffff0000, v219
	s_mov_b64 s[98:99], 0x24000
	v_lshl_add_u64 v[254:255], v[250:251], 0, s[98:99]
	global_load_dwordx4 v[212:215], v[254:255], off offset:256
	s_mov_b64 s[98:99], 0x2024000
	v_lshl_add_u64 v[254:255], v[250:251], 0, s[98:99]
	global_load_dwordx4 v[216:219], v[254:255], off offset:256
	v_pk_add_f32 v[240:241], v[240:241], v[182:183]
	v_pk_add_f32 v[242:243], v[242:243], v[190:191]
	v_pk_mul_f32 v[240:241], v[240:241], v[246:247]
	v_pk_mul_f32 v[242:243], v[242:243], v[246:247]
	v_exp_f32_e32 v242, v242
	v_exp_f32_e32 v243, v243
	v_exp_f32_e32 v240, v240
	v_exp_f32_e32 v241, v241
	v_min_f32_e32 v242, v242, v248
	v_min_f32_e32 v243, v243, v248
	v_pk_add_f32 v[240:241], v[240:241], v[244:245]
	v_pk_add_f32 v[242:243], v[242:243], v[244:245]
	v_rcp_f32_e32 v240, v240
	v_rcp_f32_e32 v241, v241
	s_nop 0
	v_pk_mul_f32 v[242:243], v[242:243], v[240:241]
	v_pk_mul_f32 v[52:53], v[52:53], v[242:243]
	s_waitcnt vmcnt(6)
; __device__ __forceinline__ float bflo(unsigned u) { return __uint_as_float(u << 16); }
; __device__ __forceinline__ float bfhi(unsigned u) { return __uint_as_float(u & 0xffff0000u); }
; __device__ __forceinline__ float sigm(float v) { return __builtin_amdgcn_rcpf(1.0f + __expf(-v)); }
; DI float bflo(unsigned u) { return __uint_as_float(u << 16); }
; DI float bfhi(unsigned u) { return __uint_as_float(u & 0xffff0000u); }
;     __device__ __forceinline__ void operator()(const f32x4 (&acc)[2][2][4][2], const Unit& u, int wr, int wc, int fr, int fq) const {
;     ...
;         for (int bj = 0; bj < 2; ++bj) {
;             const f32x4 b0 = *(const f32x4*)(gb + col0 + bj * HALF), b1 = *(const f32x4*)(gb + col0 + bj * HALF + 4);
; #pragma unroll
;             for (int ai = 0; ai < 2; ++ai)
; #pragma unroll
;                 for (int m = 0; m < 4; ++m) { const size_t row = (size_t)(row0 + ai * HALF + m * 16);
;                     const u32x4 g = *(const u32x4*)(gbase + row * 512 + gcol0 + bj * HALF);
;                     const f32x4 v0 = acc[ai][bj][m][0], v1 = acc[ai][bj][m][1];
;                     float r0 = v0[0] * sigm(bflo(g.x) + b0[0]), r1 = v0[1] * sigm(bfhi(g.x) + b0[1]), r2 = v0[2] * sigm(bflo(g.y) + b0[2]), r3 = v0[3] * sigm(bfhi(g.y) + b0[3]);
;                     float r4 = v1[0] * sigm(bflo(g.z) + b1[0]), r5 = v1[1] * sigm(bfhi(g.z) + b1[1]), r6 = v1[2] * sigm(bflo(g.w) + b1[2]), r7 = v1[3] * sigm(bfhi(g.w) + b1[3]);
	v_lshlrev_b32_e32 v240, 16, v220
	v_and_b32_e32 v241, 0xffff0000, v220
	v_lshlrev_b32_e32 v242, 16, v224
	v_and_b32_e32 v243, 0xffff0000, v224
	v_pk_add_f32 v[240:241], v[240:241], v[176:177]
	v_pk_add_f32 v[242:243], v[242:243], v[184:185]
	v_pk_mul_f32 v[240:241], v[240:241], v[246:247]
	v_pk_mul_f32 v[242:243], v[242:243], v[246:247]
	v_exp_f32_e32 v242, v242
	v_exp_f32_e32 v243, v243
	v_exp_f32_e32 v240, v240
	v_exp_f32_e32 v241, v241
	v_min_f32_e32 v242, v242, v248
	v_min_f32_e32 v243, v243, v248
	v_pk_add_f32 v[240:241], v[240:241], v[244:245]
	v_pk_add_f32 v[242:243], v[242:243], v[244:245]
	v_rcp_f32_e32 v240, v240
	v_rcp_f32_e32 v241, v241
	s_nop 0
	v_pk_mul_f32 v[242:243], v[242:243], v[240:241]
	v_pk_mul_f32 v[46:47], v[46:47], v[242:243]
	v_lshlrev_b32_e32 v240, 16, v221
	v_and_b32_e32 v241, 0xffff0000, v221
	v_lshlrev_b32_e32 v242, 16, v225
	v_and_b32_e32 v243, 0xffff0000, v225
	v_pk_add_f32 v[240:241], v[240:241], v[178:179]
	v_pk_add_f32 v[242:243], v[242:243], v[186:187]
	v_pk_mul_f32 v[240:241], v[240:241], v[246:247]
	v_pk_mul_f32 v[242:243], v[242:243], v[246:247]
	v_exp_f32_e32 v242, v242
	v_exp_f32_e32 v243, v243
	v_exp_f32_e32 v240, v240
	v_exp_f32_e32 v241, v241
	v_min_f32_e32 v242, v242, v248
	v_min_f32_e32 v243, v243, v248
	v_pk_add_f32 v[240:241], v[240:241], v[244:245]
	v_pk_add_f32 v[242:243], v[242:243], v[244:245]
	v_rcp_f32_e32 v240, v240
	v_rcp_f32_e32 v241, v241
	s_nop 0
	v_pk_mul_f32 v[242:243], v[242:243], v[240:241]
	v_pk_mul_f32 v[48:49], v[48:49], v[242:243]
	v_lshlrev_b32_e32 v240, 16, v222
	v_and_b32_e32 v241, 0xffff0000, v222
	v_lshlrev_b32_e32 v242, 16, v226
	v_and_b32_e32 v243, 0xffff0000, v226
	v_pk_add_f32 v[240:241], v[240:241], v[180:181]
	v_pk_add_f32 v[242:243], v[242:243], v[188:189]
	v_pk_mul_f32 v[240:241], v[240:241], v[246:247]
	v_pk_mul_f32 v[242:243], v[242:243], v[246:247]
	v_exp_f32_e32 v242, v242
	v_exp_f32_e32 v243, v243
	v_exp_f32_e32 v240, v240
	v_exp_f32_e32 v241, v241
	v_min_f32_e32 v242, v242, v248
	v_min_f32_e32 v243, v243, v248
	v_pk_add_f32 v[240:241], v[240:241], v[244:245]
	v_pk_add_f32 v[242:243], v[242:243], v[244:245]
	v_rcp_f32_e32 v240, v240
	v_rcp_f32_e32 v241, v241
	s_nop 0
	v_pk_mul_f32 v[242:243], v[242:243], v[240:241]
	v_pk_mul_f32 v[42:43], v[42:43], v[242:243]
	v_lshlrev_b32_e32 v240, 16, v223
	v_and_b32_e32 v241, 0xffff0000, v223
	v_lshlrev_b32_e32 v242, 16, v227
	v_and_b32_e32 v243, 0xffff0000, v227
	s_mov_b64 s[98:99], 0x28000
	v_lshl_add_u64 v[254:255], v[250:251], 0, s[98:99]
	global_load_dwordx4 v[220:223], v[254:255], off offset:256
	s_mov_b64 s[98:99], 0x2028000
	v_lshl_add_u64 v[254:255], v[250:251], 0, s[98:99]
	global_load_dwordx4 v[224:227], v[254:255], off offset:256
	v_pk_add_f32 v[240:241], v[240:241], v[182:183]
	v_pk_add_f32 v[242:243], v[242:243], v[190:191]
	v_pk_mul_f32 v[240:241], v[240:241], v[246:247]
	v_pk_mul_f32 v[242:243], v[242:243], v[246:247]
	v_exp_f32_e32 v242, v242
	v_exp_f32_e32 v243, v243
	v_exp_f32_e32 v240, v240
	v_exp_f32_e32 v241, v241
	v_min_f32_e32 v242, v242, v248
	v_min_f32_e32 v243, v243, v248
	v_pk_add_f32 v[240:241], v[240:241], v[244:245]
	v_pk_add_f32 v[242:243], v[242:243], v[244:245]
	v_rcp_f32_e32 v240, v240
	v_rcp_f32_e32 v241, v241
	s_nop 0
	v_pk_mul_f32 v[242:243], v[242:243], v[240:241]
	v_pk_mul_f32 v[44:45], v[44:45], v[242:243]
	s_waitcnt vmcnt(6)
	v_lshlrev_b32_e32 v240, 16, v192
	v_and_b32_e32 v241, 0xffff0000, v192
	v_lshlrev_b32_e32 v242, 16, v166
	v_and_b32_e32 v243, 0xffff0000, v166
	v_pk_add_f32 v[240:241], v[240:241], v[176:177]
	v_pk_add_f32 v[242:243], v[242:243], v[184:185]
	v_pk_mul_f32 v[240:241], v[240:241], v[246:247]
	v_pk_mul_f32 v[242:243], v[242:243], v[246:247]
	v_exp_f32_e32 v242, v242
	v_exp_f32_e32 v243, v243
	v_exp_f32_e32 v240, v240
	v_exp_f32_e32 v241, v241
	v_min_f32_e32 v242, v242, v248
	v_min_f32_e32 v243, v243, v248
	v_pk_add_f32 v[240:241], v[240:241], v[244:245]
	v_pk_add_f32 v[242:243], v[242:243], v[244:245]
	v_rcp_f32_e32 v240, v240
	v_rcp_f32_e32 v241, v241
	s_nop 0
	v_pk_mul_f32 v[242:243], v[242:243], v[240:241]
	v_pk_mul_f32 v[38:39], v[38:39], v[242:243]
	v_lshlrev_b32_e32 v240, 16, v193
	v_and_b32_e32 v241, 0xffff0000, v193
	v_lshlrev_b32_e32 v242, 16, v167
	v_and_b32_e32 v243, 0xffff0000, v167
	v_pk_add_f32 v[240:241], v[240:241], v[178:179]
	v_pk_add_f32 v[242:243], v[242:243], v[186:187]
	v_pk_mul_f32 v[240:241], v[240:241], v[246:247]
	v_pk_mul_f32 v[242:243], v[242:243], v[246:247]
	v_exp_f32_e32 v242, v242
	v_exp_f32_e32 v243, v243
	v_exp_f32_e32 v240, v240
	v_exp_f32_e32 v241, v241
	v_min_f32_e32 v242, v242, v248
	v_min_f32_e32 v243, v243, v248
	v_pk_add_f32 v[240:241], v[240:241], v[244:245]
	v_pk_add_f32 v[242:243], v[242:243], v[244:245]
	v_rcp_f32_e32 v240, v240
	v_rcp_f32_e32 v241, v241
	s_nop 0
	v_pk_mul_f32 v[242:243], v[242:243], v[240:241]
	v_pk_mul_f32 v[40:41], v[40:41], v[242:243]
	v_lshlrev_b32_e32 v240, 16, v194
	v_and_b32_e32 v241, 0xffff0000, v194
	v_lshlrev_b32_e32 v242, 16, v168
	v_and_b32_e32 v243, 0xffff0000, v168
	v_pk_add_f32 v[240:241], v[240:241], v[180:181]
	v_pk_add_f32 v[242:243], v[242:243], v[188:189]
	v_pk_mul_f32 v[240:241], v[240:241], v[246:247]
	v_pk_mul_f32 v[242:243], v[242:243], v[246:247]
	v_exp_f32_e32 v242, v242
	v_exp_f32_e32 v243, v243
	v_exp_f32_e32 v240, v240
	v_exp_f32_e32 v241, v241
	v_min_f32_e32 v242, v242, v248
	v_min_f32_e32 v243, v243, v248
	v_pk_add_f32 v[240:241], v[240:241], v[244:245]
	v_pk_add_f32 v[242:243], v[242:243], v[244:245]
	v_rcp_f32_e32 v240, v240
	v_rcp_f32_e32 v241, v241
	s_nop 0
	v_pk_mul_f32 v[242:243], v[242:243], v[240:241]
	v_pk_mul_f32 v[34:35], v[34:35], v[242:243]
	v_lshlrev_b32_e32 v240, 16, v195
	v_and_b32_e32 v241, 0xffff0000, v195
	v_lshlrev_b32_e32 v242, 16, v169
	v_and_b32_e32 v243, 0xffff0000, v169
	s_mov_b64 s[98:99], 0x2c000
	v_lshl_add_u64 v[254:255], v[250:251], 0, s[98:99]
	global_load_dwordx4 v[192:195], v[254:255], off offset:256
	s_mov_b64 s[98:99], 0x202c000
	v_lshl_add_u64 v[254:255], v[250:251], 0, s[98:99]
	global_load_dwordx4 v[166:169], v[254:255], off offset:256
	v_pk_add_f32 v[240:241], v[240:241], v[182:183]
	v_pk_add_f32 v[242:243], v[242:243], v[190:191]
	v_pk_mul_f32 v[240:241], v[240:241], v[246:247]
	v_pk_mul_f32 v[242:243], v[242:243], v[246:247]
	v_exp_f32_e32 v242, v242
	v_exp_f32_e32 v243, v243
	v_exp_f32_e32 v240, v240
	v_exp_f32_e32 v241, v241
	v_min_f32_e32 v242, v242, v248
	v_min_f32_e32 v243, v243, v248
	v_pk_add_f32 v[240:241], v[240:241], v[244:245]
	v_pk_add_f32 v[242:243], v[242:243], v[244:245]
	v_rcp_f32_e32 v240, v240
	v_rcp_f32_e32 v241, v241
	s_nop 0
	v_pk_mul_f32 v[242:243], v[242:243], v[240:241]
	v_pk_mul_f32 v[36:37], v[36:37], v[242:243]
	s_waitcnt vmcnt(6)
; __device__ __forceinline__ float bflo(unsigned u) { return __uint_as_float(u << 16); }
; __device__ __forceinline__ float bfhi(unsigned u) { return __uint_as_float(u & 0xffff0000u); }
; __device__ __forceinline__ float sigm(float v) { return __builtin_amdgcn_rcpf(1.0f + __expf(-v)); }
; DI float bflo(unsigned u) { return __uint_as_float(u << 16); }
; DI float bfhi(unsigned u) { return __uint_as_float(u & 0xffff0000u); }
;     __device__ __forceinline__ void operator()(const f32x4 (&acc)[2][2][4][2], const Unit& u, int wr, int wc, int fr, int fq) const {
;     ...
;         for (int bj = 0; bj < 2; ++bj) {
;             const f32x4 b0 = *(const f32x4*)(gb + col0 + bj * HALF), b1 = *(const f32x4*)(gb + col0 + bj * HALF + 4);
; #pragma unroll
;             for (int ai = 0; ai < 2; ++ai)
; #pragma unroll
;                 for (int m = 0; m < 4; ++m) { const size_t row = (size_t)(row0 + ai * HALF + m * 16);
;                     const u32x4 g = *(const u32x4*)(gbase + row * 512 + gcol0 + bj * HALF);
;                     const f32x4 v0 = acc[ai][bj][m][0], v1 = acc[ai][bj][m][1];
;                     float r0 = v0[0] * sigm(bflo(g.x) + b0[0]), r1 = v0[1] * sigm(bfhi(g.x) + b0[1]), r2 = v0[2] * sigm(bflo(g.y) + b0[2]), r3 = v0[3] * sigm(bfhi(g.y) + b0[3]);
;                     float r4 = v1[0] * sigm(bflo(g.z) + b1[0]), r5 = v1[1] * sigm(bfhi(g.z) + b1[1]), r6 = v1[2] * sigm(bflo(g.w) + b1[2]), r7 = v1[3] * sigm(bfhi(g.w) + b1[3]);
	v_lshlrev_b32_e32 v240, 16, v204
	v_and_b32_e32 v241, 0xffff0000, v204
	v_lshlrev_b32_e32 v242, 16, v208
	v_and_b32_e32 v243, 0xffff0000, v208
	v_pk_add_f32 v[240:241], v[240:241], v[176:177]
	v_pk_add_f32 v[242:243], v[242:243], v[184:185]
	v_pk_mul_f32 v[240:241], v[240:241], v[246:247]
	v_pk_mul_f32 v[242:243], v[242:243], v[246:247]
	v_exp_f32_e32 v242, v242
	v_exp_f32_e32 v243, v243
	v_exp_f32_e32 v240, v240
	v_exp_f32_e32 v241, v241
	v_min_f32_e32 v242, v242, v248
	v_min_f32_e32 v243, v243, v248
	v_pk_add_f32 v[240:241], v[240:241], v[244:245]
	v_pk_add_f32 v[242:243], v[242:243], v[244:245]
	v_rcp_f32_e32 v240, v240
	v_rcp_f32_e32 v241, v241
	s_nop 0
	v_pk_mul_f32 v[242:243], v[242:243], v[240:241]
	v_pk_mul_f32 v[30:31], v[30:31], v[242:243]
	v_lshlrev_b32_e32 v240, 16, v205
	v_and_b32_e32 v241, 0xffff0000, v205
	v_lshlrev_b32_e32 v242, 16, v209
	v_and_b32_e32 v243, 0xffff0000, v209
	v_pk_add_f32 v[240:241], v[240:241], v[178:179]
	v_pk_add_f32 v[242:243], v[242:243], v[186:187]
	v_pk_mul_f32 v[240:241], v[240:241], v[246:247]
	v_pk_mul_f32 v[242:243], v[242:243], v[246:247]
	v_exp_f32_e32 v242, v242
	v_exp_f32_e32 v243, v243
	v_exp_f32_e32 v240, v240
	v_exp_f32_e32 v241, v241
	v_min_f32_e32 v242, v242, v248
	v_min_f32_e32 v243, v243, v248
	v_pk_add_f32 v[240:241], v[240:241], v[244:245]
	v_pk_add_f32 v[242:243], v[242:243], v[244:245]
	v_rcp_f32_e32 v240, v240
	v_rcp_f32_e32 v241, v241
	s_nop 0
	v_pk_mul_f32 v[242:243], v[242:243], v[240:241]
	v_pk_mul_f32 v[32:33], v[32:33], v[242:243]
	v_lshlrev_b32_e32 v240, 16, v206
	v_and_b32_e32 v241, 0xffff0000, v206
	v_lshlrev_b32_e32 v242, 16, v210
	v_and_b32_e32 v243, 0xffff0000, v210
	v_pk_add_f32 v[240:241], v[240:241], v[180:181]
	v_pk_add_f32 v[242:243], v[242:243], v[188:189]
	v_pk_mul_f32 v[240:241], v[240:241], v[246:247]
	v_pk_mul_f32 v[242:243], v[242:243], v[246:247]
	v_exp_f32_e32 v242, v242
	v_exp_f32_e32 v243, v243
	v_exp_f32_e32 v240, v240
	v_exp_f32_e32 v241, v241
	v_min_f32_e32 v242, v242, v248
	v_min_f32_e32 v243, v243, v248
	v_pk_add_f32 v[240:241], v[240:241], v[244:245]
	v_pk_add_f32 v[242:243], v[242:243], v[244:245]
	v_rcp_f32_e32 v240, v240
	v_rcp_f32_e32 v241, v241
	s_nop 0
	v_pk_mul_f32 v[242:243], v[242:243], v[240:241]
	v_pk_mul_f32 v[26:27], v[26:27], v[242:243]
	v_lshlrev_b32_e32 v240, 16, v207
	v_and_b32_e32 v241, 0xffff0000, v207
	v_lshlrev_b32_e32 v242, 16, v211
	v_and_b32_e32 v243, 0xffff0000, v211
	v_pk_add_f32 v[240:241], v[240:241], v[182:183]
	v_pk_add_f32 v[242:243], v[242:243], v[190:191]
	v_pk_mul_f32 v[240:241], v[240:241], v[246:247]
	v_pk_mul_f32 v[242:243], v[242:243], v[246:247]
	v_exp_f32_e32 v242, v242
	v_exp_f32_e32 v243, v243
	v_exp_f32_e32 v240, v240
	v_exp_f32_e32 v241, v241
	v_min_f32_e32 v242, v242, v248
	v_min_f32_e32 v243, v243, v248
	v_pk_add_f32 v[240:241], v[240:241], v[244:245]
	v_pk_add_f32 v[242:243], v[242:243], v[244:245]
	v_rcp_f32_e32 v240, v240
	v_rcp_f32_e32 v241, v241
	s_nop 0
	v_pk_mul_f32 v[242:243], v[242:243], v[240:241]
	v_pk_mul_f32 v[28:29], v[28:29], v[242:243]
	s_waitcnt vmcnt(4)
	v_lshlrev_b32_e32 v240, 16, v212
	v_and_b32_e32 v241, 0xffff0000, v212
	v_lshlrev_b32_e32 v242, 16, v216
	v_and_b32_e32 v243, 0xffff0000, v216
	v_pk_add_f32 v[240:241], v[240:241], v[176:177]
	v_pk_add_f32 v[242:243], v[242:243], v[184:185]
	v_pk_mul_f32 v[240:241], v[240:241], v[246:247]
	v_pk_mul_f32 v[242:243], v[242:243], v[246:247]
	v_exp_f32_e32 v242, v242
	v_exp_f32_e32 v243, v243
	v_exp_f32_e32 v240, v240
	v_exp_f32_e32 v241, v241
	v_min_f32_e32 v242, v242, v248
	v_min_f32_e32 v243, v243, v248
	v_pk_add_f32 v[240:241], v[240:241], v[244:245]
	v_pk_add_f32 v[242:243], v[242:243], v[244:245]
	v_rcp_f32_e32 v240, v240
	v_rcp_f32_e32 v241, v241
	s_nop 0
	v_pk_mul_f32 v[242:243], v[242:243], v[240:241]
	v_pk_mul_f32 v[22:23], v[22:23], v[242:243]
	v_lshlrev_b32_e32 v240, 16, v213
	v_and_b32_e32 v241, 0xffff0000, v213
	v_lshlrev_b32_e32 v242, 16, v217
	v_and_b32_e32 v243, 0xffff0000, v217
	v_pk_add_f32 v[240:241], v[240:241], v[178:179]
	v_pk_add_f32 v[242:243], v[242:243], v[186:187]
	v_pk_mul_f32 v[240:241], v[240:241], v[246:247]
	v_pk_mul_f32 v[242:243], v[242:243], v[246:247]
	v_exp_f32_e32 v242, v242
	v_exp_f32_e32 v243, v243
	v_exp_f32_e32 v240, v240
	v_exp_f32_e32 v241, v241
	v_min_f32_e32 v242, v242, v248
	v_min_f32_e32 v243, v243, v248
	v_pk_add_f32 v[240:241], v[240:241], v[244:245]
	v_pk_add_f32 v[242:243], v[242:243], v[244:245]
	v_rcp_f32_e32 v240, v240
	v_rcp_f32_e32 v241, v241
	s_nop 0
	v_pk_mul_f32 v[242:243], v[242:243], v[240:241]
	v_pk_mul_f32 v[24:25], v[24:25], v[242:243]
	v_lshlrev_b32_e32 v240, 16, v214
	v_and_b32_e32 v241, 0xffff0000, v214
	v_lshlrev_b32_e32 v242, 16, v218
	v_and_b32_e32 v243, 0xffff0000, v218
	v_pk_add_f32 v[240:241], v[240:241], v[180:181]
	v_pk_add_f32 v[242:243], v[242:243], v[188:189]
	v_pk_mul_f32 v[240:241], v[240:241], v[246:247]
	v_pk_mul_f32 v[242:243], v[242:243], v[246:247]
	v_exp_f32_e32 v242, v242
	v_exp_f32_e32 v243, v243
	v_exp_f32_e32 v240, v240
	v_exp_f32_e32 v241, v241
	v_min_f32_e32 v242, v242, v248
	v_min_f32_e32 v243, v243, v248
	v_pk_add_f32 v[240:241], v[240:241], v[244:245]
	v_pk_add_f32 v[242:243], v[242:243], v[244:245]
	v_rcp_f32_e32 v240, v240
	v_rcp_f32_e32 v241, v241
	s_nop 0
	v_pk_mul_f32 v[242:243], v[242:243], v[240:241]
	v_pk_mul_f32 v[18:19], v[18:19], v[242:243]
	v_lshlrev_b32_e32 v240, 16, v215
	v_and_b32_e32 v241, 0xffff0000, v215
	v_lshlrev_b32_e32 v242, 16, v219
	v_and_b32_e32 v243, 0xffff0000, v219
	v_pk_add_f32 v[240:241], v[240:241], v[182:183]
	v_pk_add_f32 v[242:243], v[242:243], v[190:191]
	v_pk_mul_f32 v[240:241], v[240:241], v[246:247]
	v_pk_mul_f32 v[242:243], v[242:243], v[246:247]
	v_exp_f32_e32 v242, v242
	v_exp_f32_e32 v243, v243
	v_exp_f32_e32 v240, v240
	v_exp_f32_e32 v241, v241
	v_min_f32_e32 v242, v242, v248
	v_min_f32_e32 v243, v243, v248
	v_pk_add_f32 v[240:241], v[240:241], v[244:245]
	v_pk_add_f32 v[242:243], v[242:243], v[244:245]
	v_rcp_f32_e32 v240, v240
	v_rcp_f32_e32 v241, v241
	s_nop 0
	v_pk_mul_f32 v[242:243], v[242:243], v[240:241]
	v_pk_mul_f32 v[20:21], v[20:21], v[242:243]
	s_waitcnt vmcnt(2)
; __device__ __forceinline__ float bflo(unsigned u) { return __uint_as_float(u << 16); }
; __device__ __forceinline__ float bfhi(unsigned u) { return __uint_as_float(u & 0xffff0000u); }
; __device__ __forceinline__ float sigm(float v) { return __builtin_amdgcn_rcpf(1.0f + __expf(-v)); }
; DI float bflo(unsigned u) { return __uint_as_float(u << 16); }
; DI float bfhi(unsigned u) { return __uint_as_float(u & 0xffff0000u); }
;     __device__ __forceinline__ void operator()(const f32x4 (&acc)[2][2][4][2], const Unit& u, int wr, int wc, int fr, int fq) const {
;     ...
;         for (int bj = 0; bj < 2; ++bj) {
;             const f32x4 b0 = *(const f32x4*)(gb + col0 + bj * HALF), b1 = *(const f32x4*)(gb + col0 + bj * HALF + 4);
; #pragma unroll
;             for (int ai = 0; ai < 2; ++ai)
; #pragma unroll
;                 for (int m = 0; m < 4; ++m) { const size_t row = (size_t)(row0 + ai * HALF + m * 16);
;                     const u32x4 g = *(const u32x4*)(gbase + row * 512 + gcol0 + bj * HALF);
;                     const f32x4 v0 = acc[ai][bj][m][0], v1 = acc[ai][bj][m][1];
;                     float r0 = v0[0] * sigm(bflo(g.x) + b0[0]), r1 = v0[1] * sigm(bfhi(g.x) + b0[1]), r2 = v0[2] * sigm(bflo(g.y) + b0[2]), r3 = v0[3] * sigm(bfhi(g.y) + b0[3]);
;                     float r4 = v1[0] * sigm(bflo(g.z) + b1[0]), r5 = v1[1] * sigm(bfhi(g.z) + b1[1]), r6 = v1[2] * sigm(bflo(g.w) + b1[2]), r7 = v1[3] * sigm(bfhi(g.w) + b1[3]);
; template <class Epi, class Sched, bool ALIGN_EPI = false, bool SP2 = false>
; __device__ __forceinline__ void gemm_phase(PG8_LAS unsigned char* lds, const Gemm g, const Sched& S, const Epi& E) {
;     ...
;         for (int a = 0; a < 2; ++a)
; #pragma unroll
;             for (int b = 0; b < 2; ++b)
; #pragma unroll
;                 for (int m = 0; m < 4; ++m)
; #pragma unroll
;                     for (int n = 0; n < 2; ++n) acc[a][b][m][n] = (f32x4){0.f, 0.f, 0.f, 0.f};
;         cur = nxt; cA = nA; cB = nB; ++ui;
	v_lshlrev_b32_e32 v240, 16, v220
	v_and_b32_e32 v241, 0xffff0000, v220
	v_lshlrev_b32_e32 v242, 16, v224
	v_and_b32_e32 v243, 0xffff0000, v224
	v_pk_add_f32 v[240:241], v[240:241], v[176:177]
	v_pk_add_f32 v[242:243], v[242:243], v[184:185]
	v_pk_mul_f32 v[240:241], v[240:241], v[246:247]
	v_pk_mul_f32 v[242:243], v[242:243], v[246:247]
	v_exp_f32_e32 v242, v242
	v_exp_f32_e32 v243, v243
	v_exp_f32_e32 v240, v240
	v_exp_f32_e32 v241, v241
	v_min_f32_e32 v242, v242, v248
	v_min_f32_e32 v243, v243, v248
	v_pk_add_f32 v[240:241], v[240:241], v[244:245]
	v_pk_add_f32 v[242:243], v[242:243], v[244:245]
	v_rcp_f32_e32 v240, v240
	v_rcp_f32_e32 v241, v241
	s_nop 0
	v_pk_mul_f32 v[242:243], v[242:243], v[240:241]
	v_pk_mul_f32 v[14:15], v[14:15], v[242:243]
	v_lshlrev_b32_e32 v240, 16, v221
	v_and_b32_e32 v241, 0xffff0000, v221
	v_lshlrev_b32_e32 v242, 16, v225
	v_and_b32_e32 v243, 0xffff0000, v225
	v_pk_add_f32 v[240:241], v[240:241], v[178:179]
	v_pk_add_f32 v[242:243], v[242:243], v[186:187]
	v_pk_mul_f32 v[240:241], v[240:241], v[246:247]
	v_pk_mul_f32 v[242:243], v[242:243], v[246:247]
	v_exp_f32_e32 v242, v242
	v_exp_f32_e32 v243, v243
	v_exp_f32_e32 v240, v240
	v_exp_f32_e32 v241, v241
	v_min_f32_e32 v242, v242, v248
	v_min_f32_e32 v243, v243, v248
	v_pk_add_f32 v[240:241], v[240:241], v[244:245]
	v_pk_add_f32 v[242:243], v[242:243], v[244:245]
	v_rcp_f32_e32 v240, v240
	v_rcp_f32_e32 v241, v241
	s_nop 0
	v_pk_mul_f32 v[242:243], v[242:243], v[240:241]
	v_pk_mul_f32 v[16:17], v[16:17], v[242:243]
	v_lshlrev_b32_e32 v240, 16, v222
	v_and_b32_e32 v241, 0xffff0000, v222
	v_lshlrev_b32_e32 v242, 16, v226
	v_and_b32_e32 v243, 0xffff0000, v226
	v_pk_add_f32 v[240:241], v[240:241], v[180:181]
	v_pk_add_f32 v[242:243], v[242:243], v[188:189]
	v_pk_mul_f32 v[240:241], v[240:241], v[246:247]
	v_pk_mul_f32 v[242:243], v[242:243], v[246:247]
	v_exp_f32_e32 v242, v242
	v_exp_f32_e32 v243, v243
	v_exp_f32_e32 v240, v240
	v_exp_f32_e32 v241, v241
	v_min_f32_e32 v242, v242, v248
	v_min_f32_e32 v243, v243, v248
	v_pk_add_f32 v[240:241], v[240:241], v[244:245]
	v_pk_add_f32 v[242:243], v[242:243], v[244:245]
	v_rcp_f32_e32 v240, v240
	v_rcp_f32_e32 v241, v241
	s_nop 0
	v_pk_mul_f32 v[242:243], v[242:243], v[240:241]
	v_pk_mul_f32 v[10:11], v[10:11], v[242:243]
	v_lshlrev_b32_e32 v240, 16, v223
	v_and_b32_e32 v241, 0xffff0000, v223
	v_lshlrev_b32_e32 v242, 16, v227
	v_and_b32_e32 v243, 0xffff0000, v227
	v_pk_add_f32 v[240:241], v[240:241], v[182:183]
	v_pk_add_f32 v[242:243], v[242:243], v[190:191]
	v_pk_mul_f32 v[240:241], v[240:241], v[246:247]
	v_pk_mul_f32 v[242:243], v[242:243], v[246:247]
	v_exp_f32_e32 v242, v242
	v_exp_f32_e32 v243, v243
	v_exp_f32_e32 v240, v240
	v_exp_f32_e32 v241, v241
	v_min_f32_e32 v242, v242, v248
	v_min_f32_e32 v243, v243, v248
	v_pk_add_f32 v[240:241], v[240:241], v[244:245]
	v_pk_add_f32 v[242:243], v[242:243], v[244:245]
	v_rcp_f32_e32 v240, v240
	v_rcp_f32_e32 v241, v241
	s_nop 0
	v_pk_mul_f32 v[242:243], v[242:243], v[240:241]
	v_pk_mul_f32 v[12:13], v[12:13], v[242:243]
	s_waitcnt vmcnt(0)
	v_lshlrev_b32_e32 v240, 16, v192
	v_and_b32_e32 v241, 0xffff0000, v192
	v_lshlrev_b32_e32 v242, 16, v166
	v_and_b32_e32 v243, 0xffff0000, v166
	v_pk_add_f32 v[240:241], v[240:241], v[176:177]
	v_pk_add_f32 v[242:243], v[242:243], v[184:185]
	v_pk_mul_f32 v[240:241], v[240:241], v[246:247]
	v_pk_mul_f32 v[242:243], v[242:243], v[246:247]
	v_exp_f32_e32 v242, v242
	v_exp_f32_e32 v243, v243
	v_exp_f32_e32 v240, v240
	v_exp_f32_e32 v241, v241
	v_min_f32_e32 v242, v242, v248
	v_min_f32_e32 v243, v243, v248
	v_pk_add_f32 v[240:241], v[240:241], v[244:245]
	v_pk_add_f32 v[242:243], v[242:243], v[244:245]
	v_rcp_f32_e32 v240, v240
	v_rcp_f32_e32 v241, v241
	s_nop 0
	v_pk_mul_f32 v[242:243], v[242:243], v[240:241]
	v_pk_mul_f32 v[6:7], v[6:7], v[242:243]
	v_lshlrev_b32_e32 v240, 16, v193
	v_and_b32_e32 v241, 0xffff0000, v193
	v_lshlrev_b32_e32 v242, 16, v167
	v_and_b32_e32 v243, 0xffff0000, v167
	v_pk_add_f32 v[240:241], v[240:241], v[178:179]
	v_pk_add_f32 v[242:243], v[242:243], v[186:187]
	v_pk_mul_f32 v[240:241], v[240:241], v[246:247]
	v_pk_mul_f32 v[242:243], v[242:243], v[246:247]
	v_exp_f32_e32 v242, v242
	v_exp_f32_e32 v243, v243
	v_exp_f32_e32 v240, v240
	v_exp_f32_e32 v241, v241
	v_min_f32_e32 v242, v242, v248
	v_min_f32_e32 v243, v243, v248
	v_pk_add_f32 v[240:241], v[240:241], v[244:245]
	v_pk_add_f32 v[242:243], v[242:243], v[244:245]
	v_rcp_f32_e32 v240, v240
	v_rcp_f32_e32 v241, v241
	s_nop 0
	v_pk_mul_f32 v[242:243], v[242:243], v[240:241]
	v_pk_mul_f32 v[8:9], v[8:9], v[242:243]
	v_lshlrev_b32_e32 v240, 16, v194
	v_and_b32_e32 v241, 0xffff0000, v194
	v_lshlrev_b32_e32 v242, 16, v168
	v_and_b32_e32 v243, 0xffff0000, v168
	v_pk_add_f32 v[240:241], v[240:241], v[180:181]
	v_pk_add_f32 v[242:243], v[242:243], v[188:189]
	v_pk_mul_f32 v[240:241], v[240:241], v[246:247]
	v_pk_mul_f32 v[242:243], v[242:243], v[246:247]
	v_exp_f32_e32 v242, v242
	v_exp_f32_e32 v243, v243
	v_exp_f32_e32 v240, v240
	v_exp_f32_e32 v241, v241
	v_min_f32_e32 v242, v242, v248
	v_min_f32_e32 v243, v243, v248
	v_pk_add_f32 v[240:241], v[240:241], v[244:245]
	v_pk_add_f32 v[242:243], v[242:243], v[244:245]
	v_rcp_f32_e32 v240, v240
	v_rcp_f32_e32 v241, v241
	s_nop 0
	v_pk_mul_f32 v[242:243], v[242:243], v[240:241]
	v_pk_mul_f32 v[2:3], v[2:3], v[242:243]
	v_lshlrev_b32_e32 v240, 16, v195
	v_and_b32_e32 v241, 0xffff0000, v195
	v_lshlrev_b32_e32 v242, 16, v169
	v_and_b32_e32 v243, 0xffff0000, v169
	v_pk_add_f32 v[240:241], v[240:241], v[182:183]
	v_pk_add_f32 v[242:243], v[242:243], v[190:191]
	v_pk_mul_f32 v[240:241], v[240:241], v[246:247]
	v_pk_mul_f32 v[242:243], v[242:243], v[246:247]
	v_exp_f32_e32 v242, v242
	v_exp_f32_e32 v243, v243
	v_exp_f32_e32 v240, v240
	v_exp_f32_e32 v241, v241
	v_min_f32_e32 v242, v242, v248
	v_min_f32_e32 v243, v243, v248
	v_pk_add_f32 v[240:241], v[240:241], v[244:245]
	v_pk_add_f32 v[242:243], v[242:243], v[244:245]
	v_rcp_f32_e32 v240, v240
	v_rcp_f32_e32 v241, v241
	s_nop 0
	v_pk_mul_f32 v[242:243], v[242:243], v[240:241]
	v_pk_mul_f32 v[4:5], v[4:5], v[242:243]
	v_mov_b32_e32 v240, v2
	v_mov_b32_e32 v241, v3
	v_mov_b32_e32 v242, v4
	v_mov_b32_e32 v243, v5
	v_mov_b32_e32 v244, v6
	v_mov_b32_e32 v245, v7
	v_mov_b32_e32 v246, v8
	v_mov_b32_e32 v247, v9
	v_mov_b32_e32 v248, v10
	v_mov_b32_e32 v249, v11
	v_mov_b32_e32 v250, v12
	v_mov_b32_e32 v251, v13
	v_mov_b32_e32 v252, v14
	v_mov_b32_e32 v253, v15
	v_mov_b32_e32 v254, v16
	s_branch .Lg1_exit

; #define PG8_STAGE(bufoff, gbase, voff) do { _Pragma("unroll") for (int _i = 0; _i < 2; ++_i) \
;         __builtin_amdgcn_global_load_lds((const unsigned*)((const char*)(gbase) + (voff)[_i]), (PG8_LAS unsigned*)(lds + (bufoff) + ldsw + _i * 8192), 16, 0, 0); } while (0)
; #define PG8_LDA(dst, b, h) do { _Pragma("unroll") for (int m = 0; m < 4; ++m) _Pragma("unroll") for (int k = 0; k < 2; ++k) dst[m][k] = *(const PG8_LAS bf16x8*)(lds + PG8_SA(b, h) + aoff + m * 2048 + k * 1024); } while (0)
; #define PG8_LDB(dst, b, h) do { _Pragma("unroll") for (int n = 0; n < 2; ++n) _Pragma("unroll") for (int k = 0; k < 2; ++k) dst[n][k] = *(const PG8_LAS bf16x8*)(lds + PG8_SB(b, h) + boff + n * 2048 + k * 1024); } while (0)
; #define PG8_WAIT_V(n) asm volatile("s_waitcnt vmcnt(" #n ")" ::: "memory")
; #define PG8_WAIT_L(n) asm volatile("s_waitcnt lgkmcnt(" #n ")" ::: "memory")
; #define PG8_BAR __builtin_amdgcn_s_barrier()
; #define PG8_SCHED __builtin_amdgcn_sched_barrier(0)
; template <class Epi, class Sched, bool ALIGN_EPI = false, bool SP2 = false>
; __device__ __forceinline__ void gemm_phase(PG8_LAS unsigned char* lds, const Gemm g, const Sched& S, const Epi& E) {
;     ...
; #pragma unroll
;     for (int a = 0; a < 2; ++a)
; #pragma unroll
;         for (int b = 0; b < 2; ++b)
; #pragma unroll
;             for (int m = 0; m < 4; ++m)
; #pragma unroll
;                 for (int n = 0; n < 2; ++n) acc[a][b][m][n] = (f32x4){0.f, 0.f, 0.f, 0.f};
;     ...
;         const bool has_next = S.next(ui + 1, nxt);
;         const char* nA = has_next ? (const char*)g.A + (size_t)nxt.pm * tstep : cA; const char* nB = has_next ? (const char*)g.Bt + (size_t)nxt.pn * tstep : cB;
;         for (int t = 0; t < nt; t += 2) {
;             const bool last = (t == nt - 2);
;             const char* a1 = cA + (size_t)(t + 1) * kstep;
;             const char* a2 = last ? nA : cA + (size_t)(t + 2) * kstep; const char* b2 = last ? nB : cB + (size_t)(t + 2) * kstep;
;             const char* a3 = a2 + kstep; const char* b3 = b2 + kstep;
;             if (last && has_next) S.a_ready(nxt);
;             if constexpr (SP2) {
;             PG8_LDB(B0, 0, 0); PG8_LDB(B1, 0, 1); PG8_SCHED; PG8_LDA(At, 0, 0); PG8_STAGE(PG8_SA(1, 1), a1 + hstep, voffA);
;             PG8_WAIT_V(8); PG8_WAIT_L(0); PG8_BAR; PG8_MMA(0, 0, At, B0); PG8_MMA(0, 1, At, B1); PG8_BAR; PG8_SCHED;
.LBB0_900:
	s_ashr_i32 s19, s18, 31
	s_lshl_b64 s[20:21], s[18:19], 18
	s_add_u32 s20, s8, s20
	s_addc_u32 s21, s9, s21
	s_and_b64 s[22:23], s[6:7], exec
	s_cselect_b32 s19, s21, s27
	s_cselect_b32 s49, s20, s26
	s_ashr_i32 s17, s16, 31
	s_lshl_b64 s[22:23], s[16:17], 18
	s_add_u32 s22, s33, s22
	s_addc_u32 s23, s34, s23
	s_and_b64 s[30:31], s[6:7], exec
	s_cselect_b32 s17, s23, s29
	s_cselect_b32 s50, s22, s28
	s_add_u32 s26, s26, 0x20080
	s_addc_u32 s27, s27, 0
	s_add_u32 s51, s28, 0x100
	v_mov_b32_e32 v2, 0
	s_addc_u32 s52, s29, 0
	s_mov_b32 s53, -2
	v_readlane_b32 s100, v239, 56
	s_nop 0
	s_cmpk_eq_i32 s100, 0x100
	s_cbranch_scc1 .Lg2_keep
	v_mov_b32_e32 v3, v2
	v_mov_b32_e32 v4, v2
	v_mov_b32_e32 v5, v2
	v_mov_b32_e32 v6, v2
	v_mov_b32_e32 v7, v2
	v_mov_b32_e32 v8, v2
	v_mov_b32_e32 v9, v2
	v_mov_b32_e32 v10, v2
	v_mov_b32_e32 v11, v2
	v_mov_b32_e32 v12, v2
	v_mov_b32_e32 v13, v2
	v_mov_b32_e32 v14, v2
	v_mov_b32_e32 v15, v2
	v_mov_b32_e32 v16, v2
	v_mov_b32_e32 v17, v2
	v_mov_b32_e32 v18, v2
	v_mov_b32_e32 v19, v2
	v_mov_b32_e32 v20, v2
	v_mov_b32_e32 v21, v2
	v_mov_b32_e32 v22, v2
	v_mov_b32_e32 v23, v2
	v_mov_b32_e32 v24, v2
	v_mov_b32_e32 v25, v2
	v_mov_b32_e32 v26, v2
	v_mov_b32_e32 v27, v2
	v_mov_b32_e32 v28, v2
	v_mov_b32_e32 v29, v2
	v_mov_b32_e32 v30, v2
	v_mov_b32_e32 v31, v2
	v_mov_b32_e32 v32, v2
	v_mov_b32_e32 v33, v2
	v_mov_b32_e32 v66, v2
	v_mov_b32_e32 v67, v2
	v_mov_b32_e32 v68, v2
	v_mov_b32_e32 v69, v2
	v_mov_b32_e32 v70, v2
	v_mov_b32_e32 v71, v2
	v_mov_b32_e32 v72, v2
	v_mov_b32_e32 v73, v2
	v_mov_b32_e32 v74, v2
	v_mov_b32_e32 v75, v2
	v_mov_b32_e32 v76, v2
	v_mov_b32_e32 v77, v2
	v_mov_b32_e32 v78, v2
	v_mov_b32_e32 v79, v2
	v_mov_b32_e32 v80, v2
	v_mov_b32_e32 v81, v2
	v_mov_b32_e32 v82, v2
	v_mov_b32_e32 v83, v2
	v_mov_b32_e32 v84, v2
	v_mov_b32_e32 v85, v2
	v_mov_b32_e32 v86, v2
	v_mov_b32_e32 v87, v2
	v_mov_b32_e32 v88, v2
	v_mov_b32_e32 v89, v2
	v_mov_b32_e32 v90, v2
	v_mov_b32_e32 v91, v2
	v_mov_b32_e32 v92, v2
	v_mov_b32_e32 v93, v2
	v_mov_b32_e32 v94, v2
	v_mov_b32_e32 v95, v2
	v_mov_b32_e32 v96, v2
	v_mov_b32_e32 v97, v2
	v_mov_b32_e32 v34, v2
	v_mov_b32_e32 v35, v2
	v_mov_b32_e32 v36, v2
	v_mov_b32_e32 v37, v2
	v_mov_b32_e32 v38, v2
	v_mov_b32_e32 v39, v2
	v_mov_b32_e32 v40, v2
	v_mov_b32_e32 v41, v2
	v_mov_b32_e32 v42, v2
	v_mov_b32_e32 v43, v2
	v_mov_b32_e32 v44, v2
	v_mov_b32_e32 v45, v2
	v_mov_b32_e32 v46, v2
	v_mov_b32_e32 v47, v2
	v_mov_b32_e32 v48, v2
	v_mov_b32_e32 v49, v2
	v_mov_b32_e32 v50, v2
	v_mov_b32_e32 v51, v2
	v_mov_b32_e32 v52, v2
	v_mov_b32_e32 v53, v2
	v_mov_b32_e32 v54, v2
	v_mov_b32_e32 v55, v2
	v_mov_b32_e32 v56, v2
	v_mov_b32_e32 v57, v2
	v_mov_b32_e32 v58, v2
	v_mov_b32_e32 v59, v2
	v_mov_b32_e32 v60, v2
	v_mov_b32_e32 v61, v2
	v_mov_b32_e32 v62, v2
	v_mov_b32_e32 v63, v2
	v_mov_b32_e32 v64, v2
	v_mov_b32_e32 v65, v2
	v_mov_b32_e32 v98, v2
	v_mov_b32_e32 v99, v2
	v_mov_b32_e32 v100, v2
	v_mov_b32_e32 v101, v2
	v_mov_b32_e32 v102, v2
	v_mov_b32_e32 v103, v2
	v_mov_b32_e32 v104, v2
	v_mov_b32_e32 v105, v2
	v_mov_b32_e32 v106, v2
	v_mov_b32_e32 v107, v2
	v_mov_b32_e32 v108, v2
	v_mov_b32_e32 v109, v2
	v_mov_b32_e32 v110, v2
	v_mov_b32_e32 v111, v2
	v_mov_b32_e32 v112, v2
	v_mov_b32_e32 v113, v2
	v_mov_b32_e32 v122, v2
	v_mov_b32_e32 v123, v2
	v_mov_b32_e32 v124, v2
	v_mov_b32_e32 v125, v2
	v_mov_b32_e32 v126, v2
	v_mov_b32_e32 v127, v2
	v_mov_b32_e32 v128, v2
	v_mov_b32_e32 v129, v2
	v_mov_b32_e32 v130, v2
	v_mov_b32_e32 v131, v2
	v_mov_b32_e32 v132, v2
	v_mov_b32_e32 v133, v2
	v_mov_b32_e32 v134, v2
	v_mov_b32_e32 v135, v2
	v_mov_b32_e32 v136, v2
	v_mov_b32_e32 v137, v2
	s_branch .Lg2_go
.Lg2_keep:
	v_mov_b32_e32 v2, v240
	v_mov_b32_e32 v3, v241
	v_mov_b32_e32 v4, v242
	v_mov_b32_e32 v5, v243
	v_mov_b32_e32 v6, v244
	v_mov_b32_e32 v7, v245
	v_mov_b32_e32 v8, v246
	v_mov_b32_e32 v9, v247
	v_mov_b32_e32 v10, v248
	v_mov_b32_e32 v11, v249
	v_mov_b32_e32 v12, v250
	v_mov_b32_e32 v13, v251
	v_mov_b32_e32 v14, v252
	v_mov_b32_e32 v15, v253
	v_mov_b32_e32 v16, v254
.Lg2_go:
.LBB0_901:
	ds_read_b128 v[114:117], v173
	ds_read_b128 v[118:121], v173 offset:1024
	ds_read_b128 v[154:157], v173 offset:2048
	ds_read_b128 v[158:161], v173 offset:3072
	ds_read_b128 v[166:169], v174
	ds_read_b128 v[176:179], v174 offset:1024
	ds_read_b128 v[180:183], v174 offset:2048
	ds_read_b128 v[184:187], v174 offset:3072
	s_add_u32 s2, s26, 0xfffe0080
	s_addc_u32 s28, s27, -1
	s_cmp_eq_u32 s53, 4
	s_cselect_b32 s31, s19, s28
	s_cselect_b32 s30, s49, s2
	s_cselect_b32 s29, s17, s52
	s_cselect_b32 s28, s50, s51
	v_lshl_add_u64 v[170:171], s[26:27], 0, v[146:147]
	s_add_i32 m0, s25, 0xc000
	ds_read_b128 v[188:191], v175
	ds_read_b128 v[192:195], v175 offset:1024
	ds_read_b128 v[204:207], v175 offset:2048
	ds_read_b128 v[208:211], v175 offset:3072
	ds_read_b128 v[212:215], v175 offset:4096
	ds_read_b128 v[216:219], v175 offset:5120
	ds_read_b128 v[220:223], v175 offset:6144
	ds_read_b128 v[224:227], v175 offset:7168
	global_load_lds_dwordx4 v[170:171], off
	v_lshl_add_u64 v[170:171], s[26:27], 0, v[148:149]
	s_add_i32 m0, s25, 0xe000
	s_nop 0
	global_load_lds_dwordx4 v[170:171], off
	s_waitcnt vmcnt(8)
	s_waitcnt lgkmcnt(0)
	s_barrier
; #define PG8_STAGE(bufoff, gbase, voff) do { _Pragma("unroll") for (int _i = 0; _i < 2; ++_i) \
;         __builtin_amdgcn_global_load_lds((const unsigned*)((const char*)(gbase) + (voff)[_i]), (PG8_LAS unsigned*)(lds + (bufoff) + ldsw + _i * 8192), 16, 0, 0); } while (0)
; #define PG8_LDA(dst, b, h) do { _Pragma("unroll") for (int m = 0; m < 4; ++m) _Pragma("unroll") for (int k = 0; k < 2; ++k) dst[m][k] = *(const PG8_LAS bf16x8*)(lds + PG8_SA(b, h) + aoff + m * 2048 + k * 1024); } while (0)
; #define PG8_LDB(dst, b, h) do { _Pragma("unroll") for (int n = 0; n < 2; ++n) _Pragma("unroll") for (int k = 0; k < 2; ++k) dst[n][k] = *(const PG8_LAS bf16x8*)(lds + PG8_SB(b, h) + boff + n * 2048 + k * 1024); } while (0)
; #define PG8_MMA(ai, bj, At, Bt) do { __builtin_amdgcn_s_setprio(1); _Pragma("unroll") for (int m = 0; m < 4; ++m) _Pragma("unroll") for (int n = 0; n < 2; ++n) _Pragma("unroll") for (int k = 0; k < 2; ++k) \
;         acc[ai][bj][m][n] = __builtin_amdgcn_mfma_f32_16x16x32_bf16(Bt[n][k], At[m][k], acc[ai][bj][m][n], 0, 0, 0); __builtin_amdgcn_s_setprio(0); } while (0)
; #define PG8_WAIT_V(n) asm volatile("s_waitcnt vmcnt(" #n ")" ::: "memory")
; #define PG8_WAIT_L(n) asm volatile("s_waitcnt lgkmcnt(" #n ")" ::: "memory")
; #define PG8_BAR __builtin_amdgcn_s_barrier()
; #define PG8_SCHED __builtin_amdgcn_sched_barrier(0)
; template <class Epi, class Sched, bool ALIGN_EPI = false, bool SP2 = false>
; __device__ __forceinline__ void gemm_phase(PG8_LAS unsigned char* lds, const Gemm g, const Sched& S, const Epi& E) {
;     ...
;             PG8_LDB(B0, 0, 0); PG8_LDB(B1, 0, 1); PG8_SCHED; PG8_LDA(At, 0, 0); PG8_STAGE(PG8_SA(1, 1), a1 + hstep, voffA);
;             PG8_WAIT_V(8); PG8_WAIT_L(0); PG8_BAR; PG8_MMA(0, 0, At, B0); PG8_MMA(0, 1, At, B1); PG8_BAR; PG8_SCHED;
;             PG8_LDA(At, 0, 1); PG8_STAGE(PG8_SB(0, 0), b2, voffB); PG8_STAGE(PG8_SB(0, 1), b2 + hstep, voffB); PG8_STAGE(PG8_SA(0, 0), a2, voffA);
;             PG8_WAIT_V(8); PG8_WAIT_L(0); PG8_BAR; PG8_MMA(1, 0, At, B0); PG8_MMA(1, 1, At, B1); PG8_BAR; PG8_SCHED;
	s_setprio 1
	s_waitcnt lgkmcnt(0)
	v_mfma_f32_16x16x32_bf16 v[134:137], v[114:117], v[188:191], v[134:137]
	v_mfma_f32_16x16x32_bf16 v[130:133], v[154:157], v[188:191], v[130:133]
	v_mfma_f32_16x16x32_bf16 v[126:129], v[114:117], v[204:207], v[126:129]
	v_mfma_f32_16x16x32_bf16 v[122:125], v[154:157], v[204:207], v[122:125]
	v_mfma_f32_16x16x32_bf16 v[110:113], v[114:117], v[212:215], v[110:113]
	v_mfma_f32_16x16x32_bf16 v[106:109], v[154:157], v[212:215], v[106:109]
	v_mfma_f32_16x16x32_bf16 v[102:105], v[114:117], v[220:223], v[102:105]
	v_mfma_f32_16x16x32_bf16 v[98:101], v[154:157], v[220:223], v[98:101]
	v_mfma_f32_16x16x32_bf16 v[134:137], v[118:121], v[192:195], v[134:137]
	v_mfma_f32_16x16x32_bf16 v[130:133], v[158:161], v[192:195], v[130:133]
	v_mfma_f32_16x16x32_bf16 v[126:129], v[118:121], v[208:211], v[126:129]
	v_mfma_f32_16x16x32_bf16 v[122:125], v[158:161], v[208:211], v[122:125]
	v_mfma_f32_16x16x32_bf16 v[110:113], v[118:121], v[216:219], v[110:113]
	v_mfma_f32_16x16x32_bf16 v[106:109], v[158:161], v[216:219], v[106:109]
	v_mfma_f32_16x16x32_bf16 v[102:105], v[118:121], v[224:227], v[102:105]
	v_mfma_f32_16x16x32_bf16 v[98:101], v[158:161], v[224:227], v[98:101]
	s_setprio 0
	s_setprio 1
	v_mfma_f32_16x16x32_bf16 v[62:65], v[166:169], v[188:191], v[62:65]
	v_mfma_f32_16x16x32_bf16 v[58:61], v[180:183], v[188:191], v[58:61]
	v_mfma_f32_16x16x32_bf16 v[54:57], v[166:169], v[204:207], v[54:57]
	v_mfma_f32_16x16x32_bf16 v[50:53], v[180:183], v[204:207], v[50:53]
	v_mfma_f32_16x16x32_bf16 v[46:49], v[166:169], v[212:215], v[46:49]
	v_mfma_f32_16x16x32_bf16 v[42:45], v[180:183], v[212:215], v[42:45]
	v_mfma_f32_16x16x32_bf16 v[38:41], v[166:169], v[220:223], v[38:41]
	v_mfma_f32_16x16x32_bf16 v[34:37], v[180:183], v[220:223], v[34:37]
	v_mfma_f32_16x16x32_bf16 v[62:65], v[176:179], v[192:195], v[62:65]
	v_mfma_f32_16x16x32_bf16 v[58:61], v[184:187], v[192:195], v[58:61]
	v_mfma_f32_16x16x32_bf16 v[54:57], v[176:179], v[208:211], v[54:57]
	v_mfma_f32_16x16x32_bf16 v[50:53], v[184:187], v[208:211], v[50:53]
	v_mfma_f32_16x16x32_bf16 v[46:49], v[176:179], v[216:219], v[46:49]
	v_mfma_f32_16x16x32_bf16 v[42:45], v[184:187], v[216:219], v[42:45]
	v_mfma_f32_16x16x32_bf16 v[38:41], v[176:179], v[224:227], v[38:41]
	v_mfma_f32_16x16x32_bf16 v[34:37], v[184:187], v[224:227], v[34:37]
	s_setprio 0
	s_barrier
	s_add_i32 s2, s46, s35
	v_lshl_add_u64 v[170:171], s[28:29], 0, v[140:141]
	s_mov_b32 m0, s2
	ds_read_b128 v[188:191], v175 offset:16384
	ds_read_b128 v[192:195], v175 offset:17408
	ds_read_b128 v[204:207], v175 offset:18432
	ds_read_b128 v[208:211], v175 offset:19456
	ds_read_b128 v[212:215], v175 offset:20480
	ds_read_b128 v[216:219], v175 offset:21504
	ds_read_b128 v[220:223], v175 offset:22528
	ds_read_b128 v[224:227], v175 offset:23552
	global_load_lds_dwordx4 v[170:171], off
	s_add_i32 m0, s2, 0x2000
	s_add_u32 s54, s28, 0x20000
	v_lshl_add_u64 v[228:229], s[28:29], 0, v[144:145]
	s_addc_u32 s55, s29, 0
	s_add_i32 s2, s47, s35
	global_load_lds_dwordx4 v[228:229], off
	v_lshl_add_u64 v[230:231], s[54:55], 0, v[140:141]
	s_mov_b32 m0, s2
	v_lshl_add_u64 v[232:233], s[30:31], 0, v[142:143]
	global_load_lds_dwordx4 v[230:231], off
	v_lshl_add_u64 v[230:231], s[54:55], 0, v[144:145]
	s_add_i32 m0, s2, 0x2000
	s_nop 0
	global_load_lds_dwordx4 v[230:231], off
	v_lshl_add_u64 v[230:231], s[30:31], 0, v[138:139]
	s_mov_b32 m0, s25
	s_nop 0
	global_load_lds_dwordx4 v[230:231], off
	s_mov_b32 m0, s36
	s_nop 0
	global_load_lds_dwordx4 v[232:233], off
	s_waitcnt vmcnt(8)
	s_waitcnt lgkmcnt(0)
	s_barrier
	s_setprio 1
	s_waitcnt lgkmcnt(0)
	v_mfma_f32_16x16x32_bf16 v[94:97], v[114:117], v[188:191], v[94:97]
	v_mfma_f32_16x16x32_bf16 v[90:93], v[154:157], v[188:191], v[90:93]
	v_mfma_f32_16x16x32_bf16 v[86:89], v[114:117], v[204:207], v[86:89]
	v_mfma_f32_16x16x32_bf16 v[82:85], v[154:157], v[204:207], v[82:85]
	v_mfma_f32_16x16x32_bf16 v[78:81], v[114:117], v[212:215], v[78:81]
	v_mfma_f32_16x16x32_bf16 v[74:77], v[154:157], v[212:215], v[74:77]
	v_mfma_f32_16x16x32_bf16 v[70:73], v[114:117], v[220:223], v[70:73]
	v_mfma_f32_16x16x32_bf16 v[66:69], v[154:157], v[220:223], v[66:69]
	v_mfma_f32_16x16x32_bf16 v[94:97], v[118:121], v[192:195], v[94:97]
	v_mfma_f32_16x16x32_bf16 v[90:93], v[158:161], v[192:195], v[90:93]
	v_mfma_f32_16x16x32_bf16 v[86:89], v[118:121], v[208:211], v[86:89]
	v_mfma_f32_16x16x32_bf16 v[82:85], v[158:161], v[208:211], v[82:85]
	v_mfma_f32_16x16x32_bf16 v[78:81], v[118:121], v[216:219], v[78:81]
	v_mfma_f32_16x16x32_bf16 v[74:77], v[158:161], v[216:219], v[74:77]
	v_mfma_f32_16x16x32_bf16 v[70:73], v[118:121], v[224:227], v[70:73]
	v_mfma_f32_16x16x32_bf16 v[66:69], v[158:161], v[224:227], v[66:69]
	s_setprio 0
	s_setprio 1
	v_mfma_f32_16x16x32_bf16 v[30:33], v[166:169], v[188:191], v[30:33]
	v_mfma_f32_16x16x32_bf16 v[26:29], v[180:183], v[188:191], v[26:29]
	v_mfma_f32_16x16x32_bf16 v[22:25], v[166:169], v[204:207], v[22:25]
	v_mfma_f32_16x16x32_bf16 v[18:21], v[180:183], v[204:207], v[18:21]
	v_mfma_f32_16x16x32_bf16 v[14:17], v[166:169], v[212:215], v[14:17]
	v_mfma_f32_16x16x32_bf16 v[10:13], v[180:183], v[212:215], v[10:13]
	v_mfma_f32_16x16x32_bf16 v[6:9], v[166:169], v[220:223], v[6:9]
	v_mfma_f32_16x16x32_bf16 v[2:5], v[180:183], v[220:223], v[2:5]
	v_mfma_f32_16x16x32_bf16 v[30:33], v[176:179], v[192:195], v[30:33]
	v_mfma_f32_16x16x32_bf16 v[26:29], v[184:187], v[192:195], v[26:29]
	v_mfma_f32_16x16x32_bf16 v[22:25], v[176:179], v[208:211], v[22:25]
	v_mfma_f32_16x16x32_bf16 v[18:21], v[184:187], v[208:211], v[18:21]
	v_mfma_f32_16x16x32_bf16 v[14:17], v[176:179], v[216:219], v[14:17]
	v_mfma_f32_16x16x32_bf16 v[10:13], v[184:187], v[216:219], v[10:13]
	v_mfma_f32_16x16x32_bf16 v[6:9], v[176:179], v[224:227], v[6:9]
	v_mfma_f32_16x16x32_bf16 v[2:5], v[184:187], v[224:227], v[2:5]
	s_setprio 0
	s_barrier
; #define PG8_STAGE(bufoff, gbase, voff) do { _Pragma("unroll") for (int _i = 0; _i < 2; ++_i) \
;         __builtin_amdgcn_global_load_lds((const unsigned*)((const char*)(gbase) + (voff)[_i]), (PG8_LAS unsigned*)(lds + (bufoff) + ldsw + _i * 8192), 16, 0, 0); } while (0)
; #define PG8_LDA(dst, b, h) do { _Pragma("unroll") for (int m = 0; m < 4; ++m) _Pragma("unroll") for (int k = 0; k < 2; ++k) dst[m][k] = *(const PG8_LAS bf16x8*)(lds + PG8_SA(b, h) + aoff + m * 2048 + k * 1024); } while (0)
; #define PG8_LDB(dst, b, h) do { _Pragma("unroll") for (int n = 0; n < 2; ++n) _Pragma("unroll") for (int k = 0; k < 2; ++k) dst[n][k] = *(const PG8_LAS bf16x8*)(lds + PG8_SB(b, h) + boff + n * 2048 + k * 1024); } while (0)
; #define PG8_MMA(ai, bj, At, Bt) do { __builtin_amdgcn_s_setprio(1); _Pragma("unroll") for (int m = 0; m < 4; ++m) _Pragma("unroll") for (int n = 0; n < 2; ++n) _Pragma("unroll") for (int k = 0; k < 2; ++k) \
;         acc[ai][bj][m][n] = __builtin_amdgcn_mfma_f32_16x16x32_bf16(Bt[n][k], At[m][k], acc[ai][bj][m][n], 0, 0, 0); __builtin_amdgcn_s_setprio(0); } while (0)
; #define PG8_WAIT_V(n) asm volatile("s_waitcnt vmcnt(" #n ")" ::: "memory")
; #define PG8_WAIT_L(n) asm volatile("s_waitcnt lgkmcnt(" #n ")" ::: "memory")
; #define PG8_BAR __builtin_amdgcn_s_barrier()
; #define PG8_SCHED __builtin_amdgcn_sched_barrier(0)
; template <class Epi, class Sched, bool ALIGN_EPI = false, bool SP2 = false>
; __device__ __forceinline__ void gemm_phase(PG8_LAS unsigned char* lds, const Gemm g, const Sched& S, const Epi& E) {
;     ...
;             PG8_LDA(At, 0, 1); PG8_STAGE(PG8_SB(0, 0), b2, voffB); PG8_STAGE(PG8_SB(0, 1), b2 + hstep, voffB); PG8_STAGE(PG8_SA(0, 0), a2, voffA);
;             PG8_WAIT_V(8); PG8_WAIT_L(0); PG8_BAR; PG8_MMA(1, 0, At, B0); PG8_MMA(1, 1, At, B1); PG8_BAR; PG8_SCHED;
;             PG8_LDB(B0, 1, 0); PG8_LDB(B1, 1, 1); PG8_SCHED; PG8_LDA(At, 1, 0); PG8_STAGE(PG8_SA(0, 1), a2 + hstep, voffA);
;             PG8_WAIT_V(8); PG8_WAIT_L(0); PG8_BAR; PG8_MMA(0, 0, At, B0); PG8_MMA(0, 1, At, B1); PG8_BAR; PG8_SCHED;
;             PG8_LDA(At, 1, 1); PG8_STAGE(PG8_SB(1, 0), b3, voffB); PG8_STAGE(PG8_SB(1, 1), b3 + hstep, voffB); PG8_STAGE(PG8_SA(1, 0), a3, voffA);
	s_add_i32 s2, 0, 0x18000
	s_add_i32 s54, 0, 0x1c000
	v_add_u32_e32 v158, s2, v165
	v_add_u32_e32 v184, s54, v165
	ds_read_b128 v[114:117], v158
	ds_read_b128 v[118:121], v158 offset:1024
	ds_read_b128 v[154:157], v158 offset:2048
	ds_read_b128 v[158:161], v158 offset:3072
	ds_read_b128 v[166:169], v184
	ds_read_b128 v[176:179], v184 offset:1024
	ds_read_b128 v[180:183], v184 offset:2048
	ds_read_b128 v[184:187], v184 offset:3072
	s_add_u32 s30, s30, 0x20000
	s_addc_u32 s31, s31, 0
	s_mov_b32 m0, s37
	v_lshl_add_u64 v[234:235], s[30:31], 0, v[138:139]
	ds_read_b128 v[188:191], v175 offset:32768
	ds_read_b128 v[192:195], v175 offset:33792
	ds_read_b128 v[204:207], v175 offset:34816
	ds_read_b128 v[208:211], v175 offset:35840
	ds_read_b128 v[212:215], v175 offset:36864
	ds_read_b128 v[216:219], v175 offset:37888
	ds_read_b128 v[220:223], v175 offset:38912
	ds_read_b128 v[224:227], v175 offset:39936
	global_load_lds_dwordx4 v[234:235], off
	v_lshl_add_u64 v[234:235], s[30:31], 0, v[142:143]
	s_mov_b32 m0, s38
	s_nop 0
	global_load_lds_dwordx4 v[234:235], off
	s_waitcnt vmcnt(8)
	s_waitcnt lgkmcnt(0)
	s_barrier
	s_setprio 1
	s_waitcnt lgkmcnt(0)
	v_mfma_f32_16x16x32_bf16 v[134:137], v[114:117], v[188:191], v[134:137]
	v_mfma_f32_16x16x32_bf16 v[130:133], v[154:157], v[188:191], v[130:133]
	v_mfma_f32_16x16x32_bf16 v[126:129], v[114:117], v[204:207], v[126:129]
	v_mfma_f32_16x16x32_bf16 v[122:125], v[154:157], v[204:207], v[122:125]
	v_mfma_f32_16x16x32_bf16 v[110:113], v[114:117], v[212:215], v[110:113]
	v_mfma_f32_16x16x32_bf16 v[106:109], v[154:157], v[212:215], v[106:109]
	v_mfma_f32_16x16x32_bf16 v[102:105], v[114:117], v[220:223], v[102:105]
	v_mfma_f32_16x16x32_bf16 v[98:101], v[154:157], v[220:223], v[98:101]
	v_mfma_f32_16x16x32_bf16 v[134:137], v[118:121], v[192:195], v[134:137]
	v_mfma_f32_16x16x32_bf16 v[130:133], v[158:161], v[192:195], v[130:133]
	v_mfma_f32_16x16x32_bf16 v[126:129], v[118:121], v[208:211], v[126:129]
	v_mfma_f32_16x16x32_bf16 v[122:125], v[158:161], v[208:211], v[122:125]
	v_mfma_f32_16x16x32_bf16 v[110:113], v[118:121], v[216:219], v[110:113]
	v_mfma_f32_16x16x32_bf16 v[106:109], v[158:161], v[216:219], v[106:109]
	v_mfma_f32_16x16x32_bf16 v[102:105], v[118:121], v[224:227], v[102:105]
	v_mfma_f32_16x16x32_bf16 v[98:101], v[158:161], v[224:227], v[98:101]
	s_setprio 0
	s_setprio 1
	v_mfma_f32_16x16x32_bf16 v[62:65], v[166:169], v[188:191], v[62:65]
	v_mfma_f32_16x16x32_bf16 v[58:61], v[180:183], v[188:191], v[58:61]
	v_mfma_f32_16x16x32_bf16 v[54:57], v[166:169], v[204:207], v[54:57]
	v_mfma_f32_16x16x32_bf16 v[50:53], v[180:183], v[204:207], v[50:53]
	v_mfma_f32_16x16x32_bf16 v[46:49], v[166:169], v[212:215], v[46:49]
	v_mfma_f32_16x16x32_bf16 v[42:45], v[180:183], v[212:215], v[42:45]
	v_mfma_f32_16x16x32_bf16 v[38:41], v[166:169], v[220:223], v[38:41]
	v_mfma_f32_16x16x32_bf16 v[34:37], v[180:183], v[220:223], v[34:37]
	v_mfma_f32_16x16x32_bf16 v[62:65], v[176:179], v[192:195], v[62:65]
	v_mfma_f32_16x16x32_bf16 v[58:61], v[184:187], v[192:195], v[58:61]
	v_mfma_f32_16x16x32_bf16 v[54:57], v[176:179], v[208:211], v[54:57]
	v_mfma_f32_16x16x32_bf16 v[50:53], v[184:187], v[208:211], v[50:53]
	v_mfma_f32_16x16x32_bf16 v[46:49], v[176:179], v[216:219], v[46:49]
	v_mfma_f32_16x16x32_bf16 v[42:45], v[184:187], v[216:219], v[42:45]
	v_mfma_f32_16x16x32_bf16 v[38:41], v[176:179], v[224:227], v[38:41]
	v_mfma_f32_16x16x32_bf16 v[34:37], v[184:187], v[224:227], v[34:37]
	s_setprio 0
	s_barrier
	s_add_i32 s2, s2, s35
	v_lshl_add_u64 v[170:171], v[170:171], 0, s[12:13]
	s_mov_b32 m0, s2
	ds_read_b128 v[188:191], v175 offset:49152
	ds_read_b128 v[192:195], v175 offset:50176
	ds_read_b128 v[204:207], v175 offset:51200
	ds_read_b128 v[208:211], v175 offset:52224
	ds_read_b128 v[212:215], v175 offset:53248
	ds_read_b128 v[216:219], v175 offset:54272
	ds_read_b128 v[220:223], v175 offset:55296
	ds_read_b128 v[224:227], v175 offset:56320
	global_load_lds_dwordx4 v[170:171], off
	s_add_i32 m0, s2, 0x2000
	s_add_u32 s28, s28, 0x20080
	v_lshl_add_u64 v[170:171], v[228:229], 0, s[12:13]
	s_addc_u32 s29, s29, 0
	s_add_i32 s2, s54, s35
	global_load_lds_dwordx4 v[170:171], off
	v_lshl_add_u64 v[170:171], s[28:29], 0, v[140:141]
	s_mov_b32 m0, s2
	s_nop 0
	global_load_lds_dwordx4 v[170:171], off
	v_lshl_add_u64 v[170:171], s[28:29], 0, v[144:145]
	s_add_i32 m0, s2, 0x2000
	s_nop 0
	global_load_lds_dwordx4 v[170:171], off
	v_lshl_add_u64 v[170:171], v[230:231], 0, s[12:13]
	s_mov_b32 m0, s42
	s_nop 0
	global_load_lds_dwordx4 v[170:171], off
	v_lshl_add_u64 v[170:171], v[232:233], 0, s[12:13]
	s_mov_b32 m0, s43
	s_nop 0
	global_load_lds_dwordx4 v[170:171], off
	s_waitcnt vmcnt(8)
	s_waitcnt lgkmcnt(0)
	s_barrier
; #define PG8_STAGE(bufoff, gbase, voff) do { _Pragma("unroll") for (int _i = 0; _i < 2; ++_i) \
;         __builtin_amdgcn_global_load_lds((const unsigned*)((const char*)(gbase) + (voff)[_i]), (PG8_LAS unsigned*)(lds + (bufoff) + ldsw + _i * 8192), 16, 0, 0); } while (0)
; #define PG8_LDA(dst, b, h) do { _Pragma("unroll") for (int m = 0; m < 4; ++m) _Pragma("unroll") for (int k = 0; k < 2; ++k) dst[m][k] = *(const PG8_LAS bf16x8*)(lds + PG8_SA(b, h) + aoff + m * 2048 + k * 1024); } while (0)
; #define PG8_MMA(ai, bj, At, Bt) do { __builtin_amdgcn_s_setprio(1); _Pragma("unroll") for (int m = 0; m < 4; ++m) _Pragma("unroll") for (int n = 0; n < 2; ++n) _Pragma("unroll") for (int k = 0; k < 2; ++k) \
;         acc[ai][bj][m][n] = __builtin_amdgcn_mfma_f32_16x16x32_bf16(Bt[n][k], At[m][k], acc[ai][bj][m][n], 0, 0, 0); __builtin_amdgcn_s_setprio(0); } while (0)
; #define PG8_WAIT_V(n) asm volatile("s_waitcnt vmcnt(" #n ")" ::: "memory")
; #define PG8_WAIT_L(n) asm volatile("s_waitcnt lgkmcnt(" #n ")" ::: "memory")
; #define PG8_BAR __builtin_amdgcn_s_barrier()
; #define PG8_SCHED __builtin_amdgcn_sched_barrier(0)
; template <class Epi, class Sched, bool ALIGN_EPI = false, bool SP2 = false>
; __device__ __forceinline__ void gemm_phase(PG8_LAS unsigned char* lds, const Gemm g, const Sched& S, const Epi& E) {
;     ...
;             PG8_WAIT_V(8); PG8_WAIT_L(0); PG8_BAR; PG8_MMA(0, 0, At, B0); PG8_MMA(0, 1, At, B1); PG8_BAR; PG8_SCHED;
;             PG8_LDA(At, 1, 1); PG8_STAGE(PG8_SB(1, 0), b3, voffB); PG8_STAGE(PG8_SB(1, 1), b3 + hstep, voffB); PG8_STAGE(PG8_SA(1, 0), a3, voffA);
;             PG8_WAIT_V(8); PG8_WAIT_L(0); PG8_BAR; PG8_MMA(1, 0, At, B0); PG8_MMA(1, 1, At, B1); PG8_BAR; PG8_SCHED;
;     ...
;         if constexpr (ALIGN_EPI) { if (wr == 0) PG8_BAR; }
;         if constexpr (!Epi::AFTER_DRAIN) { E(acc, cur, wr, wc, fr, fq); S.done(cur); }
	s_setprio 1
	s_waitcnt lgkmcnt(0)
	v_mfma_f32_16x16x32_bf16 v[94:97], v[114:117], v[188:191], v[94:97]
	v_mfma_f32_16x16x32_bf16 v[90:93], v[154:157], v[188:191], v[90:93]
	v_mfma_f32_16x16x32_bf16 v[86:89], v[114:117], v[204:207], v[86:89]
	v_mfma_f32_16x16x32_bf16 v[82:85], v[154:157], v[204:207], v[82:85]
	v_mfma_f32_16x16x32_bf16 v[78:81], v[114:117], v[212:215], v[78:81]
	v_mfma_f32_16x16x32_bf16 v[74:77], v[154:157], v[212:215], v[74:77]
	v_mfma_f32_16x16x32_bf16 v[70:73], v[114:117], v[220:223], v[70:73]
	v_mfma_f32_16x16x32_bf16 v[66:69], v[154:157], v[220:223], v[66:69]
	v_mfma_f32_16x16x32_bf16 v[94:97], v[118:121], v[192:195], v[94:97]
	v_mfma_f32_16x16x32_bf16 v[90:93], v[158:161], v[192:195], v[90:93]
	v_mfma_f32_16x16x32_bf16 v[86:89], v[118:121], v[208:211], v[86:89]
	v_mfma_f32_16x16x32_bf16 v[82:85], v[158:161], v[208:211], v[82:85]
	v_mfma_f32_16x16x32_bf16 v[78:81], v[118:121], v[216:219], v[78:81]
	v_mfma_f32_16x16x32_bf16 v[74:77], v[158:161], v[216:219], v[74:77]
	v_mfma_f32_16x16x32_bf16 v[70:73], v[118:121], v[224:227], v[70:73]
	v_mfma_f32_16x16x32_bf16 v[66:69], v[158:161], v[224:227], v[66:69]
	s_setprio 0
	s_setprio 1
	v_mfma_f32_16x16x32_bf16 v[30:33], v[166:169], v[188:191], v[30:33]
	v_mfma_f32_16x16x32_bf16 v[26:29], v[180:183], v[188:191], v[26:29]
	v_mfma_f32_16x16x32_bf16 v[22:25], v[166:169], v[204:207], v[22:25]
	v_mfma_f32_16x16x32_bf16 v[18:21], v[180:183], v[204:207], v[18:21]
	v_mfma_f32_16x16x32_bf16 v[14:17], v[166:169], v[212:215], v[14:17]
	v_mfma_f32_16x16x32_bf16 v[10:13], v[180:183], v[212:215], v[10:13]
	v_mfma_f32_16x16x32_bf16 v[6:9], v[166:169], v[220:223], v[6:9]
	v_mfma_f32_16x16x32_bf16 v[2:5], v[180:183], v[220:223], v[2:5]
	v_mfma_f32_16x16x32_bf16 v[30:33], v[176:179], v[192:195], v[30:33]
	v_mfma_f32_16x16x32_bf16 v[26:29], v[184:187], v[192:195], v[26:29]
	v_mfma_f32_16x16x32_bf16 v[22:25], v[176:179], v[208:211], v[22:25]
	v_mfma_f32_16x16x32_bf16 v[18:21], v[184:187], v[208:211], v[18:21]
	v_mfma_f32_16x16x32_bf16 v[14:17], v[176:179], v[216:219], v[14:17]
	v_mfma_f32_16x16x32_bf16 v[10:13], v[184:187], v[216:219], v[10:13]
	v_mfma_f32_16x16x32_bf16 v[6:9], v[176:179], v[224:227], v[6:9]
	v_mfma_f32_16x16x32_bf16 v[2:5], v[184:187], v[224:227], v[2:5]
	s_setprio 0
	s_barrier
	s_add_i32 s53, s53, 2
	s_add_u32 s26, s26, 0x100
	s_addc_u32 s27, s27, 0
	s_add_u32 s51, s51, 0x100
	s_addc_u32 s52, s52, 0
	s_cmp_gt_u32 s53, 5
	s_cbranch_scc0 .LBB0_901
	s_and_b64 vcc, exec, s[14:15]
	s_cbranch_vccz .LBB0_904
	s_barrier
.LBB0_904:
	v_readlane_b32 s100, v239, 56
	s_nop 0
	s_cmpk_eq_i32 s100, 0x100
	s_cbranch_scc1 .Lg2n_start
	s_lshr_b32 s2, s48, 31
	s_add_i32 s2, s48, s2
	s_ashr_i32 s26, s2, 1
	s_ashr_i32 s27, s26, 31
	s_lshl_b64 s[28:29], s[26:27], 24
	s_add_u32 s28, s40, s28
	s_addc_u32 s29, s41, s29
	v_lshl_or_b32 v114, s48, 8, v172
	s_lshl_b32 s2, s26, 9
	v_lshl_add_u32 v168, s24, 8, v1
	v_subrev_u32_e32 v116, s2, v114
	v_ashrrev_i32_e32 v117, 31, v116
	v_ashrrev_i32_e32 v169, 31, v168
	v_lshl_add_u64 v[170:171], v[116:117], 1, s[28:29]
	v_lshlrev_b64 v[116:117], 10, v[168:169]
	v_lshl_add_u64 v[158:159], v[170:171], 0, v[116:117]
	v_ashrrev_i32_e32 v115, 31, v114
	v_lshlrev_b64 v[116:117], 11, v[168:169]
	v_lshl_add_u64 v[116:117], s[10:11], 0, v[116:117]
	v_lshlrev_b64 v[166:167], 1, v[114:115]
	global_load_dwordx4 v[176:179], v[158:159], off
	v_lshl_add_u64 v[154:155], v[116:117], 0, v[166:167]
	v_lshl_add_u64 v[160:161], v[114:115], 2, s[4:5]
	global_load_dwordx4 v[180:183], v[154:155], off
	global_load_dwordx4 v[118:121], v[160:161], off
	global_load_dwordx4 v[114:117], v[160:161], off offset:16
	v_or_b32_e32 v184, 16, v168
	v_ashrrev_i32_e32 v185, 31, v184
	v_lshlrev_b64 v[156:157], 10, v[184:185]
	v_lshl_add_u64 v[156:157], v[170:171], 0, v[156:157]
	s_andn2_b64 vcc, exec, s[6:7]
	s_mov_b64 s[6:7], -1
	v_mov_b32_e32 v250, v158
	v_mov_b32_e32 v251, v159
	v_mov_b32_e32 v252, v154
	v_mov_b32_e32 v253, v155
	s_mov_b64 s[98:99], 0x4000
	v_lshl_add_u64 v[248:249], v[250:251], 0, s[98:99]
	global_load_dwordx4 v[204:207], v[248:249], off
	s_mov_b64 s[98:99], 0x8000
	v_lshl_add_u64 v[248:249], v[252:253], 0, s[98:99]
	global_load_dwordx4 v[216:219], v[248:249], off
	s_mov_b64 s[98:99], 0x8000
	v_lshl_add_u64 v[248:249], v[250:251], 0, s[98:99]
	global_load_dwordx4 v[208:211], v[248:249], off
	s_mov_b64 s[98:99], 0x10000
	v_lshl_add_u64 v[248:249], v[252:253], 0, s[98:99]
	global_load_dwordx4 v[220:223], v[248:249], off
	s_mov_b64 s[98:99], 0xc000
	v_lshl_add_u64 v[248:249], v[250:251], 0, s[98:99]
	global_load_dwordx4 v[212:215], v[248:249], off
	s_mov_b64 s[98:99], 0x18000
	v_lshl_add_u64 v[248:249], v[252:253], 0, s[98:99]
	global_load_dwordx4 v[224:227], v[248:249], off
	global_load_dwordx4 v[240:243], v[160:161], off offset:512
	global_load_dwordx4 v[244:247], v[160:161], off offset:528
	s_waitcnt vmcnt(8)
; __device__ __forceinline__ unsigned cvt_pk_bf16(float lo, float hi) { unsigned r; asm volatile("v_cvt_pk_bf16_f32 %0, %1, %2" : "=v"(r) : "v"(lo), "v"(hi)); return r; }
; __device__ __forceinline__ float bflo(unsigned u) { return __uint_as_float(u << 16); }
; __device__ __forceinline__ float bfhi(unsigned u) { return __uint_as_float(u & 0xffff0000u); }
; __device__ __forceinline__ float sigm(float v) { return __builtin_amdgcn_rcpf(1.0f + __expf(-v)); }
; DI float bflo(unsigned u) { return __uint_as_float(u << 16); }
; DI float bfhi(unsigned u) { return __uint_as_float(u & 0xffff0000u); }
;     __device__ __forceinline__ void operator()(const f32x4 (&acc)[2][2][4][2], const Unit& u, int wr, int wc, int fr, int fq) const {
;     ...
;         for (int bj = 0; bj < 2; ++bj) {
;             const f32x4 b0 = *(const f32x4*)(gb + col0 + bj * HALF), b1 = *(const f32x4*)(gb + col0 + bj * HALF + 4);
; #pragma unroll
;             for (int ai = 0; ai < 2; ++ai)
; #pragma unroll
;                 for (int m = 0; m < 4; ++m) { const size_t row = (size_t)(row0 + ai * HALF + m * 16);
;                     const u32x4 g = *(const u32x4*)(gbase + row * 512 + gcol0 + bj * HALF);
;                     const f32x4 v0 = acc[ai][bj][m][0], v1 = acc[ai][bj][m][1];
;                     float r0 = v0[0] * sigm(bflo(g.x) + b0[0]), r1 = v0[1] * sigm(bfhi(g.x) + b0[1]), r2 = v0[2] * sigm(bflo(g.y) + b0[2]), r3 = v0[3] * sigm(bfhi(g.y) + b0[3]);
;                     float r4 = v1[0] * sigm(bflo(g.z) + b1[0]), r5 = v1[1] * sigm(bfhi(g.z) + b1[1]), r6 = v1[2] * sigm(bflo(g.w) + b1[2]), r7 = v1[3] * sigm(bfhi(g.w) + b1[3]);
;                     bf16_t* op = Mo + row * 1024 + col0 + bj * HALF;
;                     if (accum) { const u32x4 p = *(const u32x4*)op; r0 += bflo(p.x); r1 += bfhi(p.x); r2 += bflo(p.y); r3 += bfhi(p.y); r4 += bflo(p.z); r5 += bfhi(p.z); r6 += bflo(p.w); r7 += bfhi(p.w); }
;                     u32x4 w; w.x = cvt_pk_bf16(r0, r1); w.y = cvt_pk_bf16(r2, r3); w.z = cvt_pk_bf16(r4, r5); w.w = cvt_pk_bf16(r6, r7);
;                     *(u32x4*)op = w; }
	v_lshlrev_b32_e32 v169, 16, v176
	v_and_b32_e32 v176, 0xffff0000, v176
	v_lshlrev_b32_e32 v186, 16, v177
	v_and_b32_e32 v177, 0xffff0000, v177
	v_lshlrev_b32_e32 v187, 16, v178
	v_and_b32_e32 v178, 0xffff0000, v178
	v_lshlrev_b32_e32 v188, 16, v179
	v_and_b32_e32 v179, 0xffff0000, v179
	v_add_f32_e32 v169, v118, v169
	v_add_f32_e32 v176, v119, v176
	v_add_f32_e32 v186, v120, v186
	v_add_f32_e32 v177, v121, v177
	v_add_f32_e32 v187, v114, v187
	v_add_f32_e32 v178, v115, v178
	v_add_f32_e32 v188, v116, v188
	v_add_f32_e32 v179, v117, v179
	v_mul_f32_e32 v169, 0xbfb8aa3b, v169
	v_mul_f32_e32 v176, 0xbfb8aa3b, v176
	v_mul_f32_e32 v186, 0xbfb8aa3b, v186
	v_mul_f32_e32 v177, 0xbfb8aa3b, v177
	v_mul_f32_e32 v187, 0xbfb8aa3b, v187
	v_mul_f32_e32 v178, 0xbfb8aa3b, v178
	v_mul_f32_e32 v188, 0xbfb8aa3b, v188
	v_mul_f32_e32 v179, 0xbfb8aa3b, v179
	v_exp_f32_e32 v169, v169
	v_exp_f32_e32 v176, v176
	v_exp_f32_e32 v186, v186
	v_exp_f32_e32 v177, v177
	v_exp_f32_e32 v187, v187
	v_exp_f32_e32 v178, v178
	v_exp_f32_e32 v188, v188
	v_exp_f32_e32 v179, v179
	v_add_f32_e32 v169, 1.0, v169
	v_add_f32_e32 v176, 1.0, v176
	v_add_f32_e32 v186, 1.0, v186
	v_add_f32_e32 v177, 1.0, v177
	v_add_f32_e32 v187, 1.0, v187
	v_add_f32_e32 v178, 1.0, v178
	v_add_f32_e32 v188, 1.0, v188
	v_add_f32_e32 v179, 1.0, v179
	v_rcp_f32_e32 v169, v169
	v_rcp_f32_e32 v176, v176
	v_rcp_f32_e32 v186, v186
	v_rcp_f32_e32 v177, v177
	v_rcp_f32_e32 v187, v187
	v_rcp_f32_e32 v178, v178
	v_rcp_f32_e32 v188, v188
	v_rcp_f32_e32 v179, v179
	v_lshlrev_b32_e32 v189, 16, v180
	v_and_b32_e32 v180, 0xffff0000, v180
	v_lshlrev_b32_e32 v190, 16, v181
	v_and_b32_e32 v181, 0xffff0000, v181
	v_lshlrev_b32_e32 v191, 16, v182
	v_and_b32_e32 v182, 0xffff0000, v182
	v_lshlrev_b32_e32 v192, 16, v183
	v_and_b32_e32 v183, 0xffff0000, v183
	v_fmac_f32_e32 v189, v134, v169
	v_fmac_f32_e32 v180, v135, v176
	v_fmac_f32_e32 v190, v136, v186
	v_fmac_f32_e32 v181, v137, v177
	v_fmac_f32_e32 v191, v130, v187
	v_fmac_f32_e32 v182, v131, v178
	v_fmac_f32_e32 v192, v132, v188
	v_fmac_f32_e32 v183, v133, v179
	v_cvt_pk_bf16_f32 v130, v189, v180
	v_cvt_pk_bf16_f32 v131, v190, v181
	v_cvt_pk_bf16_f32 v132, v191, v182
	v_cvt_pk_bf16_f32 v133, v192, v183
	global_store_dwordx4 v[154:155], v[130:133], off
	s_nop 0
	v_or_b32_e32 v180, 32, v168
	v_lshlrev_b64 v[130:131], 11, v[184:185]
	v_lshl_add_u64 v[130:131], s[10:11], 0, v[130:131]
	v_lshl_add_u64 v[130:131], v[130:131], 0, v[166:167]
	s_nop 0
	v_ashrrev_i32_e32 v181, 31, v180
	v_lshlrev_b64 v[132:133], 10, v[180:181]
	v_lshl_add_u64 v[132:133], v[170:171], 0, v[132:133]
	s_waitcnt vmcnt(8)
	v_lshlrev_b32_e32 v169, 16, v204
	v_and_b32_e32 v134, 0xffff0000, v204
	v_lshlrev_b32_e32 v182, 16, v205
	v_and_b32_e32 v135, 0xffff0000, v205
	v_lshlrev_b32_e32 v183, 16, v206
	v_and_b32_e32 v136, 0xffff0000, v206
	v_lshlrev_b32_e32 v184, 16, v207
	v_and_b32_e32 v137, 0xffff0000, v207
	s_mov_b64 s[98:99], 0x20000
	v_lshl_add_u64 v[248:249], v[250:251], 0, s[98:99]
	global_load_dwordx4 v[204:207], v[248:249], off
	v_add_f32_e32 v169, v118, v169
	v_add_f32_e32 v134, v119, v134
	v_add_f32_e32 v182, v120, v182
	v_add_f32_e32 v135, v121, v135
	v_add_f32_e32 v183, v114, v183
	v_add_f32_e32 v136, v115, v136
	v_add_f32_e32 v184, v116, v184
	v_add_f32_e32 v137, v117, v137
	v_mul_f32_e32 v169, 0xbfb8aa3b, v169
	v_mul_f32_e32 v134, 0xbfb8aa3b, v134
	v_mul_f32_e32 v182, 0xbfb8aa3b, v182
	v_mul_f32_e32 v135, 0xbfb8aa3b, v135
	v_mul_f32_e32 v183, 0xbfb8aa3b, v183
	v_mul_f32_e32 v136, 0xbfb8aa3b, v136
	v_mul_f32_e32 v184, 0xbfb8aa3b, v184
	v_mul_f32_e32 v137, 0xbfb8aa3b, v137
	v_exp_f32_e32 v169, v169
	v_exp_f32_e32 v134, v134
	v_exp_f32_e32 v182, v182
	v_exp_f32_e32 v135, v135
	v_exp_f32_e32 v183, v183
	v_exp_f32_e32 v136, v136
	v_exp_f32_e32 v184, v184
	v_exp_f32_e32 v137, v137
	v_add_f32_e32 v169, 1.0, v169
	v_add_f32_e32 v134, 1.0, v134
	v_add_f32_e32 v182, 1.0, v182
	v_add_f32_e32 v135, 1.0, v135
	v_add_f32_e32 v183, 1.0, v183
	v_add_f32_e32 v136, 1.0, v136
	v_add_f32_e32 v184, 1.0, v184
	v_add_f32_e32 v137, 1.0, v137
	v_rcp_f32_e32 v169, v169
	v_rcp_f32_e32 v134, v134
	v_rcp_f32_e32 v182, v182
	v_rcp_f32_e32 v135, v135
	v_rcp_f32_e32 v183, v183
	v_rcp_f32_e32 v136, v136
	v_rcp_f32_e32 v184, v184
	v_rcp_f32_e32 v137, v137
	s_waitcnt vmcnt(8)
	v_lshlrev_b32_e32 v185, 16, v216
	v_and_b32_e32 v176, 0xffff0000, v216
	v_lshlrev_b32_e32 v186, 16, v217
	v_and_b32_e32 v177, 0xffff0000, v217
	v_lshlrev_b32_e32 v187, 16, v218
	v_and_b32_e32 v178, 0xffff0000, v218
	v_lshlrev_b32_e32 v188, 16, v219
	v_and_b32_e32 v179, 0xffff0000, v219
	s_mov_b64 s[98:99], 0x40000
	v_lshl_add_u64 v[248:249], v[252:253], 0, s[98:99]
	global_load_dwordx4 v[216:219], v[248:249], off
	v_fmac_f32_e32 v185, v126, v169
	v_fmac_f32_e32 v176, v127, v134
	v_fmac_f32_e32 v186, v128, v182
	v_fmac_f32_e32 v177, v129, v135
	v_fmac_f32_e32 v187, v122, v183
	v_fmac_f32_e32 v178, v123, v136
	v_fmac_f32_e32 v188, v124, v184
	v_fmac_f32_e32 v179, v125, v137
	v_cvt_pk_bf16_f32 v122, v185, v176
	v_cvt_pk_bf16_f32 v123, v186, v177
	v_cvt_pk_bf16_f32 v124, v187, v178
	v_cvt_pk_bf16_f32 v125, v188, v179
	global_store_dwordx4 v[130:131], v[122:125], off
	s_nop 0
	v_or_b32_e32 v176, 48, v168
	v_lshlrev_b64 v[122:123], 11, v[180:181]
	v_lshl_add_u64 v[122:123], s[10:11], 0, v[122:123]
	v_lshl_add_u64 v[122:123], v[122:123], 0, v[166:167]
	s_nop 0
	v_ashrrev_i32_e32 v177, 31, v176
	v_lshlrev_b64 v[124:125], 10, v[176:177]
	v_lshl_add_u64 v[124:125], v[170:171], 0, v[124:125]
	s_waitcnt vmcnt(9)
; __device__ __forceinline__ unsigned cvt_pk_bf16(float lo, float hi) { unsigned r; asm volatile("v_cvt_pk_bf16_f32 %0, %1, %2" : "=v"(r) : "v"(lo), "v"(hi)); return r; }
; __device__ __forceinline__ float bflo(unsigned u) { return __uint_as_float(u << 16); }
; __device__ __forceinline__ float bfhi(unsigned u) { return __uint_as_float(u & 0xffff0000u); }
; __device__ __forceinline__ float sigm(float v) { return __builtin_amdgcn_rcpf(1.0f + __expf(-v)); }
; DI float bflo(unsigned u) { return __uint_as_float(u << 16); }
; DI float bfhi(unsigned u) { return __uint_as_float(u & 0xffff0000u); }
;     __device__ __forceinline__ void operator()(const f32x4 (&acc)[2][2][4][2], const Unit& u, int wr, int wc, int fr, int fq) const {
;     ...
;         for (int bj = 0; bj < 2; ++bj) {
;             const f32x4 b0 = *(const f32x4*)(gb + col0 + bj * HALF), b1 = *(const f32x4*)(gb + col0 + bj * HALF + 4);
; #pragma unroll
;             for (int ai = 0; ai < 2; ++ai)
; #pragma unroll
;                 for (int m = 0; m < 4; ++m) { const size_t row = (size_t)(row0 + ai * HALF + m * 16);
;                     const u32x4 g = *(const u32x4*)(gbase + row * 512 + gcol0 + bj * HALF);
;                     const f32x4 v0 = acc[ai][bj][m][0], v1 = acc[ai][bj][m][1];
;                     float r0 = v0[0] * sigm(bflo(g.x) + b0[0]), r1 = v0[1] * sigm(bfhi(g.x) + b0[1]), r2 = v0[2] * sigm(bflo(g.y) + b0[2]), r3 = v0[3] * sigm(bfhi(g.y) + b0[3]);
;                     float r4 = v1[0] * sigm(bflo(g.z) + b1[0]), r5 = v1[1] * sigm(bfhi(g.z) + b1[1]), r6 = v1[2] * sigm(bflo(g.w) + b1[2]), r7 = v1[3] * sigm(bfhi(g.w) + b1[3]);
;                     bf16_t* op = Mo + row * 1024 + col0 + bj * HALF;
;                     if (accum) { const u32x4 p = *(const u32x4*)op; r0 += bflo(p.x); r1 += bfhi(p.x); r2 += bflo(p.y); r3 += bfhi(p.y); r4 += bflo(p.z); r5 += bfhi(p.z); r6 += bflo(p.w); r7 += bfhi(p.w); }
;                     u32x4 w; w.x = cvt_pk_bf16(r0, r1); w.y = cvt_pk_bf16(r2, r3); w.z = cvt_pk_bf16(r4, r5); w.w = cvt_pk_bf16(r6, r7);
;                     *(u32x4*)op = w; }
	v_lshlrev_b32_e32 v169, 16, v208
	v_and_b32_e32 v126, 0xffff0000, v208
	v_lshlrev_b32_e32 v178, 16, v209
	v_and_b32_e32 v127, 0xffff0000, v209
	v_lshlrev_b32_e32 v179, 16, v210
	v_and_b32_e32 v128, 0xffff0000, v210
	v_lshlrev_b32_e32 v180, 16, v211
	v_and_b32_e32 v129, 0xffff0000, v211
	s_mov_b64 s[98:99], 0x24000
	v_lshl_add_u64 v[248:249], v[250:251], 0, s[98:99]
	global_load_dwordx4 v[208:211], v[248:249], off
	v_add_f32_e32 v169, v118, v169
	v_add_f32_e32 v126, v119, v126
	v_add_f32_e32 v178, v120, v178
	v_add_f32_e32 v127, v121, v127
	v_add_f32_e32 v179, v114, v179
	v_add_f32_e32 v128, v115, v128
	v_add_f32_e32 v180, v116, v180
	v_add_f32_e32 v129, v117, v129
	v_mul_f32_e32 v169, 0xbfb8aa3b, v169
	v_mul_f32_e32 v126, 0xbfb8aa3b, v126
	v_mul_f32_e32 v178, 0xbfb8aa3b, v178
	v_mul_f32_e32 v127, 0xbfb8aa3b, v127
	v_mul_f32_e32 v179, 0xbfb8aa3b, v179
	v_mul_f32_e32 v128, 0xbfb8aa3b, v128
	v_mul_f32_e32 v180, 0xbfb8aa3b, v180
	v_mul_f32_e32 v129, 0xbfb8aa3b, v129
	v_exp_f32_e32 v169, v169
	v_exp_f32_e32 v126, v126
	v_exp_f32_e32 v178, v178
	v_exp_f32_e32 v127, v127
	v_exp_f32_e32 v179, v179
	v_exp_f32_e32 v128, v128
	v_exp_f32_e32 v180, v180
	v_exp_f32_e32 v129, v129
	v_add_f32_e32 v169, 1.0, v169
	v_add_f32_e32 v126, 1.0, v126
	v_add_f32_e32 v178, 1.0, v178
	v_add_f32_e32 v127, 1.0, v127
	v_add_f32_e32 v179, 1.0, v179
	v_add_f32_e32 v128, 1.0, v128
	v_add_f32_e32 v180, 1.0, v180
	v_add_f32_e32 v129, 1.0, v129
	v_rcp_f32_e32 v169, v169
	v_rcp_f32_e32 v126, v126
	v_rcp_f32_e32 v178, v178
	v_rcp_f32_e32 v127, v127
	v_rcp_f32_e32 v179, v179
	v_rcp_f32_e32 v128, v128
	v_rcp_f32_e32 v180, v180
	v_rcp_f32_e32 v129, v129
	s_waitcnt vmcnt(9)
	v_lshlrev_b32_e32 v181, 16, v220
	v_and_b32_e32 v134, 0xffff0000, v220
	v_lshlrev_b32_e32 v182, 16, v221
	v_and_b32_e32 v135, 0xffff0000, v221
	v_lshlrev_b32_e32 v183, 16, v222
	v_and_b32_e32 v136, 0xffff0000, v222
	v_lshlrev_b32_e32 v184, 16, v223
	v_and_b32_e32 v137, 0xffff0000, v223
	s_mov_b64 s[98:99], 0x48000
	v_lshl_add_u64 v[248:249], v[252:253], 0, s[98:99]
	global_load_dwordx4 v[220:223], v[248:249], off
	v_fmac_f32_e32 v181, v110, v169
	v_fmac_f32_e32 v134, v111, v126
	v_fmac_f32_e32 v182, v112, v178
	v_fmac_f32_e32 v135, v113, v127
	v_fmac_f32_e32 v183, v106, v179
	v_fmac_f32_e32 v136, v107, v128
	v_fmac_f32_e32 v184, v108, v180
	v_fmac_f32_e32 v137, v109, v129
	v_cvt_pk_bf16_f32 v106, v181, v134
	v_cvt_pk_bf16_f32 v107, v182, v135
	v_cvt_pk_bf16_f32 v108, v183, v136
	v_cvt_pk_bf16_f32 v109, v184, v137
	global_store_dwordx4 v[122:123], v[106:109], off
	s_nop 0
	v_add_u32_e32 v134, 0x80, v168
	v_lshlrev_b64 v[106:107], 11, v[176:177]
	v_lshl_add_u64 v[106:107], s[10:11], 0, v[106:107]
	v_lshl_add_u64 v[106:107], v[106:107], 0, v[166:167]
	s_nop 0
	v_ashrrev_i32_e32 v135, 31, v134
	v_lshlrev_b64 v[108:109], 10, v[134:135]
	v_lshl_add_u64 v[108:109], v[170:171], 0, v[108:109]
	s_waitcnt vmcnt(10)
	v_lshlrev_b32_e32 v136, 16, v212
	v_and_b32_e32 v110, 0xffff0000, v212
	v_lshlrev_b32_e32 v137, 16, v213
	v_and_b32_e32 v111, 0xffff0000, v213
	v_lshlrev_b32_e32 v169, 16, v214
	v_and_b32_e32 v112, 0xffff0000, v214
	v_lshlrev_b32_e32 v176, 16, v215
	v_and_b32_e32 v113, 0xffff0000, v215
	s_mov_b64 s[98:99], 0x28000
	v_lshl_add_u64 v[248:249], v[250:251], 0, s[98:99]
	global_load_dwordx4 v[212:215], v[248:249], off
	v_add_f32_e32 v136, v118, v136
	v_add_f32_e32 v110, v119, v110
	v_add_f32_e32 v137, v120, v137
	v_add_f32_e32 v111, v121, v111
	v_add_f32_e32 v169, v114, v169
	v_add_f32_e32 v112, v115, v112
	v_add_f32_e32 v176, v116, v176
	v_add_f32_e32 v113, v117, v113
	v_mul_f32_e32 v136, 0xbfb8aa3b, v136
	v_mul_f32_e32 v110, 0xbfb8aa3b, v110
	v_mul_f32_e32 v137, 0xbfb8aa3b, v137
	v_mul_f32_e32 v111, 0xbfb8aa3b, v111
	v_mul_f32_e32 v169, 0xbfb8aa3b, v169
	v_mul_f32_e32 v112, 0xbfb8aa3b, v112
	v_mul_f32_e32 v176, 0xbfb8aa3b, v176
	v_mul_f32_e32 v113, 0xbfb8aa3b, v113
	v_exp_f32_e32 v136, v136
	v_exp_f32_e32 v110, v110
	v_exp_f32_e32 v137, v137
	v_exp_f32_e32 v111, v111
	v_exp_f32_e32 v169, v169
	v_exp_f32_e32 v112, v112
	v_exp_f32_e32 v176, v176
	v_exp_f32_e32 v113, v113
	v_add_f32_e32 v136, 1.0, v136
	v_add_f32_e32 v110, 1.0, v110
	v_add_f32_e32 v137, 1.0, v137
	v_add_f32_e32 v111, 1.0, v111
	v_add_f32_e32 v169, 1.0, v169
	v_add_f32_e32 v112, 1.0, v112
	v_add_f32_e32 v176, 1.0, v176
	v_add_f32_e32 v113, 1.0, v113
	v_rcp_f32_e32 v136, v136
	v_rcp_f32_e32 v110, v110
	v_rcp_f32_e32 v137, v137
	v_rcp_f32_e32 v111, v111
	v_rcp_f32_e32 v169, v169
	v_rcp_f32_e32 v112, v112
	v_rcp_f32_e32 v176, v176
	v_rcp_f32_e32 v113, v113
	s_waitcnt vmcnt(10)
	v_lshlrev_b32_e32 v177, 16, v224
	v_and_b32_e32 v126, 0xffff0000, v224
	v_lshlrev_b32_e32 v178, 16, v225
	v_and_b32_e32 v127, 0xffff0000, v225
	v_lshlrev_b32_e32 v179, 16, v226
	v_and_b32_e32 v128, 0xffff0000, v226
	v_lshlrev_b32_e32 v180, 16, v227
	v_and_b32_e32 v129, 0xffff0000, v227
	s_mov_b64 s[98:99], 0x50000
	v_lshl_add_u64 v[248:249], v[252:253], 0, s[98:99]
	global_load_dwordx4 v[224:227], v[248:249], off
	v_fmac_f32_e32 v177, v102, v136
	v_fmac_f32_e32 v126, v103, v110
	v_fmac_f32_e32 v178, v104, v137
	v_fmac_f32_e32 v127, v105, v111
	v_fmac_f32_e32 v179, v98, v169
	v_fmac_f32_e32 v128, v99, v112
	v_fmac_f32_e32 v180, v100, v176
	v_fmac_f32_e32 v129, v101, v113
	v_cvt_pk_bf16_f32 v98, v177, v126
	v_cvt_pk_bf16_f32 v99, v178, v127
	v_cvt_pk_bf16_f32 v100, v179, v128
	v_cvt_pk_bf16_f32 v101, v180, v129
	global_store_dwordx4 v[106:107], v[98:101], off
	s_nop 0
	v_add_u32_e32 v126, 0x90, v168
	v_lshlrev_b64 v[98:99], 11, v[134:135]
	v_lshl_add_u64 v[98:99], s[10:11], 0, v[98:99]
	v_lshl_add_u64 v[98:99], v[98:99], 0, v[166:167]
	s_nop 0
	v_ashrrev_i32_e32 v127, 31, v126
	v_lshlrev_b64 v[100:101], 10, v[126:127]
	v_lshl_add_u64 v[100:101], v[170:171], 0, v[100:101]
	s_waitcnt vmcnt(8)
; __device__ __forceinline__ unsigned cvt_pk_bf16(float lo, float hi) { unsigned r; asm volatile("v_cvt_pk_bf16_f32 %0, %1, %2" : "=v"(r) : "v"(lo), "v"(hi)); return r; }
; __device__ __forceinline__ float bflo(unsigned u) { return __uint_as_float(u << 16); }
; __device__ __forceinline__ float bfhi(unsigned u) { return __uint_as_float(u & 0xffff0000u); }
; __device__ __forceinline__ float sigm(float v) { return __builtin_amdgcn_rcpf(1.0f + __expf(-v)); }
; DI float bflo(unsigned u) { return __uint_as_float(u << 16); }
; DI float bfhi(unsigned u) { return __uint_as_float(u & 0xffff0000u); }
;     __device__ __forceinline__ void operator()(const f32x4 (&acc)[2][2][4][2], const Unit& u, int wr, int wc, int fr, int fq) const {
;     ...
;         for (int bj = 0; bj < 2; ++bj) {
;             const f32x4 b0 = *(const f32x4*)(gb + col0 + bj * HALF), b1 = *(const f32x4*)(gb + col0 + bj * HALF + 4);
; #pragma unroll
;             for (int ai = 0; ai < 2; ++ai)
; #pragma unroll
;                 for (int m = 0; m < 4; ++m) { const size_t row = (size_t)(row0 + ai * HALF + m * 16);
;                     const u32x4 g = *(const u32x4*)(gbase + row * 512 + gcol0 + bj * HALF);
;                     const f32x4 v0 = acc[ai][bj][m][0], v1 = acc[ai][bj][m][1];
;                     float r0 = v0[0] * sigm(bflo(g.x) + b0[0]), r1 = v0[1] * sigm(bfhi(g.x) + b0[1]), r2 = v0[2] * sigm(bflo(g.y) + b0[2]), r3 = v0[3] * sigm(bfhi(g.y) + b0[3]);
;                     float r4 = v1[0] * sigm(bflo(g.z) + b1[0]), r5 = v1[1] * sigm(bfhi(g.z) + b1[1]), r6 = v1[2] * sigm(bflo(g.w) + b1[2]), r7 = v1[3] * sigm(bfhi(g.w) + b1[3]);
;                     bf16_t* op = Mo + row * 1024 + col0 + bj * HALF;
;                     if (accum) { const u32x4 p = *(const u32x4*)op; r0 += bflo(p.x); r1 += bfhi(p.x); r2 += bflo(p.y); r3 += bfhi(p.y); r4 += bflo(p.z); r5 += bfhi(p.z); r6 += bflo(p.w); r7 += bfhi(p.w); }
;                     u32x4 w; w.x = cvt_pk_bf16(r0, r1); w.y = cvt_pk_bf16(r2, r3); w.z = cvt_pk_bf16(r4, r5); w.w = cvt_pk_bf16(r6, r7);
;                     *(u32x4*)op = w; }
	v_lshlrev_b32_e32 v128, 16, v204
	v_and_b32_e32 v102, 0xffff0000, v204
	v_lshlrev_b32_e32 v129, 16, v205
	v_and_b32_e32 v103, 0xffff0000, v205
	v_lshlrev_b32_e32 v134, 16, v206
	v_and_b32_e32 v104, 0xffff0000, v206
	v_lshlrev_b32_e32 v135, 16, v207
	v_and_b32_e32 v105, 0xffff0000, v207
	s_mov_b64 s[98:99], 0x2c000
	v_lshl_add_u64 v[248:249], v[250:251], 0, s[98:99]
	global_load_dwordx4 v[204:207], v[248:249], off
	v_add_f32_e32 v128, v118, v128
	v_add_f32_e32 v102, v119, v102
	v_add_f32_e32 v129, v120, v129
	v_add_f32_e32 v103, v121, v103
	v_add_f32_e32 v134, v114, v134
	v_add_f32_e32 v104, v115, v104
	v_add_f32_e32 v135, v116, v135
	v_add_f32_e32 v105, v117, v105
	v_mul_f32_e32 v128, 0xbfb8aa3b, v128
	v_mul_f32_e32 v102, 0xbfb8aa3b, v102
	v_mul_f32_e32 v129, 0xbfb8aa3b, v129
	v_mul_f32_e32 v103, 0xbfb8aa3b, v103
	v_mul_f32_e32 v134, 0xbfb8aa3b, v134
	v_mul_f32_e32 v104, 0xbfb8aa3b, v104
	v_mul_f32_e32 v135, 0xbfb8aa3b, v135
	v_mul_f32_e32 v105, 0xbfb8aa3b, v105
	v_exp_f32_e32 v128, v128
	v_exp_f32_e32 v102, v102
	v_exp_f32_e32 v129, v129
	v_exp_f32_e32 v103, v103
	v_exp_f32_e32 v134, v134
	v_exp_f32_e32 v104, v104
	v_exp_f32_e32 v135, v135
	v_exp_f32_e32 v105, v105
	v_add_f32_e32 v128, 1.0, v128
	v_add_f32_e32 v102, 1.0, v102
	v_add_f32_e32 v129, 1.0, v129
	v_add_f32_e32 v103, 1.0, v103
	v_add_f32_e32 v134, 1.0, v134
	v_add_f32_e32 v104, 1.0, v104
	v_add_f32_e32 v135, 1.0, v135
	v_add_f32_e32 v105, 1.0, v105
	v_rcp_f32_e32 v128, v128
	v_rcp_f32_e32 v102, v102
	v_rcp_f32_e32 v129, v129
	v_rcp_f32_e32 v103, v103
	v_rcp_f32_e32 v134, v134
	v_rcp_f32_e32 v104, v104
	v_rcp_f32_e32 v135, v135
	v_rcp_f32_e32 v105, v105
	s_waitcnt vmcnt(8)
	v_lshlrev_b32_e32 v136, 16, v216
	v_and_b32_e32 v110, 0xffff0000, v216
	v_lshlrev_b32_e32 v137, 16, v217
	v_and_b32_e32 v111, 0xffff0000, v217
	v_lshlrev_b32_e32 v169, 16, v218
	v_and_b32_e32 v112, 0xffff0000, v218
	v_lshlrev_b32_e32 v176, 16, v219
	v_and_b32_e32 v113, 0xffff0000, v219
	s_mov_b64 s[98:99], 0x58000
	v_lshl_add_u64 v[248:249], v[252:253], 0, s[98:99]
	global_load_dwordx4 v[216:219], v[248:249], off
	v_fmac_f32_e32 v136, v94, v128
	v_fmac_f32_e32 v110, v95, v102
	v_fmac_f32_e32 v137, v96, v129
	v_fmac_f32_e32 v111, v97, v103
	v_fmac_f32_e32 v169, v90, v134
	v_fmac_f32_e32 v112, v91, v104
	v_fmac_f32_e32 v176, v92, v135
	v_fmac_f32_e32 v113, v93, v105
	v_cvt_pk_bf16_f32 v90, v136, v110
	v_cvt_pk_bf16_f32 v91, v137, v111
	v_cvt_pk_bf16_f32 v92, v169, v112
	v_cvt_pk_bf16_f32 v93, v176, v113
	global_store_dwordx4 v[98:99], v[90:93], off
	s_nop 0
	v_add_u32_e32 v110, 0xa0, v168
	v_lshlrev_b64 v[90:91], 11, v[126:127]
	v_lshl_add_u64 v[90:91], s[10:11], 0, v[90:91]
	v_lshl_add_u64 v[90:91], v[90:91], 0, v[166:167]
	s_nop 0
	v_ashrrev_i32_e32 v111, 31, v110
	v_lshlrev_b64 v[92:93], 10, v[110:111]
	v_lshl_add_u64 v[92:93], v[170:171], 0, v[92:93]
	s_waitcnt vmcnt(8)
	v_lshlrev_b32_e32 v112, 16, v208
	v_and_b32_e32 v94, 0xffff0000, v208
	v_lshlrev_b32_e32 v113, 16, v209
	v_and_b32_e32 v95, 0xffff0000, v209
	v_lshlrev_b32_e32 v126, 16, v210
	v_and_b32_e32 v96, 0xffff0000, v210
	v_lshlrev_b32_e32 v127, 16, v211
	v_and_b32_e32 v97, 0xffff0000, v211
	global_load_dwordx4 v[208:211], v[250:251], off offset:256
	v_add_f32_e32 v112, v118, v112
	v_add_f32_e32 v94, v119, v94
	v_add_f32_e32 v113, v120, v113
	v_add_f32_e32 v95, v121, v95
	v_add_f32_e32 v126, v114, v126
	v_add_f32_e32 v96, v115, v96
	v_add_f32_e32 v127, v116, v127
	v_add_f32_e32 v97, v117, v97
	v_mul_f32_e32 v112, 0xbfb8aa3b, v112
	v_mul_f32_e32 v94, 0xbfb8aa3b, v94
	v_mul_f32_e32 v113, 0xbfb8aa3b, v113
	v_mul_f32_e32 v95, 0xbfb8aa3b, v95
	v_mul_f32_e32 v126, 0xbfb8aa3b, v126
	v_mul_f32_e32 v96, 0xbfb8aa3b, v96
	v_mul_f32_e32 v127, 0xbfb8aa3b, v127
	v_mul_f32_e32 v97, 0xbfb8aa3b, v97
	v_exp_f32_e32 v112, v112
	v_exp_f32_e32 v94, v94
	v_exp_f32_e32 v113, v113
	v_exp_f32_e32 v95, v95
	v_exp_f32_e32 v126, v126
	v_exp_f32_e32 v96, v96
	v_exp_f32_e32 v127, v127
	v_exp_f32_e32 v97, v97
	v_add_f32_e32 v112, 1.0, v112
	v_add_f32_e32 v94, 1.0, v94
	v_add_f32_e32 v113, 1.0, v113
	v_add_f32_e32 v95, 1.0, v95
	v_add_f32_e32 v126, 1.0, v126
	v_add_f32_e32 v96, 1.0, v96
	v_add_f32_e32 v127, 1.0, v127
	v_add_f32_e32 v97, 1.0, v97
	v_rcp_f32_e32 v112, v112
	v_rcp_f32_e32 v94, v94
	v_rcp_f32_e32 v113, v113
	v_rcp_f32_e32 v95, v95
	v_rcp_f32_e32 v126, v126
	v_rcp_f32_e32 v96, v96
	v_rcp_f32_e32 v127, v127
	v_rcp_f32_e32 v97, v97
	s_waitcnt vmcnt(8)
	v_lshlrev_b32_e32 v128, 16, v220
	v_and_b32_e32 v102, 0xffff0000, v220
	v_lshlrev_b32_e32 v129, 16, v221
	v_and_b32_e32 v103, 0xffff0000, v221
	v_lshlrev_b32_e32 v134, 16, v222
	v_and_b32_e32 v104, 0xffff0000, v222
	v_lshlrev_b32_e32 v135, 16, v223
	v_and_b32_e32 v105, 0xffff0000, v223
	global_load_dwordx4 v[220:223], v[252:253], off offset:256
	v_fmac_f32_e32 v128, v86, v112
	v_fmac_f32_e32 v102, v87, v94
	v_fmac_f32_e32 v129, v88, v113
	v_fmac_f32_e32 v103, v89, v95
	v_fmac_f32_e32 v134, v82, v126
	v_fmac_f32_e32 v104, v83, v96
	v_fmac_f32_e32 v135, v84, v127
	v_fmac_f32_e32 v105, v85, v97
	v_cvt_pk_bf16_f32 v82, v128, v102
	v_cvt_pk_bf16_f32 v83, v129, v103
	v_cvt_pk_bf16_f32 v84, v134, v104
	v_cvt_pk_bf16_f32 v85, v135, v105
	global_store_dwordx4 v[90:91], v[82:85], off
	s_nop 0
	v_add_u32_e32 v102, 0xb0, v168
	v_lshlrev_b64 v[82:83], 11, v[110:111]
	v_lshl_add_u64 v[82:83], s[10:11], 0, v[82:83]
	v_lshl_add_u64 v[82:83], v[82:83], 0, v[166:167]
	s_nop 0
	v_ashrrev_i32_e32 v103, 31, v102
	v_lshlrev_b64 v[84:85], 10, v[102:103]
	v_lshl_add_u64 v[84:85], v[170:171], 0, v[84:85]
	s_waitcnt vmcnt(8)
; __device__ __forceinline__ unsigned cvt_pk_bf16(float lo, float hi) { unsigned r; asm volatile("v_cvt_pk_bf16_f32 %0, %1, %2" : "=v"(r) : "v"(lo), "v"(hi)); return r; }
; __device__ __forceinline__ float bflo(unsigned u) { return __uint_as_float(u << 16); }
; __device__ __forceinline__ float bfhi(unsigned u) { return __uint_as_float(u & 0xffff0000u); }
; __device__ __forceinline__ float sigm(float v) { return __builtin_amdgcn_rcpf(1.0f + __expf(-v)); }
; DI float bflo(unsigned u) { return __uint_as_float(u << 16); }
; DI float bfhi(unsigned u) { return __uint_as_float(u & 0xffff0000u); }
;     __device__ __forceinline__ void operator()(const f32x4 (&acc)[2][2][4][2], const Unit& u, int wr, int wc, int fr, int fq) const {
;     ...
;         for (int bj = 0; bj < 2; ++bj) {
;             const f32x4 b0 = *(const f32x4*)(gb + col0 + bj * HALF), b1 = *(const f32x4*)(gb + col0 + bj * HALF + 4);
; #pragma unroll
;             for (int ai = 0; ai < 2; ++ai)
; #pragma unroll
;                 for (int m = 0; m < 4; ++m) { const size_t row = (size_t)(row0 + ai * HALF + m * 16);
;                     const u32x4 g = *(const u32x4*)(gbase + row * 512 + gcol0 + bj * HALF);
;                     const f32x4 v0 = acc[ai][bj][m][0], v1 = acc[ai][bj][m][1];
;                     float r0 = v0[0] * sigm(bflo(g.x) + b0[0]), r1 = v0[1] * sigm(bfhi(g.x) + b0[1]), r2 = v0[2] * sigm(bflo(g.y) + b0[2]), r3 = v0[3] * sigm(bfhi(g.y) + b0[3]);
;                     float r4 = v1[0] * sigm(bflo(g.z) + b1[0]), r5 = v1[1] * sigm(bfhi(g.z) + b1[1]), r6 = v1[2] * sigm(bflo(g.w) + b1[2]), r7 = v1[3] * sigm(bfhi(g.w) + b1[3]);
;                     bf16_t* op = Mo + row * 1024 + col0 + bj * HALF;
;                     if (accum) { const u32x4 p = *(const u32x4*)op; r0 += bflo(p.x); r1 += bfhi(p.x); r2 += bflo(p.y); r3 += bfhi(p.y); r4 += bflo(p.z); r5 += bfhi(p.z); r6 += bflo(p.w); r7 += bfhi(p.w); }
;                     u32x4 w; w.x = cvt_pk_bf16(r0, r1); w.y = cvt_pk_bf16(r2, r3); w.z = cvt_pk_bf16(r4, r5); w.w = cvt_pk_bf16(r6, r7);
;                     *(u32x4*)op = w; }
	v_lshlrev_b32_e32 v104, 16, v212
	v_and_b32_e32 v86, 0xffff0000, v212
	v_lshlrev_b32_e32 v105, 16, v213
	v_and_b32_e32 v87, 0xffff0000, v213
	v_lshlrev_b32_e32 v110, 16, v214
	v_and_b32_e32 v88, 0xffff0000, v214
	v_lshlrev_b32_e32 v111, 16, v215
	v_and_b32_e32 v89, 0xffff0000, v215
	s_mov_b64 s[98:99], 0x4000
	v_lshl_add_u64 v[248:249], v[250:251], 0, s[98:99]
	global_load_dwordx4 v[212:215], v[248:249], off offset:256
	v_add_f32_e32 v104, v118, v104
	v_add_f32_e32 v86, v119, v86
	v_add_f32_e32 v105, v120, v105
	v_add_f32_e32 v87, v121, v87
	v_add_f32_e32 v110, v114, v110
	v_add_f32_e32 v88, v115, v88
	v_add_f32_e32 v111, v116, v111
	v_add_f32_e32 v89, v117, v89
	v_mul_f32_e32 v104, 0xbfb8aa3b, v104
	v_mul_f32_e32 v86, 0xbfb8aa3b, v86
	v_mul_f32_e32 v105, 0xbfb8aa3b, v105
	v_mul_f32_e32 v87, 0xbfb8aa3b, v87
	v_mul_f32_e32 v110, 0xbfb8aa3b, v110
	v_mul_f32_e32 v88, 0xbfb8aa3b, v88
	v_mul_f32_e32 v111, 0xbfb8aa3b, v111
	v_mul_f32_e32 v89, 0xbfb8aa3b, v89
	v_exp_f32_e32 v104, v104
	v_exp_f32_e32 v86, v86
	v_exp_f32_e32 v105, v105
	v_exp_f32_e32 v87, v87
	v_exp_f32_e32 v110, v110
	v_exp_f32_e32 v88, v88
	v_exp_f32_e32 v111, v111
	v_exp_f32_e32 v89, v89
	v_add_f32_e32 v104, 1.0, v104
	v_add_f32_e32 v86, 1.0, v86
	v_add_f32_e32 v105, 1.0, v105
	v_add_f32_e32 v87, 1.0, v87
	v_add_f32_e32 v110, 1.0, v110
	v_add_f32_e32 v88, 1.0, v88
	v_add_f32_e32 v111, 1.0, v111
	v_add_f32_e32 v89, 1.0, v89
	v_rcp_f32_e32 v104, v104
	v_rcp_f32_e32 v86, v86
	v_rcp_f32_e32 v105, v105
	v_rcp_f32_e32 v87, v87
	v_rcp_f32_e32 v110, v110
	v_rcp_f32_e32 v88, v88
	v_rcp_f32_e32 v111, v111
	v_rcp_f32_e32 v89, v89
	s_waitcnt vmcnt(8)
	v_lshlrev_b32_e32 v112, 16, v224
	v_and_b32_e32 v94, 0xffff0000, v224
	v_lshlrev_b32_e32 v113, 16, v225
	v_and_b32_e32 v95, 0xffff0000, v225
	v_lshlrev_b32_e32 v126, 16, v226
	v_and_b32_e32 v96, 0xffff0000, v226
	v_lshlrev_b32_e32 v127, 16, v227
	v_and_b32_e32 v97, 0xffff0000, v227
	s_mov_b64 s[98:99], 0x8000
	v_lshl_add_u64 v[248:249], v[252:253], 0, s[98:99]
	global_load_dwordx4 v[224:227], v[248:249], off offset:256
	v_fmac_f32_e32 v112, v78, v104
	v_fmac_f32_e32 v94, v79, v86
	v_fmac_f32_e32 v113, v80, v105
	v_fmac_f32_e32 v95, v81, v87
	v_fmac_f32_e32 v126, v74, v110
	v_fmac_f32_e32 v96, v75, v88
	v_fmac_f32_e32 v127, v76, v111
	v_fmac_f32_e32 v97, v77, v89
	v_cvt_pk_bf16_f32 v74, v112, v94
	v_cvt_pk_bf16_f32 v75, v113, v95
	v_cvt_pk_bf16_f32 v76, v126, v96
	v_cvt_pk_bf16_f32 v77, v127, v97
	global_store_dwordx4 v[82:83], v[74:77], off
	s_nop 0
	s_nop 0
	v_lshlrev_b64 v[74:75], 11, v[102:103]
	v_lshl_add_u64 v[74:75], s[10:11], 0, v[74:75]
	v_lshl_add_u64 v[74:75], v[74:75], 0, v[166:167]
	s_nop 0
	s_waitcnt vmcnt(8)
	v_lshlrev_b32_e32 v80, 16, v204
	v_and_b32_e32 v76, 0xffff0000, v204
	v_lshlrev_b32_e32 v81, 16, v205
	v_and_b32_e32 v77, 0xffff0000, v205
	v_lshlrev_b32_e32 v94, 16, v206
	v_and_b32_e32 v78, 0xffff0000, v206
	v_lshlrev_b32_e32 v95, 16, v207
	v_and_b32_e32 v79, 0xffff0000, v207
	s_mov_b64 s[98:99], 0x8000
	v_lshl_add_u64 v[248:249], v[250:251], 0, s[98:99]
	global_load_dwordx4 v[204:207], v[248:249], off offset:256
	v_add_f32_e32 v80, v118, v80
	v_add_f32_e32 v76, v119, v76
	v_add_f32_e32 v81, v120, v81
	v_add_f32_e32 v77, v121, v77
	v_add_f32_e32 v94, v114, v94
	v_add_f32_e32 v78, v115, v78
	v_add_f32_e32 v95, v116, v95
	v_add_f32_e32 v79, v117, v79
	v_mul_f32_e32 v80, 0xbfb8aa3b, v80
	v_mul_f32_e32 v76, 0xbfb8aa3b, v76
	v_mul_f32_e32 v81, 0xbfb8aa3b, v81
	v_mul_f32_e32 v77, 0xbfb8aa3b, v77
	v_mul_f32_e32 v94, 0xbfb8aa3b, v94
	v_mul_f32_e32 v78, 0xbfb8aa3b, v78
	v_mul_f32_e32 v95, 0xbfb8aa3b, v95
	v_mul_f32_e32 v79, 0xbfb8aa3b, v79
	v_exp_f32_e32 v80, v80
	v_exp_f32_e32 v76, v76
	v_exp_f32_e32 v81, v81
	v_exp_f32_e32 v77, v77
	v_exp_f32_e32 v94, v94
	v_exp_f32_e32 v78, v78
	v_exp_f32_e32 v95, v95
	v_exp_f32_e32 v79, v79
	v_add_f32_e32 v80, 1.0, v80
	v_add_f32_e32 v76, 1.0, v76
	v_add_f32_e32 v81, 1.0, v81
	v_add_f32_e32 v77, 1.0, v77
	v_add_f32_e32 v94, 1.0, v94
	v_add_f32_e32 v78, 1.0, v78
	v_add_f32_e32 v95, 1.0, v95
	v_add_f32_e32 v79, 1.0, v79
	v_rcp_f32_e32 v80, v80
	v_rcp_f32_e32 v76, v76
	v_rcp_f32_e32 v81, v81
	v_rcp_f32_e32 v77, v77
	v_rcp_f32_e32 v94, v94
	v_rcp_f32_e32 v78, v78
	v_rcp_f32_e32 v95, v95
	v_rcp_f32_e32 v79, v79
	s_waitcnt vmcnt(8)
	v_lshlrev_b32_e32 v96, 16, v216
	v_and_b32_e32 v86, 0xffff0000, v216
	v_lshlrev_b32_e32 v97, 16, v217
	v_and_b32_e32 v87, 0xffff0000, v217
	v_lshlrev_b32_e32 v102, 16, v218
	v_and_b32_e32 v88, 0xffff0000, v218
	v_lshlrev_b32_e32 v103, 16, v219
	v_and_b32_e32 v89, 0xffff0000, v219
	s_mov_b64 s[98:99], 0x10000
	v_lshl_add_u64 v[248:249], v[252:253], 0, s[98:99]
	global_load_dwordx4 v[216:219], v[248:249], off offset:256
	v_fmac_f32_e32 v96, v70, v80
	v_fmac_f32_e32 v86, v71, v76
	v_fmac_f32_e32 v97, v72, v81
	v_fmac_f32_e32 v87, v73, v77
	v_fmac_f32_e32 v102, v66, v94
	v_fmac_f32_e32 v88, v67, v78
	v_fmac_f32_e32 v103, v68, v95
	v_fmac_f32_e32 v89, v69, v79
	v_cvt_pk_bf16_f32 v66, v96, v86
	v_cvt_pk_bf16_f32 v67, v97, v87
	v_cvt_pk_bf16_f32 v68, v102, v88
	v_cvt_pk_bf16_f32 v69, v103, v89
	global_store_dwordx4 v[74:75], v[66:69], off
	s_nop 0
	s_nop 0
	v_mov_b32_e32 v70, v240
	v_mov_b32_e32 v71, v241
	v_mov_b32_e32 v72, v242
	v_mov_b32_e32 v73, v243
	s_nop 0
	v_mov_b32_e32 v66, v244
	v_mov_b32_e32 v67, v245
	v_mov_b32_e32 v68, v246
	v_mov_b32_e32 v69, v247
	s_waitcnt vmcnt(8)
	v_lshlrev_b32_e32 v80, 16, v208
	v_and_b32_e32 v76, 0xffff0000, v208
	v_lshlrev_b32_e32 v81, 16, v209
	v_and_b32_e32 v77, 0xffff0000, v209
	v_lshlrev_b32_e32 v94, 16, v210
	v_and_b32_e32 v78, 0xffff0000, v210
	v_lshlrev_b32_e32 v95, 16, v211
	v_and_b32_e32 v79, 0xffff0000, v211
	s_mov_b64 s[98:99], 0xc000
	v_lshl_add_u64 v[248:249], v[250:251], 0, s[98:99]
	global_load_dwordx4 v[208:211], v[248:249], off offset:256
	s_nop 0
	v_add_f32_e32 v80, v70, v80
	v_add_f32_e32 v76, v71, v76
	v_add_f32_e32 v81, v72, v81
	v_add_f32_e32 v77, v73, v77
	s_waitcnt vmcnt(8)
; __device__ __forceinline__ unsigned cvt_pk_bf16(float lo, float hi) { unsigned r; asm volatile("v_cvt_pk_bf16_f32 %0, %1, %2" : "=v"(r) : "v"(lo), "v"(hi)); return r; }
; __device__ __forceinline__ float bflo(unsigned u) { return __uint_as_float(u << 16); }
; __device__ __forceinline__ float bfhi(unsigned u) { return __uint_as_float(u & 0xffff0000u); }
; __device__ __forceinline__ float sigm(float v) { return __builtin_amdgcn_rcpf(1.0f + __expf(-v)); }
; DI float bflo(unsigned u) { return __uint_as_float(u << 16); }
; DI float bfhi(unsigned u) { return __uint_as_float(u & 0xffff0000u); }
;     __device__ __forceinline__ void operator()(const f32x4 (&acc)[2][2][4][2], const Unit& u, int wr, int wc, int fr, int fq) const {
;     ...
;         for (int bj = 0; bj < 2; ++bj) {
;             const f32x4 b0 = *(const f32x4*)(gb + col0 + bj * HALF), b1 = *(const f32x4*)(gb + col0 + bj * HALF + 4);
; #pragma unroll
;             for (int ai = 0; ai < 2; ++ai)
; #pragma unroll
;                 for (int m = 0; m < 4; ++m) { const size_t row = (size_t)(row0 + ai * HALF + m * 16);
;                     const u32x4 g = *(const u32x4*)(gbase + row * 512 + gcol0 + bj * HALF);
;                     const f32x4 v0 = acc[ai][bj][m][0], v1 = acc[ai][bj][m][1];
;                     float r0 = v0[0] * sigm(bflo(g.x) + b0[0]), r1 = v0[1] * sigm(bfhi(g.x) + b0[1]), r2 = v0[2] * sigm(bflo(g.y) + b0[2]), r3 = v0[3] * sigm(bfhi(g.y) + b0[3]);
;                     float r4 = v1[0] * sigm(bflo(g.z) + b1[0]), r5 = v1[1] * sigm(bfhi(g.z) + b1[1]), r6 = v1[2] * sigm(bflo(g.w) + b1[2]), r7 = v1[3] * sigm(bfhi(g.w) + b1[3]);
;                     bf16_t* op = Mo + row * 1024 + col0 + bj * HALF;
;                     if (accum) { const u32x4 p = *(const u32x4*)op; r0 += bflo(p.x); r1 += bfhi(p.x); r2 += bflo(p.y); r3 += bfhi(p.y); r4 += bflo(p.z); r5 += bfhi(p.z); r6 += bflo(p.w); r7 += bfhi(p.w); }
;                     u32x4 w; w.x = cvt_pk_bf16(r0, r1); w.y = cvt_pk_bf16(r2, r3); w.z = cvt_pk_bf16(r4, r5); w.w = cvt_pk_bf16(r6, r7);
;                     *(u32x4*)op = w; }
	v_add_f32_e32 v94, v66, v94
	v_add_f32_e32 v78, v67, v78
	v_add_f32_e32 v95, v68, v95
	v_add_f32_e32 v79, v69, v79
	v_mul_f32_e32 v80, 0xbfb8aa3b, v80
	v_mul_f32_e32 v76, 0xbfb8aa3b, v76
	v_mul_f32_e32 v81, 0xbfb8aa3b, v81
	v_mul_f32_e32 v77, 0xbfb8aa3b, v77
	v_mul_f32_e32 v94, 0xbfb8aa3b, v94
	v_mul_f32_e32 v78, 0xbfb8aa3b, v78
	v_mul_f32_e32 v95, 0xbfb8aa3b, v95
	v_mul_f32_e32 v79, 0xbfb8aa3b, v79
	v_exp_f32_e32 v80, v80
	v_exp_f32_e32 v76, v76
	v_exp_f32_e32 v81, v81
	v_exp_f32_e32 v77, v77
	v_exp_f32_e32 v94, v94
	v_exp_f32_e32 v78, v78
	v_exp_f32_e32 v95, v95
	v_exp_f32_e32 v79, v79
	v_add_f32_e32 v80, 1.0, v80
	v_add_f32_e32 v76, 1.0, v76
	v_add_f32_e32 v81, 1.0, v81
	v_add_f32_e32 v77, 1.0, v77
	v_add_f32_e32 v94, 1.0, v94
	v_add_f32_e32 v78, 1.0, v78
	v_add_f32_e32 v95, 1.0, v95
	v_add_f32_e32 v79, 1.0, v79
	v_rcp_f32_e32 v80, v80
	v_rcp_f32_e32 v76, v76
	v_rcp_f32_e32 v81, v81
	v_rcp_f32_e32 v77, v77
	v_rcp_f32_e32 v94, v94
	v_rcp_f32_e32 v78, v78
	v_rcp_f32_e32 v95, v95
	v_rcp_f32_e32 v79, v79
	v_lshlrev_b32_e32 v96, 16, v220
	v_and_b32_e32 v86, 0xffff0000, v220
	v_lshlrev_b32_e32 v97, 16, v221
	v_and_b32_e32 v87, 0xffff0000, v221
	v_lshlrev_b32_e32 v102, 16, v222
	v_and_b32_e32 v88, 0xffff0000, v222
	v_lshlrev_b32_e32 v103, 16, v223
	v_and_b32_e32 v89, 0xffff0000, v223
	s_mov_b64 s[98:99], 0x18000
	v_lshl_add_u64 v[248:249], v[252:253], 0, s[98:99]
	global_load_dwordx4 v[220:223], v[248:249], off offset:256
	v_fmac_f32_e32 v96, v62, v80
	v_fmac_f32_e32 v86, v63, v76
	v_fmac_f32_e32 v97, v64, v81
	v_fmac_f32_e32 v87, v65, v77
	v_fmac_f32_e32 v102, v58, v94
	v_fmac_f32_e32 v88, v59, v78
	v_fmac_f32_e32 v103, v60, v95
	v_fmac_f32_e32 v89, v61, v79
	v_cvt_pk_bf16_f32 v58, v96, v86
	v_cvt_pk_bf16_f32 v59, v97, v87
	v_cvt_pk_bf16_f32 v60, v102, v88
	v_cvt_pk_bf16_f32 v61, v103, v89
	global_store_dwordx4 v[154:155], v[58:61], off offset:256
	s_nop 0
	s_nop 0
	s_nop 0
	s_waitcnt vmcnt(8)
	v_lshlrev_b32_e32 v76, 16, v212
	v_and_b32_e32 v58, 0xffff0000, v212
	v_lshlrev_b32_e32 v77, 16, v213
	v_and_b32_e32 v59, 0xffff0000, v213
	v_lshlrev_b32_e32 v78, 16, v214
	v_and_b32_e32 v60, 0xffff0000, v214
	v_lshlrev_b32_e32 v79, 16, v215
	v_and_b32_e32 v61, 0xffff0000, v215
	s_mov_b64 s[98:99], 0x20000
	v_lshl_add_u64 v[248:249], v[250:251], 0, s[98:99]
	global_load_dwordx4 v[212:215], v[248:249], off offset:256
	v_add_f32_e32 v76, v70, v76
	v_add_f32_e32 v58, v71, v58
	v_add_f32_e32 v77, v72, v77
	v_add_f32_e32 v59, v73, v59
	v_add_f32_e32 v78, v66, v78
	v_add_f32_e32 v60, v67, v60
	v_add_f32_e32 v79, v68, v79
	v_add_f32_e32 v61, v69, v61
	v_mul_f32_e32 v76, 0xbfb8aa3b, v76
	v_mul_f32_e32 v58, 0xbfb8aa3b, v58
	v_mul_f32_e32 v77, 0xbfb8aa3b, v77
	v_mul_f32_e32 v59, 0xbfb8aa3b, v59
	v_mul_f32_e32 v78, 0xbfb8aa3b, v78
	v_mul_f32_e32 v60, 0xbfb8aa3b, v60
	v_mul_f32_e32 v79, 0xbfb8aa3b, v79
	v_mul_f32_e32 v61, 0xbfb8aa3b, v61
	v_exp_f32_e32 v76, v76
	v_exp_f32_e32 v58, v58
	v_exp_f32_e32 v77, v77
	v_exp_f32_e32 v59, v59
	v_exp_f32_e32 v78, v78
	v_exp_f32_e32 v60, v60
	v_exp_f32_e32 v79, v79
	v_exp_f32_e32 v61, v61
	v_add_f32_e32 v76, 1.0, v76
	v_add_f32_e32 v58, 1.0, v58
	v_add_f32_e32 v77, 1.0, v77
	v_add_f32_e32 v59, 1.0, v59
	v_add_f32_e32 v78, 1.0, v78
	v_add_f32_e32 v60, 1.0, v60
	v_add_f32_e32 v79, 1.0, v79
	v_add_f32_e32 v61, 1.0, v61
	v_rcp_f32_e32 v76, v76
	v_rcp_f32_e32 v58, v58
	v_rcp_f32_e32 v77, v77
	v_rcp_f32_e32 v59, v59
	v_rcp_f32_e32 v78, v78
	v_rcp_f32_e32 v60, v60
	v_rcp_f32_e32 v79, v79
	v_rcp_f32_e32 v61, v61
	s_waitcnt vmcnt(8)
	v_lshlrev_b32_e32 v80, 16, v224
	v_and_b32_e32 v62, 0xffff0000, v224
	v_lshlrev_b32_e32 v81, 16, v225
	v_and_b32_e32 v63, 0xffff0000, v225
	v_lshlrev_b32_e32 v86, 16, v226
	v_and_b32_e32 v64, 0xffff0000, v226
	v_lshlrev_b32_e32 v87, 16, v227
	v_and_b32_e32 v65, 0xffff0000, v227
	s_mov_b64 s[98:99], 0x40000
	v_lshl_add_u64 v[248:249], v[252:253], 0, s[98:99]
	global_load_dwordx4 v[224:227], v[248:249], off offset:256
	v_fmac_f32_e32 v80, v54, v76
	v_fmac_f32_e32 v62, v55, v58
	v_fmac_f32_e32 v81, v56, v77
	v_fmac_f32_e32 v63, v57, v59
	v_fmac_f32_e32 v86, v50, v78
	v_fmac_f32_e32 v64, v51, v60
	v_fmac_f32_e32 v87, v52, v79
	v_fmac_f32_e32 v65, v53, v61
	v_cvt_pk_bf16_f32 v50, v80, v62
	v_cvt_pk_bf16_f32 v51, v81, v63
	v_cvt_pk_bf16_f32 v52, v86, v64
	v_cvt_pk_bf16_f32 v53, v87, v65
	global_store_dwordx4 v[130:131], v[50:53], off offset:256
	s_nop 0
	s_nop 0
	s_nop 0
	s_waitcnt vmcnt(8)
	v_lshlrev_b32_e32 v58, 16, v204
	v_and_b32_e32 v50, 0xffff0000, v204
	v_lshlrev_b32_e32 v59, 16, v205
	v_and_b32_e32 v51, 0xffff0000, v205
	v_lshlrev_b32_e32 v60, 16, v206
	v_and_b32_e32 v52, 0xffff0000, v206
	v_lshlrev_b32_e32 v61, 16, v207
	v_and_b32_e32 v53, 0xffff0000, v207
	s_mov_b64 s[98:99], 0x24000
	v_lshl_add_u64 v[248:249], v[250:251], 0, s[98:99]
	global_load_dwordx4 v[204:207], v[248:249], off offset:256
	v_add_f32_e32 v58, v70, v58
	v_add_f32_e32 v50, v71, v50
	v_add_f32_e32 v59, v72, v59
	v_add_f32_e32 v51, v73, v51
	v_add_f32_e32 v60, v66, v60
	v_add_f32_e32 v52, v67, v52
	v_add_f32_e32 v61, v68, v61
	v_add_f32_e32 v53, v69, v53
	v_mul_f32_e32 v58, 0xbfb8aa3b, v58
	v_mul_f32_e32 v50, 0xbfb8aa3b, v50
	v_mul_f32_e32 v59, 0xbfb8aa3b, v59
	v_mul_f32_e32 v51, 0xbfb8aa3b, v51
	v_mul_f32_e32 v60, 0xbfb8aa3b, v60
	v_mul_f32_e32 v52, 0xbfb8aa3b, v52
	v_mul_f32_e32 v61, 0xbfb8aa3b, v61
	v_mul_f32_e32 v53, 0xbfb8aa3b, v53
	v_exp_f32_e32 v58, v58
	v_exp_f32_e32 v50, v50
	v_exp_f32_e32 v59, v59
	v_exp_f32_e32 v51, v51
	v_exp_f32_e32 v60, v60
	v_exp_f32_e32 v52, v52
	v_exp_f32_e32 v61, v61
	v_exp_f32_e32 v53, v53
	v_add_f32_e32 v58, 1.0, v58
	v_add_f32_e32 v50, 1.0, v50
	v_add_f32_e32 v59, 1.0, v59
	v_add_f32_e32 v51, 1.0, v51
	v_add_f32_e32 v60, 1.0, v60
	v_add_f32_e32 v52, 1.0, v52
	v_add_f32_e32 v61, 1.0, v61
	v_add_f32_e32 v53, 1.0, v53
	v_rcp_f32_e32 v58, v58
	v_rcp_f32_e32 v50, v50
	v_rcp_f32_e32 v59, v59
	v_rcp_f32_e32 v51, v51
	v_rcp_f32_e32 v60, v60
	v_rcp_f32_e32 v52, v52
	v_rcp_f32_e32 v61, v61
	v_rcp_f32_e32 v53, v53
	s_waitcnt vmcnt(8)
; __device__ __forceinline__ unsigned cvt_pk_bf16(float lo, float hi) { unsigned r; asm volatile("v_cvt_pk_bf16_f32 %0, %1, %2" : "=v"(r) : "v"(lo), "v"(hi)); return r; }
; __device__ __forceinline__ float bflo(unsigned u) { return __uint_as_float(u << 16); }
; __device__ __forceinline__ float bfhi(unsigned u) { return __uint_as_float(u & 0xffff0000u); }
; __device__ __forceinline__ float sigm(float v) { return __builtin_amdgcn_rcpf(1.0f + __expf(-v)); }
; DI float bflo(unsigned u) { return __uint_as_float(u << 16); }
; DI float bfhi(unsigned u) { return __uint_as_float(u & 0xffff0000u); }
;     __device__ __forceinline__ void operator()(const f32x4 (&acc)[2][2][4][2], const Unit& u, int wr, int wc, int fr, int fq) const {
;     ...
;         for (int bj = 0; bj < 2; ++bj) {
;             const f32x4 b0 = *(const f32x4*)(gb + col0 + bj * HALF), b1 = *(const f32x4*)(gb + col0 + bj * HALF + 4);
; #pragma unroll
;             for (int ai = 0; ai < 2; ++ai)
; #pragma unroll
;                 for (int m = 0; m < 4; ++m) { const size_t row = (size_t)(row0 + ai * HALF + m * 16);
;                     const u32x4 g = *(const u32x4*)(gbase + row * 512 + gcol0 + bj * HALF);
;                     const f32x4 v0 = acc[ai][bj][m][0], v1 = acc[ai][bj][m][1];
;                     float r0 = v0[0] * sigm(bflo(g.x) + b0[0]), r1 = v0[1] * sigm(bfhi(g.x) + b0[1]), r2 = v0[2] * sigm(bflo(g.y) + b0[2]), r3 = v0[3] * sigm(bfhi(g.y) + b0[3]);
;                     float r4 = v1[0] * sigm(bflo(g.z) + b1[0]), r5 = v1[1] * sigm(bfhi(g.z) + b1[1]), r6 = v1[2] * sigm(bflo(g.w) + b1[2]), r7 = v1[3] * sigm(bfhi(g.w) + b1[3]);
;                     bf16_t* op = Mo + row * 1024 + col0 + bj * HALF;
;                     if (accum) { const u32x4 p = *(const u32x4*)op; r0 += bflo(p.x); r1 += bfhi(p.x); r2 += bflo(p.y); r3 += bfhi(p.y); r4 += bflo(p.z); r5 += bfhi(p.z); r6 += bflo(p.w); r7 += bfhi(p.w); }
;                     u32x4 w; w.x = cvt_pk_bf16(r0, r1); w.y = cvt_pk_bf16(r2, r3); w.z = cvt_pk_bf16(r4, r5); w.w = cvt_pk_bf16(r6, r7);
;                     *(u32x4*)op = w; }
	v_lshlrev_b32_e32 v62, 16, v216
	v_and_b32_e32 v54, 0xffff0000, v216
	v_lshlrev_b32_e32 v63, 16, v217
	v_and_b32_e32 v55, 0xffff0000, v217
	v_lshlrev_b32_e32 v64, 16, v218
	v_and_b32_e32 v56, 0xffff0000, v218
	v_lshlrev_b32_e32 v65, 16, v219
	v_and_b32_e32 v57, 0xffff0000, v219
	s_mov_b64 s[98:99], 0x48000
	v_lshl_add_u64 v[248:249], v[252:253], 0, s[98:99]
	global_load_dwordx4 v[216:219], v[248:249], off offset:256
	v_fmac_f32_e32 v62, v46, v58
	v_fmac_f32_e32 v54, v47, v50
	v_fmac_f32_e32 v63, v48, v59
	v_fmac_f32_e32 v55, v49, v51
	v_fmac_f32_e32 v64, v42, v60
	v_fmac_f32_e32 v56, v43, v52
	v_fmac_f32_e32 v65, v44, v61
	v_fmac_f32_e32 v57, v45, v53
	v_cvt_pk_bf16_f32 v42, v62, v54
	v_cvt_pk_bf16_f32 v43, v63, v55
	v_cvt_pk_bf16_f32 v44, v64, v56
	v_cvt_pk_bf16_f32 v45, v65, v57
	global_store_dwordx4 v[122:123], v[42:45], off offset:256
	s_nop 0
	s_nop 0
	s_nop 0
	s_waitcnt vmcnt(8)
	v_lshlrev_b32_e32 v50, 16, v208
	v_and_b32_e32 v42, 0xffff0000, v208
	v_lshlrev_b32_e32 v51, 16, v209
	v_and_b32_e32 v43, 0xffff0000, v209
	v_lshlrev_b32_e32 v52, 16, v210
	v_and_b32_e32 v44, 0xffff0000, v210
	v_lshlrev_b32_e32 v53, 16, v211
	v_and_b32_e32 v45, 0xffff0000, v211
	s_mov_b64 s[98:99], 0x28000
	v_lshl_add_u64 v[248:249], v[250:251], 0, s[98:99]
	global_load_dwordx4 v[208:211], v[248:249], off offset:256
	v_add_f32_e32 v50, v70, v50
	v_add_f32_e32 v42, v71, v42
	v_add_f32_e32 v51, v72, v51
	v_add_f32_e32 v43, v73, v43
	v_add_f32_e32 v52, v66, v52
	v_add_f32_e32 v44, v67, v44
	v_add_f32_e32 v53, v68, v53
	v_add_f32_e32 v45, v69, v45
	v_mul_f32_e32 v50, 0xbfb8aa3b, v50
	v_mul_f32_e32 v42, 0xbfb8aa3b, v42
	v_mul_f32_e32 v51, 0xbfb8aa3b, v51
	v_mul_f32_e32 v43, 0xbfb8aa3b, v43
	v_mul_f32_e32 v52, 0xbfb8aa3b, v52
	v_mul_f32_e32 v44, 0xbfb8aa3b, v44
	v_mul_f32_e32 v53, 0xbfb8aa3b, v53
	v_mul_f32_e32 v45, 0xbfb8aa3b, v45
	v_exp_f32_e32 v50, v50
	v_exp_f32_e32 v42, v42
	v_exp_f32_e32 v51, v51
	v_exp_f32_e32 v43, v43
	v_exp_f32_e32 v52, v52
	v_exp_f32_e32 v44, v44
	v_exp_f32_e32 v53, v53
	v_exp_f32_e32 v45, v45
	v_add_f32_e32 v50, 1.0, v50
	v_add_f32_e32 v42, 1.0, v42
	v_add_f32_e32 v51, 1.0, v51
	v_add_f32_e32 v43, 1.0, v43
	v_add_f32_e32 v52, 1.0, v52
	v_add_f32_e32 v44, 1.0, v44
	v_add_f32_e32 v53, 1.0, v53
	v_add_f32_e32 v45, 1.0, v45
	v_rcp_f32_e32 v50, v50
	v_rcp_f32_e32 v42, v42
	v_rcp_f32_e32 v51, v51
	v_rcp_f32_e32 v43, v43
	v_rcp_f32_e32 v52, v52
	v_rcp_f32_e32 v44, v44
	v_rcp_f32_e32 v53, v53
	v_rcp_f32_e32 v45, v45
	s_waitcnt vmcnt(8)
	v_lshlrev_b32_e32 v54, 16, v220
	v_and_b32_e32 v46, 0xffff0000, v220
	v_lshlrev_b32_e32 v55, 16, v221
	v_and_b32_e32 v47, 0xffff0000, v221
	v_lshlrev_b32_e32 v56, 16, v222
	v_and_b32_e32 v48, 0xffff0000, v222
	v_lshlrev_b32_e32 v57, 16, v223
	v_and_b32_e32 v49, 0xffff0000, v223
	s_mov_b64 s[98:99], 0x50000
	v_lshl_add_u64 v[248:249], v[252:253], 0, s[98:99]
	global_load_dwordx4 v[220:223], v[248:249], off offset:256
	v_fmac_f32_e32 v54, v38, v50
	v_fmac_f32_e32 v46, v39, v42
	v_fmac_f32_e32 v55, v40, v51
	v_fmac_f32_e32 v47, v41, v43
	v_fmac_f32_e32 v56, v34, v52
	v_fmac_f32_e32 v48, v35, v44
	v_fmac_f32_e32 v57, v36, v53
	v_fmac_f32_e32 v49, v37, v45
	v_cvt_pk_bf16_f32 v34, v54, v46
	v_cvt_pk_bf16_f32 v35, v55, v47
	v_cvt_pk_bf16_f32 v36, v56, v48
	v_cvt_pk_bf16_f32 v37, v57, v49
	global_store_dwordx4 v[106:107], v[34:37], off offset:256
	s_nop 0
	s_nop 0
	s_nop 0
	s_waitcnt vmcnt(8)
	v_lshlrev_b32_e32 v42, 16, v212
	v_and_b32_e32 v34, 0xffff0000, v212
	v_lshlrev_b32_e32 v43, 16, v213
	v_and_b32_e32 v35, 0xffff0000, v213
	v_lshlrev_b32_e32 v44, 16, v214
	v_and_b32_e32 v36, 0xffff0000, v214
	v_lshlrev_b32_e32 v45, 16, v215
	v_and_b32_e32 v37, 0xffff0000, v215
	s_mov_b64 s[98:99], 0x2c000
	v_lshl_add_u64 v[248:249], v[250:251], 0, s[98:99]
	global_load_dwordx4 v[212:215], v[248:249], off offset:256
	v_add_f32_e32 v42, v70, v42
	v_add_f32_e32 v34, v71, v34
	v_add_f32_e32 v43, v72, v43
	v_add_f32_e32 v35, v73, v35
	v_add_f32_e32 v44, v66, v44
	v_add_f32_e32 v36, v67, v36
	v_add_f32_e32 v45, v68, v45
	v_add_f32_e32 v37, v69, v37
	v_mul_f32_e32 v42, 0xbfb8aa3b, v42
	v_mul_f32_e32 v34, 0xbfb8aa3b, v34
	v_mul_f32_e32 v43, 0xbfb8aa3b, v43
	v_mul_f32_e32 v35, 0xbfb8aa3b, v35
	v_mul_f32_e32 v44, 0xbfb8aa3b, v44
	v_mul_f32_e32 v36, 0xbfb8aa3b, v36
	v_mul_f32_e32 v45, 0xbfb8aa3b, v45
	v_mul_f32_e32 v37, 0xbfb8aa3b, v37
	v_exp_f32_e32 v42, v42
	v_exp_f32_e32 v34, v34
	v_exp_f32_e32 v43, v43
	v_exp_f32_e32 v35, v35
	v_exp_f32_e32 v44, v44
	v_exp_f32_e32 v36, v36
	v_exp_f32_e32 v45, v45
	v_exp_f32_e32 v37, v37
	v_add_f32_e32 v42, 1.0, v42
	v_add_f32_e32 v34, 1.0, v34
	v_add_f32_e32 v43, 1.0, v43
	v_add_f32_e32 v35, 1.0, v35
	v_add_f32_e32 v44, 1.0, v44
	v_add_f32_e32 v36, 1.0, v36
	v_add_f32_e32 v45, 1.0, v45
	v_add_f32_e32 v37, 1.0, v37
	v_rcp_f32_e32 v42, v42
	v_rcp_f32_e32 v34, v34
	v_rcp_f32_e32 v43, v43
	v_rcp_f32_e32 v35, v35
	v_rcp_f32_e32 v44, v44
	v_rcp_f32_e32 v36, v36
	v_rcp_f32_e32 v45, v45
	v_rcp_f32_e32 v37, v37
	s_waitcnt vmcnt(8)
	v_lshlrev_b32_e32 v46, 16, v224
	v_and_b32_e32 v38, 0xffff0000, v224
	v_lshlrev_b32_e32 v47, 16, v225
	v_and_b32_e32 v39, 0xffff0000, v225
	v_lshlrev_b32_e32 v48, 16, v226
	v_and_b32_e32 v40, 0xffff0000, v226
	v_lshlrev_b32_e32 v49, 16, v227
	v_and_b32_e32 v41, 0xffff0000, v227
	s_mov_b64 s[98:99], 0x58000
	v_lshl_add_u64 v[248:249], v[252:253], 0, s[98:99]
	global_load_dwordx4 v[224:227], v[248:249], off offset:256
	v_fmac_f32_e32 v46, v30, v42
	v_fmac_f32_e32 v38, v31, v34
	v_fmac_f32_e32 v47, v32, v43
	v_fmac_f32_e32 v39, v33, v35
	v_fmac_f32_e32 v48, v26, v44
	v_fmac_f32_e32 v40, v27, v36
	v_fmac_f32_e32 v49, v28, v45
	v_fmac_f32_e32 v41, v29, v37
	v_cvt_pk_bf16_f32 v26, v46, v38
	v_cvt_pk_bf16_f32 v27, v47, v39
	v_cvt_pk_bf16_f32 v28, v48, v40
	v_cvt_pk_bf16_f32 v29, v49, v41
	global_store_dwordx4 v[98:99], v[26:29], off offset:256
	s_nop 0
	s_nop 0
	s_nop 0
	s_waitcnt vmcnt(8)
; __device__ __forceinline__ unsigned cvt_pk_bf16(float lo, float hi) { unsigned r; asm volatile("v_cvt_pk_bf16_f32 %0, %1, %2" : "=v"(r) : "v"(lo), "v"(hi)); return r; }
; __device__ __forceinline__ float bflo(unsigned u) { return __uint_as_float(u << 16); }
; __device__ __forceinline__ float bfhi(unsigned u) { return __uint_as_float(u & 0xffff0000u); }
; __device__ __forceinline__ float sigm(float v) { return __builtin_amdgcn_rcpf(1.0f + __expf(-v)); }
; DI float bflo(unsigned u) { return __uint_as_float(u << 16); }
; DI float bfhi(unsigned u) { return __uint_as_float(u & 0xffff0000u); }
;     __device__ __forceinline__ void operator()(const f32x4 (&acc)[2][2][4][2], const Unit& u, int wr, int wc, int fr, int fq) const {
;     ...
;                 for (int m = 0; m < 4; ++m) { const size_t row = (size_t)(row0 + ai * HALF + m * 16);
;                     const u32x4 g = *(const u32x4*)(gbase + row * 512 + gcol0 + bj * HALF);
;                     const f32x4 v0 = acc[ai][bj][m][0], v1 = acc[ai][bj][m][1];
;                     float r0 = v0[0] * sigm(bflo(g.x) + b0[0]), r1 = v0[1] * sigm(bfhi(g.x) + b0[1]), r2 = v0[2] * sigm(bflo(g.y) + b0[2]), r3 = v0[3] * sigm(bfhi(g.y) + b0[3]);
;                     float r4 = v1[0] * sigm(bflo(g.z) + b1[0]), r5 = v1[1] * sigm(bfhi(g.z) + b1[1]), r6 = v1[2] * sigm(bflo(g.w) + b1[2]), r7 = v1[3] * sigm(bfhi(g.w) + b1[3]);
;                     bf16_t* op = Mo + row * 1024 + col0 + bj * HALF;
;                     if (accum) { const u32x4 p = *(const u32x4*)op; r0 += bflo(p.x); r1 += bfhi(p.x); r2 += bflo(p.y); r3 += bfhi(p.y); r4 += bflo(p.z); r5 += bfhi(p.z); r6 += bflo(p.w); r7 += bfhi(p.w); }
;                     u32x4 w; w.x = cvt_pk_bf16(r0, r1); w.y = cvt_pk_bf16(r2, r3); w.z = cvt_pk_bf16(r4, r5); w.w = cvt_pk_bf16(r6, r7);
;                     *(u32x4*)op = w; }
	v_lshlrev_b32_e32 v34, 16, v204
	v_and_b32_e32 v26, 0xffff0000, v204
	v_lshlrev_b32_e32 v35, 16, v205
	v_and_b32_e32 v27, 0xffff0000, v205
	v_lshlrev_b32_e32 v36, 16, v206
	v_and_b32_e32 v28, 0xffff0000, v206
	v_lshlrev_b32_e32 v37, 16, v207
	v_and_b32_e32 v29, 0xffff0000, v207
	v_add_f32_e32 v34, v70, v34
	v_add_f32_e32 v26, v71, v26
	v_add_f32_e32 v35, v72, v35
	v_add_f32_e32 v27, v73, v27
	v_add_f32_e32 v36, v66, v36
	v_add_f32_e32 v28, v67, v28
	v_add_f32_e32 v37, v68, v37
	v_add_f32_e32 v29, v69, v29
	v_mul_f32_e32 v34, 0xbfb8aa3b, v34
	v_mul_f32_e32 v26, 0xbfb8aa3b, v26
	v_mul_f32_e32 v35, 0xbfb8aa3b, v35
	v_mul_f32_e32 v27, 0xbfb8aa3b, v27
	v_mul_f32_e32 v36, 0xbfb8aa3b, v36
	v_mul_f32_e32 v28, 0xbfb8aa3b, v28
	v_mul_f32_e32 v37, 0xbfb8aa3b, v37
	v_mul_f32_e32 v29, 0xbfb8aa3b, v29
	v_exp_f32_e32 v34, v34
	v_exp_f32_e32 v26, v26
	v_exp_f32_e32 v35, v35
	v_exp_f32_e32 v27, v27
	v_exp_f32_e32 v36, v36
	v_exp_f32_e32 v28, v28
	v_exp_f32_e32 v37, v37
	v_exp_f32_e32 v29, v29
	v_add_f32_e32 v34, 1.0, v34
	v_add_f32_e32 v26, 1.0, v26
	v_add_f32_e32 v35, 1.0, v35
	v_add_f32_e32 v27, 1.0, v27
	v_add_f32_e32 v36, 1.0, v36
	v_add_f32_e32 v28, 1.0, v28
	v_add_f32_e32 v37, 1.0, v37
	v_add_f32_e32 v29, 1.0, v29
	v_rcp_f32_e32 v34, v34
	v_rcp_f32_e32 v26, v26
	v_rcp_f32_e32 v35, v35
	v_rcp_f32_e32 v27, v27
	v_rcp_f32_e32 v36, v36
	v_rcp_f32_e32 v28, v28
	v_rcp_f32_e32 v37, v37
	v_rcp_f32_e32 v29, v29
	s_waitcnt vmcnt(7)
	v_lshlrev_b32_e32 v38, 16, v216
	v_and_b32_e32 v30, 0xffff0000, v216
	v_lshlrev_b32_e32 v39, 16, v217
	v_and_b32_e32 v31, 0xffff0000, v217
	v_lshlrev_b32_e32 v40, 16, v218
	v_and_b32_e32 v32, 0xffff0000, v218
	v_lshlrev_b32_e32 v41, 16, v219
	v_and_b32_e32 v33, 0xffff0000, v219
	v_fmac_f32_e32 v38, v22, v34
	v_fmac_f32_e32 v30, v23, v26
	v_fmac_f32_e32 v39, v24, v35
	v_fmac_f32_e32 v31, v25, v27
	v_fmac_f32_e32 v40, v18, v36
	v_fmac_f32_e32 v32, v19, v28
	v_fmac_f32_e32 v41, v20, v37
	v_fmac_f32_e32 v33, v21, v29
	v_cvt_pk_bf16_f32 v18, v38, v30
	v_cvt_pk_bf16_f32 v19, v39, v31
	v_cvt_pk_bf16_f32 v20, v40, v32
	v_cvt_pk_bf16_f32 v21, v41, v33
	global_store_dwordx4 v[90:91], v[18:21], off offset:256
	s_nop 0
	s_nop 0
	s_nop 0
	s_waitcnt vmcnt(6)
	v_lshlrev_b32_e32 v26, 16, v208
	v_and_b32_e32 v18, 0xffff0000, v208
	v_lshlrev_b32_e32 v27, 16, v209
	v_and_b32_e32 v19, 0xffff0000, v209
	v_lshlrev_b32_e32 v28, 16, v210
	v_and_b32_e32 v20, 0xffff0000, v210
	v_lshlrev_b32_e32 v29, 16, v211
	v_and_b32_e32 v21, 0xffff0000, v211
	v_add_f32_e32 v26, v70, v26
	v_add_f32_e32 v18, v71, v18
	v_add_f32_e32 v27, v72, v27
	v_add_f32_e32 v19, v73, v19
	v_add_f32_e32 v28, v66, v28
	v_add_f32_e32 v20, v67, v20
	v_add_f32_e32 v29, v68, v29
	v_add_f32_e32 v21, v69, v21
	v_mul_f32_e32 v26, 0xbfb8aa3b, v26
	v_mul_f32_e32 v18, 0xbfb8aa3b, v18
	v_mul_f32_e32 v27, 0xbfb8aa3b, v27
	v_mul_f32_e32 v19, 0xbfb8aa3b, v19
	v_mul_f32_e32 v28, 0xbfb8aa3b, v28
	v_mul_f32_e32 v20, 0xbfb8aa3b, v20
	v_mul_f32_e32 v29, 0xbfb8aa3b, v29
	v_mul_f32_e32 v21, 0xbfb8aa3b, v21
	v_exp_f32_e32 v26, v26
	v_exp_f32_e32 v18, v18
	v_exp_f32_e32 v27, v27
	v_exp_f32_e32 v19, v19
	v_exp_f32_e32 v28, v28
	v_exp_f32_e32 v20, v20
	v_exp_f32_e32 v29, v29
	v_exp_f32_e32 v21, v21
	v_add_f32_e32 v26, 1.0, v26
	v_add_f32_e32 v18, 1.0, v18
	v_add_f32_e32 v27, 1.0, v27
	v_add_f32_e32 v19, 1.0, v19
	v_add_f32_e32 v28, 1.0, v28
	v_add_f32_e32 v20, 1.0, v20
	v_add_f32_e32 v29, 1.0, v29
	v_add_f32_e32 v21, 1.0, v21
	v_rcp_f32_e32 v26, v26
	v_rcp_f32_e32 v18, v18
	v_rcp_f32_e32 v27, v27
	v_rcp_f32_e32 v19, v19
	v_rcp_f32_e32 v28, v28
	v_rcp_f32_e32 v20, v20
	v_rcp_f32_e32 v29, v29
	v_rcp_f32_e32 v21, v21
	s_waitcnt vmcnt(5)
	v_lshlrev_b32_e32 v30, 16, v220
	v_and_b32_e32 v22, 0xffff0000, v220
	v_lshlrev_b32_e32 v31, 16, v221
	v_and_b32_e32 v23, 0xffff0000, v221
	v_lshlrev_b32_e32 v32, 16, v222
	v_and_b32_e32 v24, 0xffff0000, v222
	v_lshlrev_b32_e32 v33, 16, v223
	v_and_b32_e32 v25, 0xffff0000, v223
	v_fmac_f32_e32 v30, v14, v26
	v_fmac_f32_e32 v22, v15, v18
	v_fmac_f32_e32 v31, v16, v27
	v_fmac_f32_e32 v23, v17, v19
	v_fmac_f32_e32 v32, v10, v28
	v_fmac_f32_e32 v24, v11, v20
	v_fmac_f32_e32 v33, v12, v29
	v_fmac_f32_e32 v25, v13, v21
	v_cvt_pk_bf16_f32 v10, v30, v22
	v_cvt_pk_bf16_f32 v11, v31, v23
	v_cvt_pk_bf16_f32 v12, v32, v24
	v_cvt_pk_bf16_f32 v13, v33, v25
	global_store_dwordx4 v[82:83], v[10:13], off offset:256
	s_nop 0
	s_nop 0
	s_nop 0
	s_waitcnt vmcnt(4)
	v_lshlrev_b32_e32 v18, 16, v212
	v_and_b32_e32 v10, 0xffff0000, v212
	v_lshlrev_b32_e32 v19, 16, v213
	v_and_b32_e32 v11, 0xffff0000, v213
	v_lshlrev_b32_e32 v20, 16, v214
	v_and_b32_e32 v12, 0xffff0000, v214
	v_lshlrev_b32_e32 v21, 16, v215
	v_and_b32_e32 v13, 0xffff0000, v215
	v_add_f32_e32 v18, v70, v18
	v_add_f32_e32 v10, v71, v10
	v_add_f32_e32 v19, v72, v19
	v_add_f32_e32 v11, v73, v11
	v_add_f32_e32 v20, v66, v20
	v_add_f32_e32 v12, v67, v12
	v_add_f32_e32 v21, v68, v21
	v_add_f32_e32 v13, v69, v13
	v_mul_f32_e32 v18, 0xbfb8aa3b, v18
	v_mul_f32_e32 v10, 0xbfb8aa3b, v10
	v_mul_f32_e32 v19, 0xbfb8aa3b, v19
	v_mul_f32_e32 v11, 0xbfb8aa3b, v11
	v_mul_f32_e32 v20, 0xbfb8aa3b, v20
	v_mul_f32_e32 v12, 0xbfb8aa3b, v12
	v_mul_f32_e32 v21, 0xbfb8aa3b, v21
	v_mul_f32_e32 v13, 0xbfb8aa3b, v13
	v_exp_f32_e32 v18, v18
	v_exp_f32_e32 v10, v10
	v_exp_f32_e32 v19, v19
	v_exp_f32_e32 v11, v11
	v_exp_f32_e32 v20, v20
	v_exp_f32_e32 v12, v12
	v_exp_f32_e32 v21, v21
	v_exp_f32_e32 v13, v13
	v_add_f32_e32 v18, 1.0, v18
	v_add_f32_e32 v10, 1.0, v10
	v_add_f32_e32 v19, 1.0, v19
	v_add_f32_e32 v11, 1.0, v11
	v_add_f32_e32 v20, 1.0, v20
	v_add_f32_e32 v12, 1.0, v12
	v_add_f32_e32 v21, 1.0, v21
	v_add_f32_e32 v13, 1.0, v13
	v_rcp_f32_e32 v18, v18
	v_rcp_f32_e32 v10, v10
	v_rcp_f32_e32 v19, v19
	v_rcp_f32_e32 v11, v11
	v_rcp_f32_e32 v20, v20
	v_rcp_f32_e32 v12, v12
	v_rcp_f32_e32 v21, v21
	v_rcp_f32_e32 v13, v13
	s_waitcnt vmcnt(3)
	v_lshlrev_b32_e32 v22, 16, v224
	v_and_b32_e32 v14, 0xffff0000, v224
	v_lshlrev_b32_e32 v23, 16, v225
	v_and_b32_e32 v15, 0xffff0000, v225
	v_lshlrev_b32_e32 v24, 16, v226
	v_and_b32_e32 v16, 0xffff0000, v226
	v_lshlrev_b32_e32 v25, 16, v227
	v_and_b32_e32 v17, 0xffff0000, v227
	v_fmac_f32_e32 v22, v6, v18
	v_fmac_f32_e32 v14, v7, v10
	v_fmac_f32_e32 v23, v8, v19
	v_fmac_f32_e32 v15, v9, v11
	v_fmac_f32_e32 v24, v2, v20
	v_fmac_f32_e32 v16, v3, v12
	v_fmac_f32_e32 v25, v4, v21
	v_fmac_f32_e32 v17, v5, v13
	v_cvt_pk_bf16_f32 v2, v22, v14
	v_cvt_pk_bf16_f32 v3, v23, v15
	v_cvt_pk_bf16_f32 v4, v24, v16
	v_cvt_pk_bf16_f32 v5, v25, v17
	global_store_dwordx4 v[74:75], v[2:5], off offset:256

; __device__ __forceinline__ unsigned cvt_pk_bf16(float lo, float hi) { unsigned r; asm volatile("v_cvt_pk_bf16_f32 %0, %1, %2" : "=v"(r) : "v"(lo), "v"(hi)); return r; }
; __device__ __forceinline__ float bflo(unsigned u) { return __uint_as_float(u << 16); }
; __device__ __forceinline__ float bfhi(unsigned u) { return __uint_as_float(u & 0xffff0000u); }
; __device__ __forceinline__ float sigm(float v) { return __builtin_amdgcn_rcpf(1.0f + __expf(-v)); }
; DI float bflo(unsigned u) { return __uint_as_float(u << 16); }
; DI float bfhi(unsigned u) { return __uint_as_float(u & 0xffff0000u); }
;     __device__ __forceinline__ void operator()(const f32x4 (&acc)[2][2][4][2], const Unit& u, int wr, int wc, int fr, int fq) const {
;         const int row0 = u.pm * BM + wr * 64 + fr; const int colt = u.pn * BM; const int t = colt / 512;
;         const bf16_t* gbase = G0 + (size_t)t * split_stride; const int col0 = colt + wc * 32 + 8 * fq, gcol0 = col0 - t * 512;
; #pragma unroll
;         for (int bj = 0; bj < 2; ++bj) {
;             const f32x4 b0 = *(const f32x4*)(gb + col0 + bj * HALF), b1 = *(const f32x4*)(gb + col0 + bj * HALF + 4);
; #pragma unroll
;             for (int ai = 0; ai < 2; ++ai)
; #pragma unroll
;                 for (int m = 0; m < 4; ++m) { const size_t row = (size_t)(row0 + ai * HALF + m * 16);
;                     const u32x4 g = *(const u32x4*)(gbase + row * 512 + gcol0 + bj * HALF);
;                     const f32x4 v0 = acc[ai][bj][m][0], v1 = acc[ai][bj][m][1];
;                     float r0 = v0[0] * sigm(bflo(g.x) + b0[0]), r1 = v0[1] * sigm(bfhi(g.x) + b0[1]), r2 = v0[2] * sigm(bflo(g.y) + b0[2]), r3 = v0[3] * sigm(bfhi(g.y) + b0[3]);
;                     float r4 = v1[0] * sigm(bflo(g.z) + b1[0]), r5 = v1[1] * sigm(bfhi(g.z) + b1[1]), r6 = v1[2] * sigm(bflo(g.w) + b1[2]), r7 = v1[3] * sigm(bfhi(g.w) + b1[3]);
;                     bf16_t* op = Mo + row * 1024 + col0 + bj * HALF;
;                     if (accum) { const u32x4 p = *(const u32x4*)op; r0 += bflo(p.x); r1 += bfhi(p.x); r2 += bflo(p.y); r3 += bfhi(p.y); r4 += bflo(p.z); r5 += bfhi(p.z); r6 += bflo(p.w); r7 += bfhi(p.w); }
;                     u32x4 w; w.x = cvt_pk_bf16(r0, r1); w.y = cvt_pk_bf16(r2, r3); w.z = cvt_pk_bf16(r4, r5); w.w = cvt_pk_bf16(r6, r7);
;                     *(u32x4*)op = w; }
.Lg2n_start:
	s_lshr_b32 s2, s48, 31
	s_add_i32 s2, s48, s2
	s_ashr_i32 s26, s2, 1
	s_ashr_i32 s27, s26, 31
	s_lshl_b64 s[28:29], s[26:27], 24
	s_add_u32 s28, s40, s28
	s_addc_u32 s29, s41, s29
	v_lshl_or_b32 v114, s48, 8, v172
	s_lshl_b32 s2, s26, 9
	v_lshl_add_u32 v168, s24, 8, v1
	v_subrev_u32_e32 v116, s2, v114
	v_ashrrev_i32_e32 v117, 31, v116
	v_ashrrev_i32_e32 v169, 31, v168
	v_lshl_add_u64 v[170:171], v[116:117], 1, s[28:29]
	v_lshlrev_b64 v[116:117], 10, v[168:169]
	v_lshl_add_u64 v[158:159], v[170:171], 0, v[116:117]
	v_ashrrev_i32_e32 v115, 31, v114
	v_lshlrev_b64 v[116:117], 11, v[168:169]
	v_lshl_add_u64 v[116:117], s[10:11], 0, v[116:117]
	v_lshlrev_b64 v[166:167], 1, v[114:115]
	v_lshl_add_u64 v[154:155], v[116:117], 0, v[166:167]
	v_lshl_add_u64 v[160:161], v[114:115], 2, s[4:5]
	v_or_b32_e32 v184, 16, v168
	v_ashrrev_i32_e32 v185, 31, v184
	v_lshlrev_b64 v[156:157], 10, v[184:185]
	v_lshl_add_u64 v[156:157], v[170:171], 0, v[156:157]
	s_andn2_b64 vcc, exec, s[6:7]
	s_mov_b64 s[6:7], -1
	v_mov_b32_e32 v250, v158
	v_mov_b32_e32 v251, v159
	v_mov_b32_e32 v252, v154
	v_mov_b32_e32 v253, v155
	v_mov_b32_e32 v246, v160
	v_mov_b32_e32 v247, v161
	v_mov_b32_e32 v244, 0xbfb8aa3b
	v_mov_b32_e32 v245, 0xbfb8aa3b
	v_mov_b32_e32 v248, 0x5d800000
	v_mov_b32_e32 v249, 0x5d800000
	v_mov_b32_e32 v242, 1.0
	v_mov_b32_e32 v243, 1.0
	global_load_dwordx4 v[114:117], v[246:247], off
	global_load_dwordx4 v[118:121], v[246:247], off offset:16
	s_mov_b64 s[98:99], 0x200
	v_lshl_add_u64 v[254:255], v[246:247], 0, s[98:99]
	global_load_dwordx4 v[154:157], v[254:255], off
	global_load_dwordx4 v[158:161], v[254:255], off offset:16
	global_load_dwordx4 v[204:207], v[250:251], off
	s_mov_b64 s[98:99], 0x4000
	v_lshl_add_u64 v[254:255], v[250:251], 0, s[98:99]
	global_load_dwordx4 v[208:211], v[254:255], off
	s_mov_b64 s[98:99], 0x8000
	v_lshl_add_u64 v[254:255], v[250:251], 0, s[98:99]
	global_load_dwordx4 v[212:215], v[254:255], off
	s_mov_b64 s[98:99], 0xc000
	v_lshl_add_u64 v[254:255], v[250:251], 0, s[98:99]
	global_load_dwordx4 v[216:219], v[254:255], off
	s_mov_b64 s[98:99], 0x20000
	v_lshl_add_u64 v[254:255], v[250:251], 0, s[98:99]
	global_load_dwordx4 v[220:223], v[254:255], off
	s_mov_b64 s[98:99], 0x24000
	v_lshl_add_u64 v[254:255], v[250:251], 0, s[98:99]
	global_load_dwordx4 v[224:227], v[254:255], off
	s_mov_b64 s[98:99], 0x28000
	v_lshl_add_u64 v[254:255], v[250:251], 0, s[98:99]
	global_load_dwordx4 v[192:195], v[254:255], off
	s_mov_b64 s[98:99], 0x2c000
	v_lshl_add_u64 v[254:255], v[250:251], 0, s[98:99]
	global_load_dwordx4 v[188:191], v[254:255], off
	global_load_dwordx4 v[184:187], v[250:251], off offset:256
	s_waitcnt vmcnt(8)
	v_lshlrev_b32_e32 v240, 16, v204
	v_and_b32_e32 v241, 0xffff0000, v204
	v_pk_add_f32 v[240:241], v[240:241], v[114:115]
	v_pk_mul_f32 v[240:241], v[240:241], v[244:245]
	v_exp_f32_e32 v240, v240
	v_exp_f32_e32 v241, v241
	s_nop 0
	v_min_f32_e32 v240, v240, v248
	v_min_f32_e32 v241, v241, v248
	v_pk_add_f32 v[240:241], v[240:241], v[242:243]
	v_rcp_f32_e32 v240, v240
	v_rcp_f32_e32 v241, v241
	s_nop 0
	v_pk_mul_f32 v[240:241], v[240:241], v[134:135]
	v_cvt_pk_bf16_f32 v176, v240, v241
	v_lshlrev_b32_e32 v240, 16, v205
	v_and_b32_e32 v241, 0xffff0000, v205
	v_pk_add_f32 v[240:241], v[240:241], v[116:117]
	v_pk_mul_f32 v[240:241], v[240:241], v[244:245]
	v_exp_f32_e32 v240, v240
	v_exp_f32_e32 v241, v241
	s_nop 0
	v_min_f32_e32 v240, v240, v248
	v_min_f32_e32 v241, v241, v248
	v_pk_add_f32 v[240:241], v[240:241], v[242:243]
	v_rcp_f32_e32 v240, v240
	v_rcp_f32_e32 v241, v241
	s_nop 0
	v_pk_mul_f32 v[240:241], v[240:241], v[136:137]
	v_cvt_pk_bf16_f32 v177, v240, v241
	v_lshlrev_b32_e32 v240, 16, v206
	v_and_b32_e32 v241, 0xffff0000, v206
	v_pk_add_f32 v[240:241], v[240:241], v[118:119]
	v_pk_mul_f32 v[240:241], v[240:241], v[244:245]
	v_exp_f32_e32 v240, v240
	v_exp_f32_e32 v241, v241
	s_nop 0
	v_min_f32_e32 v240, v240, v248
	v_min_f32_e32 v241, v241, v248
	v_pk_add_f32 v[240:241], v[240:241], v[242:243]
	v_rcp_f32_e32 v240, v240
	v_rcp_f32_e32 v241, v241
	s_nop 0
	v_pk_mul_f32 v[240:241], v[240:241], v[130:131]
	v_cvt_pk_bf16_f32 v178, v240, v241
	v_lshlrev_b32_e32 v240, 16, v207
	v_and_b32_e32 v241, 0xffff0000, v207
	s_mov_b64 s[98:99], 0x4000
	v_lshl_add_u64 v[254:255], v[250:251], 0, s[98:99]
	global_load_dwordx4 v[204:207], v[254:255], off offset:256
	v_pk_add_f32 v[240:241], v[240:241], v[120:121]
	v_pk_mul_f32 v[240:241], v[240:241], v[244:245]
	v_exp_f32_e32 v240, v240
	v_exp_f32_e32 v241, v241
	s_nop 0
	v_min_f32_e32 v240, v240, v248
	v_min_f32_e32 v241, v241, v248
	v_pk_add_f32 v[240:241], v[240:241], v[242:243]
	v_rcp_f32_e32 v240, v240
	v_rcp_f32_e32 v241, v241
	s_nop 0
	v_pk_mul_f32 v[240:241], v[240:241], v[132:133]
	v_cvt_pk_bf16_f32 v179, v240, v241
	global_store_dwordx4 v[252:253], v[176:179], off
	s_waitcnt vmcnt(9)
; __device__ __forceinline__ unsigned cvt_pk_bf16(float lo, float hi) { unsigned r; asm volatile("v_cvt_pk_bf16_f32 %0, %1, %2" : "=v"(r) : "v"(lo), "v"(hi)); return r; }
; __device__ __forceinline__ float bflo(unsigned u) { return __uint_as_float(u << 16); }
; __device__ __forceinline__ float bfhi(unsigned u) { return __uint_as_float(u & 0xffff0000u); }
; __device__ __forceinline__ float sigm(float v) { return __builtin_amdgcn_rcpf(1.0f + __expf(-v)); }
; DI float bflo(unsigned u) { return __uint_as_float(u << 16); }
; DI float bfhi(unsigned u) { return __uint_as_float(u & 0xffff0000u); }
;     __device__ __forceinline__ void operator()(const f32x4 (&acc)[2][2][4][2], const Unit& u, int wr, int wc, int fr, int fq) const {
;         const int row0 = u.pm * BM + wr * 64 + fr; const int colt = u.pn * BM; const int t = colt / 512;
;         const bf16_t* gbase = G0 + (size_t)t * split_stride; const int col0 = colt + wc * 32 + 8 * fq, gcol0 = col0 - t * 512;
; #pragma unroll
;         for (int bj = 0; bj < 2; ++bj) {
;             const f32x4 b0 = *(const f32x4*)(gb + col0 + bj * HALF), b1 = *(const f32x4*)(gb + col0 + bj * HALF + 4);
; #pragma unroll
;             for (int ai = 0; ai < 2; ++ai)
; #pragma unroll
;                 for (int m = 0; m < 4; ++m) { const size_t row = (size_t)(row0 + ai * HALF + m * 16);
;                     const u32x4 g = *(const u32x4*)(gbase + row * 512 + gcol0 + bj * HALF);
;                     const f32x4 v0 = acc[ai][bj][m][0], v1 = acc[ai][bj][m][1];
;                     float r0 = v0[0] * sigm(bflo(g.x) + b0[0]), r1 = v0[1] * sigm(bfhi(g.x) + b0[1]), r2 = v0[2] * sigm(bflo(g.y) + b0[2]), r3 = v0[3] * sigm(bfhi(g.y) + b0[3]);
;                     float r4 = v1[0] * sigm(bflo(g.z) + b1[0]), r5 = v1[1] * sigm(bfhi(g.z) + b1[1]), r6 = v1[2] * sigm(bflo(g.w) + b1[2]), r7 = v1[3] * sigm(bfhi(g.w) + b1[3]);
;                     bf16_t* op = Mo + row * 1024 + col0 + bj * HALF;
;                     if (accum) { const u32x4 p = *(const u32x4*)op; r0 += bflo(p.x); r1 += bfhi(p.x); r2 += bflo(p.y); r3 += bfhi(p.y); r4 += bflo(p.z); r5 += bfhi(p.z); r6 += bflo(p.w); r7 += bfhi(p.w); }
;                     u32x4 w; w.x = cvt_pk_bf16(r0, r1); w.y = cvt_pk_bf16(r2, r3); w.z = cvt_pk_bf16(r4, r5); w.w = cvt_pk_bf16(r6, r7);
;                     *(u32x4*)op = w; }
	v_lshlrev_b32_e32 v240, 16, v208
	v_and_b32_e32 v241, 0xffff0000, v208
	v_pk_add_f32 v[240:241], v[240:241], v[114:115]
	v_pk_mul_f32 v[240:241], v[240:241], v[244:245]
	v_exp_f32_e32 v240, v240
	v_exp_f32_e32 v241, v241
	s_nop 0
	v_min_f32_e32 v240, v240, v248
	v_min_f32_e32 v241, v241, v248
	v_pk_add_f32 v[240:241], v[240:241], v[242:243]
	v_rcp_f32_e32 v240, v240
	v_rcp_f32_e32 v241, v241
	s_nop 0
	v_pk_mul_f32 v[240:241], v[240:241], v[126:127]
	v_cvt_pk_bf16_f32 v176, v240, v241
	v_lshlrev_b32_e32 v240, 16, v209
	v_and_b32_e32 v241, 0xffff0000, v209
	v_pk_add_f32 v[240:241], v[240:241], v[116:117]
	v_pk_mul_f32 v[240:241], v[240:241], v[244:245]
	v_exp_f32_e32 v240, v240
	v_exp_f32_e32 v241, v241
	s_nop 0
	v_min_f32_e32 v240, v240, v248
	v_min_f32_e32 v241, v241, v248
	v_pk_add_f32 v[240:241], v[240:241], v[242:243]
	v_rcp_f32_e32 v240, v240
	v_rcp_f32_e32 v241, v241
	s_nop 0
	v_pk_mul_f32 v[240:241], v[240:241], v[128:129]
	v_cvt_pk_bf16_f32 v177, v240, v241
	v_lshlrev_b32_e32 v240, 16, v210
	v_and_b32_e32 v241, 0xffff0000, v210
	v_pk_add_f32 v[240:241], v[240:241], v[118:119]
	v_pk_mul_f32 v[240:241], v[240:241], v[244:245]
	v_exp_f32_e32 v240, v240
	v_exp_f32_e32 v241, v241
	s_nop 0
	v_min_f32_e32 v240, v240, v248
	v_min_f32_e32 v241, v241, v248
	v_pk_add_f32 v[240:241], v[240:241], v[242:243]
	v_rcp_f32_e32 v240, v240
	v_rcp_f32_e32 v241, v241
	s_nop 0
	v_pk_mul_f32 v[240:241], v[240:241], v[122:123]
	v_cvt_pk_bf16_f32 v178, v240, v241
	v_lshlrev_b32_e32 v240, 16, v211
	v_and_b32_e32 v241, 0xffff0000, v211
	s_mov_b64 s[98:99], 0x8000
	v_lshl_add_u64 v[254:255], v[250:251], 0, s[98:99]
	global_load_dwordx4 v[208:211], v[254:255], off offset:256
	v_pk_add_f32 v[240:241], v[240:241], v[120:121]
	v_pk_mul_f32 v[240:241], v[240:241], v[244:245]
	v_exp_f32_e32 v240, v240
	v_exp_f32_e32 v241, v241
	s_nop 0
	v_min_f32_e32 v240, v240, v248
	v_min_f32_e32 v241, v241, v248
	v_pk_add_f32 v[240:241], v[240:241], v[242:243]
	v_rcp_f32_e32 v240, v240
	v_rcp_f32_e32 v241, v241
	s_nop 0
	v_pk_mul_f32 v[240:241], v[240:241], v[124:125]
	v_cvt_pk_bf16_f32 v179, v240, v241
	s_mov_b64 s[98:99], 0x8000
	v_lshl_add_u64 v[254:255], v[252:253], 0, s[98:99]
	global_store_dwordx4 v[254:255], v[176:179], off
	s_waitcnt vmcnt(10)
	v_lshlrev_b32_e32 v240, 16, v212
	v_and_b32_e32 v241, 0xffff0000, v212
	v_pk_add_f32 v[240:241], v[240:241], v[114:115]
	v_pk_mul_f32 v[240:241], v[240:241], v[244:245]
	v_exp_f32_e32 v240, v240
	v_exp_f32_e32 v241, v241
	s_nop 0
	v_min_f32_e32 v240, v240, v248
	v_min_f32_e32 v241, v241, v248
	v_pk_add_f32 v[240:241], v[240:241], v[242:243]
	v_rcp_f32_e32 v240, v240
	v_rcp_f32_e32 v241, v241
	s_nop 0
	v_pk_mul_f32 v[240:241], v[240:241], v[110:111]
	v_cvt_pk_bf16_f32 v176, v240, v241
	v_lshlrev_b32_e32 v240, 16, v213
	v_and_b32_e32 v241, 0xffff0000, v213
	v_pk_add_f32 v[240:241], v[240:241], v[116:117]
	v_pk_mul_f32 v[240:241], v[240:241], v[244:245]
	v_exp_f32_e32 v240, v240
	v_exp_f32_e32 v241, v241
	s_nop 0
	v_min_f32_e32 v240, v240, v248
	v_min_f32_e32 v241, v241, v248
	v_pk_add_f32 v[240:241], v[240:241], v[242:243]
	v_rcp_f32_e32 v240, v240
	v_rcp_f32_e32 v241, v241
	s_nop 0
	v_pk_mul_f32 v[240:241], v[240:241], v[112:113]
	v_cvt_pk_bf16_f32 v177, v240, v241
	v_lshlrev_b32_e32 v240, 16, v214
	v_and_b32_e32 v241, 0xffff0000, v214
	v_pk_add_f32 v[240:241], v[240:241], v[118:119]
	v_pk_mul_f32 v[240:241], v[240:241], v[244:245]
	v_exp_f32_e32 v240, v240
	v_exp_f32_e32 v241, v241
	s_nop 0
	v_min_f32_e32 v240, v240, v248
	v_min_f32_e32 v241, v241, v248
	v_pk_add_f32 v[240:241], v[240:241], v[242:243]
	v_rcp_f32_e32 v240, v240
	v_rcp_f32_e32 v241, v241
	s_nop 0
	v_pk_mul_f32 v[240:241], v[240:241], v[106:107]
	v_cvt_pk_bf16_f32 v178, v240, v241
	v_lshlrev_b32_e32 v240, 16, v215
	v_and_b32_e32 v241, 0xffff0000, v215
	s_mov_b64 s[98:99], 0xc000
	v_lshl_add_u64 v[254:255], v[250:251], 0, s[98:99]
	global_load_dwordx4 v[212:215], v[254:255], off offset:256
	v_pk_add_f32 v[240:241], v[240:241], v[120:121]
	v_pk_mul_f32 v[240:241], v[240:241], v[244:245]
	v_exp_f32_e32 v240, v240
	v_exp_f32_e32 v241, v241
	s_nop 0
	v_min_f32_e32 v240, v240, v248
	v_min_f32_e32 v241, v241, v248
	v_pk_add_f32 v[240:241], v[240:241], v[242:243]
	v_rcp_f32_e32 v240, v240
	v_rcp_f32_e32 v241, v241
	s_nop 0
	v_pk_mul_f32 v[240:241], v[240:241], v[108:109]
	v_cvt_pk_bf16_f32 v179, v240, v241
	s_mov_b64 s[98:99], 0x10000
	v_lshl_add_u64 v[254:255], v[252:253], 0, s[98:99]
	global_store_dwordx4 v[254:255], v[176:179], off
	s_waitcnt vmcnt(11)
	v_lshlrev_b32_e32 v240, 16, v216
	v_and_b32_e32 v241, 0xffff0000, v216
	v_pk_add_f32 v[240:241], v[240:241], v[114:115]
	v_pk_mul_f32 v[240:241], v[240:241], v[244:245]
	v_exp_f32_e32 v240, v240
	v_exp_f32_e32 v241, v241
	s_nop 0
	v_min_f32_e32 v240, v240, v248
	v_min_f32_e32 v241, v241, v248
	v_pk_add_f32 v[240:241], v[240:241], v[242:243]
	v_rcp_f32_e32 v240, v240
	v_rcp_f32_e32 v241, v241
	s_nop 0
	v_pk_mul_f32 v[240:241], v[240:241], v[102:103]
	v_cvt_pk_bf16_f32 v176, v240, v241
	v_lshlrev_b32_e32 v240, 16, v217
	v_and_b32_e32 v241, 0xffff0000, v217
	v_pk_add_f32 v[240:241], v[240:241], v[116:117]
	v_pk_mul_f32 v[240:241], v[240:241], v[244:245]
	v_exp_f32_e32 v240, v240
	v_exp_f32_e32 v241, v241
	s_nop 0
	v_min_f32_e32 v240, v240, v248
	v_min_f32_e32 v241, v241, v248
	v_pk_add_f32 v[240:241], v[240:241], v[242:243]
	v_rcp_f32_e32 v240, v240
	v_rcp_f32_e32 v241, v241
	s_nop 0
	v_pk_mul_f32 v[240:241], v[240:241], v[104:105]
	v_cvt_pk_bf16_f32 v177, v240, v241
	v_lshlrev_b32_e32 v240, 16, v218
	v_and_b32_e32 v241, 0xffff0000, v218
	v_pk_add_f32 v[240:241], v[240:241], v[118:119]
	v_pk_mul_f32 v[240:241], v[240:241], v[244:245]
	v_exp_f32_e32 v240, v240
	v_exp_f32_e32 v241, v241
	s_nop 0
	v_min_f32_e32 v240, v240, v248
	v_min_f32_e32 v241, v241, v248
	v_pk_add_f32 v[240:241], v[240:241], v[242:243]
	v_rcp_f32_e32 v240, v240
	v_rcp_f32_e32 v241, v241
	s_nop 0
	v_pk_mul_f32 v[240:241], v[240:241], v[98:99]
	v_cvt_pk_bf16_f32 v178, v240, v241
	v_lshlrev_b32_e32 v240, 16, v219
	v_and_b32_e32 v241, 0xffff0000, v219
	s_mov_b64 s[98:99], 0x20000
	v_lshl_add_u64 v[254:255], v[250:251], 0, s[98:99]
	global_load_dwordx4 v[216:219], v[254:255], off offset:256
	v_pk_add_f32 v[240:241], v[240:241], v[120:121]
	v_pk_mul_f32 v[240:241], v[240:241], v[244:245]
	v_exp_f32_e32 v240, v240
	v_exp_f32_e32 v241, v241
	s_nop 0
	v_min_f32_e32 v240, v240, v248
	v_min_f32_e32 v241, v241, v248
	v_pk_add_f32 v[240:241], v[240:241], v[242:243]
	v_rcp_f32_e32 v240, v240
	v_rcp_f32_e32 v241, v241
	s_nop 0
	v_pk_mul_f32 v[240:241], v[240:241], v[100:101]
	v_cvt_pk_bf16_f32 v179, v240, v241
	s_mov_b64 s[98:99], 0x18000
	v_lshl_add_u64 v[254:255], v[252:253], 0, s[98:99]
	global_store_dwordx4 v[254:255], v[176:179], off
	s_waitcnt vmcnt(12)
; __device__ __forceinline__ unsigned cvt_pk_bf16(float lo, float hi) { unsigned r; asm volatile("v_cvt_pk_bf16_f32 %0, %1, %2" : "=v"(r) : "v"(lo), "v"(hi)); return r; }
; __device__ __forceinline__ float bflo(unsigned u) { return __uint_as_float(u << 16); }
; __device__ __forceinline__ float bfhi(unsigned u) { return __uint_as_float(u & 0xffff0000u); }
; __device__ __forceinline__ float sigm(float v) { return __builtin_amdgcn_rcpf(1.0f + __expf(-v)); }
; DI float bflo(unsigned u) { return __uint_as_float(u << 16); }
; DI float bfhi(unsigned u) { return __uint_as_float(u & 0xffff0000u); }
;     __device__ __forceinline__ void operator()(const f32x4 (&acc)[2][2][4][2], const Unit& u, int wr, int wc, int fr, int fq) const {
;         const int row0 = u.pm * BM + wr * 64 + fr; const int colt = u.pn * BM; const int t = colt / 512;
;         const bf16_t* gbase = G0 + (size_t)t * split_stride; const int col0 = colt + wc * 32 + 8 * fq, gcol0 = col0 - t * 512;
; #pragma unroll
;         for (int bj = 0; bj < 2; ++bj) {
;             const f32x4 b0 = *(const f32x4*)(gb + col0 + bj * HALF), b1 = *(const f32x4*)(gb + col0 + bj * HALF + 4);
; #pragma unroll
;             for (int ai = 0; ai < 2; ++ai)
; #pragma unroll
;                 for (int m = 0; m < 4; ++m) { const size_t row = (size_t)(row0 + ai * HALF + m * 16);
;                     const u32x4 g = *(const u32x4*)(gbase + row * 512 + gcol0 + bj * HALF);
;                     const f32x4 v0 = acc[ai][bj][m][0], v1 = acc[ai][bj][m][1];
;                     float r0 = v0[0] * sigm(bflo(g.x) + b0[0]), r1 = v0[1] * sigm(bfhi(g.x) + b0[1]), r2 = v0[2] * sigm(bflo(g.y) + b0[2]), r3 = v0[3] * sigm(bfhi(g.y) + b0[3]);
;                     float r4 = v1[0] * sigm(bflo(g.z) + b1[0]), r5 = v1[1] * sigm(bfhi(g.z) + b1[1]), r6 = v1[2] * sigm(bflo(g.w) + b1[2]), r7 = v1[3] * sigm(bfhi(g.w) + b1[3]);
;                     bf16_t* op = Mo + row * 1024 + col0 + bj * HALF;
;                     if (accum) { const u32x4 p = *(const u32x4*)op; r0 += bflo(p.x); r1 += bfhi(p.x); r2 += bflo(p.y); r3 += bfhi(p.y); r4 += bflo(p.z); r5 += bfhi(p.z); r6 += bflo(p.w); r7 += bfhi(p.w); }
;                     u32x4 w; w.x = cvt_pk_bf16(r0, r1); w.y = cvt_pk_bf16(r2, r3); w.z = cvt_pk_bf16(r4, r5); w.w = cvt_pk_bf16(r6, r7);
;                     *(u32x4*)op = w; }
	v_lshlrev_b32_e32 v240, 16, v220
	v_and_b32_e32 v241, 0xffff0000, v220
	v_pk_add_f32 v[240:241], v[240:241], v[114:115]
	v_pk_mul_f32 v[240:241], v[240:241], v[244:245]
	v_exp_f32_e32 v240, v240
	v_exp_f32_e32 v241, v241
	s_nop 0
	v_min_f32_e32 v240, v240, v248
	v_min_f32_e32 v241, v241, v248
	v_pk_add_f32 v[240:241], v[240:241], v[242:243]
	v_rcp_f32_e32 v240, v240
	v_rcp_f32_e32 v241, v241
	s_nop 0
	v_pk_mul_f32 v[240:241], v[240:241], v[94:95]
	v_cvt_pk_bf16_f32 v176, v240, v241
	v_lshlrev_b32_e32 v240, 16, v221
	v_and_b32_e32 v241, 0xffff0000, v221
	v_pk_add_f32 v[240:241], v[240:241], v[116:117]
	v_pk_mul_f32 v[240:241], v[240:241], v[244:245]
	v_exp_f32_e32 v240, v240
	v_exp_f32_e32 v241, v241
	s_nop 0
	v_min_f32_e32 v240, v240, v248
	v_min_f32_e32 v241, v241, v248
	v_pk_add_f32 v[240:241], v[240:241], v[242:243]
	v_rcp_f32_e32 v240, v240
	v_rcp_f32_e32 v241, v241
	s_nop 0
	v_pk_mul_f32 v[240:241], v[240:241], v[96:97]
	v_cvt_pk_bf16_f32 v177, v240, v241
	v_lshlrev_b32_e32 v240, 16, v222
	v_and_b32_e32 v241, 0xffff0000, v222
	v_pk_add_f32 v[240:241], v[240:241], v[118:119]
	v_pk_mul_f32 v[240:241], v[240:241], v[244:245]
	v_exp_f32_e32 v240, v240
	v_exp_f32_e32 v241, v241
	s_nop 0
	v_min_f32_e32 v240, v240, v248
	v_min_f32_e32 v241, v241, v248
	v_pk_add_f32 v[240:241], v[240:241], v[242:243]
	v_rcp_f32_e32 v240, v240
	v_rcp_f32_e32 v241, v241
	s_nop 0
	v_pk_mul_f32 v[240:241], v[240:241], v[90:91]
	v_cvt_pk_bf16_f32 v178, v240, v241
	v_lshlrev_b32_e32 v240, 16, v223
	v_and_b32_e32 v241, 0xffff0000, v223
	s_mov_b64 s[98:99], 0x24000
	v_lshl_add_u64 v[254:255], v[250:251], 0, s[98:99]
	global_load_dwordx4 v[220:223], v[254:255], off offset:256
	v_pk_add_f32 v[240:241], v[240:241], v[120:121]
	v_pk_mul_f32 v[240:241], v[240:241], v[244:245]
	v_exp_f32_e32 v240, v240
	v_exp_f32_e32 v241, v241
	s_nop 0
	v_min_f32_e32 v240, v240, v248
	v_min_f32_e32 v241, v241, v248
	v_pk_add_f32 v[240:241], v[240:241], v[242:243]
	v_rcp_f32_e32 v240, v240
	v_rcp_f32_e32 v241, v241
	s_nop 0
	v_pk_mul_f32 v[240:241], v[240:241], v[92:93]
	v_cvt_pk_bf16_f32 v179, v240, v241
	s_mov_b64 s[98:99], 0x40000
	v_lshl_add_u64 v[254:255], v[252:253], 0, s[98:99]
	global_store_dwordx4 v[254:255], v[176:179], off
	s_waitcnt vmcnt(13)
	v_lshlrev_b32_e32 v240, 16, v224
	v_and_b32_e32 v241, 0xffff0000, v224
	v_pk_add_f32 v[240:241], v[240:241], v[114:115]
	v_pk_mul_f32 v[240:241], v[240:241], v[244:245]
	v_exp_f32_e32 v240, v240
	v_exp_f32_e32 v241, v241
	s_nop 0
	v_min_f32_e32 v240, v240, v248
	v_min_f32_e32 v241, v241, v248
	v_pk_add_f32 v[240:241], v[240:241], v[242:243]
	v_rcp_f32_e32 v240, v240
	v_rcp_f32_e32 v241, v241
	s_nop 0
	v_pk_mul_f32 v[240:241], v[240:241], v[86:87]
	v_cvt_pk_bf16_f32 v176, v240, v241
	v_lshlrev_b32_e32 v240, 16, v225
	v_and_b32_e32 v241, 0xffff0000, v225
	v_pk_add_f32 v[240:241], v[240:241], v[116:117]
	v_pk_mul_f32 v[240:241], v[240:241], v[244:245]
	v_exp_f32_e32 v240, v240
	v_exp_f32_e32 v241, v241
	s_nop 0
	v_min_f32_e32 v240, v240, v248
	v_min_f32_e32 v241, v241, v248
	v_pk_add_f32 v[240:241], v[240:241], v[242:243]
	v_rcp_f32_e32 v240, v240
	v_rcp_f32_e32 v241, v241
	s_nop 0
	v_pk_mul_f32 v[240:241], v[240:241], v[88:89]
	v_cvt_pk_bf16_f32 v177, v240, v241
	v_lshlrev_b32_e32 v240, 16, v226
	v_and_b32_e32 v241, 0xffff0000, v226
	v_pk_add_f32 v[240:241], v[240:241], v[118:119]
	v_pk_mul_f32 v[240:241], v[240:241], v[244:245]
	v_exp_f32_e32 v240, v240
	v_exp_f32_e32 v241, v241
	s_nop 0
	v_min_f32_e32 v240, v240, v248
	v_min_f32_e32 v241, v241, v248
	v_pk_add_f32 v[240:241], v[240:241], v[242:243]
	v_rcp_f32_e32 v240, v240
	v_rcp_f32_e32 v241, v241
	s_nop 0
	v_pk_mul_f32 v[240:241], v[240:241], v[82:83]
	v_cvt_pk_bf16_f32 v178, v240, v241
	v_lshlrev_b32_e32 v240, 16, v227
	v_and_b32_e32 v241, 0xffff0000, v227
	s_mov_b64 s[98:99], 0x28000
	v_lshl_add_u64 v[254:255], v[250:251], 0, s[98:99]
	global_load_dwordx4 v[224:227], v[254:255], off offset:256
	v_pk_add_f32 v[240:241], v[240:241], v[120:121]
	v_pk_mul_f32 v[240:241], v[240:241], v[244:245]
	v_exp_f32_e32 v240, v240
	v_exp_f32_e32 v241, v241
	s_nop 0
	v_min_f32_e32 v240, v240, v248
	v_min_f32_e32 v241, v241, v248
	v_pk_add_f32 v[240:241], v[240:241], v[242:243]
	v_rcp_f32_e32 v240, v240
	v_rcp_f32_e32 v241, v241
	s_nop 0
	v_pk_mul_f32 v[240:241], v[240:241], v[84:85]
	v_cvt_pk_bf16_f32 v179, v240, v241
	s_mov_b64 s[98:99], 0x48000
	v_lshl_add_u64 v[254:255], v[252:253], 0, s[98:99]
	global_store_dwordx4 v[254:255], v[176:179], off
	s_waitcnt vmcnt(14)
	v_lshlrev_b32_e32 v240, 16, v192
	v_and_b32_e32 v241, 0xffff0000, v192
	v_pk_add_f32 v[240:241], v[240:241], v[114:115]
	v_pk_mul_f32 v[240:241], v[240:241], v[244:245]
	v_exp_f32_e32 v240, v240
	v_exp_f32_e32 v241, v241
	s_nop 0
	v_min_f32_e32 v240, v240, v248
	v_min_f32_e32 v241, v241, v248
	v_pk_add_f32 v[240:241], v[240:241], v[242:243]
	v_rcp_f32_e32 v240, v240
	v_rcp_f32_e32 v241, v241
	s_nop 0
	v_pk_mul_f32 v[240:241], v[240:241], v[78:79]
	v_cvt_pk_bf16_f32 v176, v240, v241
	v_lshlrev_b32_e32 v240, 16, v193
	v_and_b32_e32 v241, 0xffff0000, v193
	v_pk_add_f32 v[240:241], v[240:241], v[116:117]
	v_pk_mul_f32 v[240:241], v[240:241], v[244:245]
	v_exp_f32_e32 v240, v240
	v_exp_f32_e32 v241, v241
	s_nop 0
	v_min_f32_e32 v240, v240, v248
	v_min_f32_e32 v241, v241, v248
	v_pk_add_f32 v[240:241], v[240:241], v[242:243]
	v_rcp_f32_e32 v240, v240
	v_rcp_f32_e32 v241, v241
	s_nop 0
	v_pk_mul_f32 v[240:241], v[240:241], v[80:81]
	v_cvt_pk_bf16_f32 v177, v240, v241
	v_lshlrev_b32_e32 v240, 16, v194
	v_and_b32_e32 v241, 0xffff0000, v194
	v_pk_add_f32 v[240:241], v[240:241], v[118:119]
	v_pk_mul_f32 v[240:241], v[240:241], v[244:245]
	v_exp_f32_e32 v240, v240
	v_exp_f32_e32 v241, v241
	s_nop 0
	v_min_f32_e32 v240, v240, v248
	v_min_f32_e32 v241, v241, v248
	v_pk_add_f32 v[240:241], v[240:241], v[242:243]
	v_rcp_f32_e32 v240, v240
	v_rcp_f32_e32 v241, v241
	s_nop 0
	v_pk_mul_f32 v[240:241], v[240:241], v[74:75]
	v_cvt_pk_bf16_f32 v178, v240, v241
	v_lshlrev_b32_e32 v240, 16, v195
	v_and_b32_e32 v241, 0xffff0000, v195
	s_mov_b64 s[98:99], 0x2c000
	v_lshl_add_u64 v[254:255], v[250:251], 0, s[98:99]
	global_load_dwordx4 v[192:195], v[254:255], off offset:256
	v_pk_add_f32 v[240:241], v[240:241], v[120:121]
	v_pk_mul_f32 v[240:241], v[240:241], v[244:245]
	v_exp_f32_e32 v240, v240
	v_exp_f32_e32 v241, v241
	s_nop 0
	v_min_f32_e32 v240, v240, v248
	v_min_f32_e32 v241, v241, v248
	v_pk_add_f32 v[240:241], v[240:241], v[242:243]
	v_rcp_f32_e32 v240, v240
	v_rcp_f32_e32 v241, v241
	s_nop 0
	v_pk_mul_f32 v[240:241], v[240:241], v[76:77]
	v_cvt_pk_bf16_f32 v179, v240, v241
	s_mov_b64 s[98:99], 0x50000
	v_lshl_add_u64 v[254:255], v[252:253], 0, s[98:99]
	global_store_dwordx4 v[254:255], v[176:179], off
	s_waitcnt vmcnt(15)
; __device__ __forceinline__ unsigned cvt_pk_bf16(float lo, float hi) { unsigned r; asm volatile("v_cvt_pk_bf16_f32 %0, %1, %2" : "=v"(r) : "v"(lo), "v"(hi)); return r; }
; __device__ __forceinline__ float bflo(unsigned u) { return __uint_as_float(u << 16); }
; __device__ __forceinline__ float bfhi(unsigned u) { return __uint_as_float(u & 0xffff0000u); }
; __device__ __forceinline__ float sigm(float v) { return __builtin_amdgcn_rcpf(1.0f + __expf(-v)); }
; DI float bflo(unsigned u) { return __uint_as_float(u << 16); }
; DI float bfhi(unsigned u) { return __uint_as_float(u & 0xffff0000u); }
;     __device__ __forceinline__ void operator()(const f32x4 (&acc)[2][2][4][2], const Unit& u, int wr, int wc, int fr, int fq) const {
;         const int row0 = u.pm * BM + wr * 64 + fr; const int colt = u.pn * BM; const int t = colt / 512;
;         const bf16_t* gbase = G0 + (size_t)t * split_stride; const int col0 = colt + wc * 32 + 8 * fq, gcol0 = col0 - t * 512;
; #pragma unroll
;         for (int bj = 0; bj < 2; ++bj) {
;             const f32x4 b0 = *(const f32x4*)(gb + col0 + bj * HALF), b1 = *(const f32x4*)(gb + col0 + bj * HALF + 4);
; #pragma unroll
;             for (int ai = 0; ai < 2; ++ai)
; #pragma unroll
;                 for (int m = 0; m < 4; ++m) { const size_t row = (size_t)(row0 + ai * HALF + m * 16);
;                     const u32x4 g = *(const u32x4*)(gbase + row * 512 + gcol0 + bj * HALF);
;                     const f32x4 v0 = acc[ai][bj][m][0], v1 = acc[ai][bj][m][1];
;                     float r0 = v0[0] * sigm(bflo(g.x) + b0[0]), r1 = v0[1] * sigm(bfhi(g.x) + b0[1]), r2 = v0[2] * sigm(bflo(g.y) + b0[2]), r3 = v0[3] * sigm(bfhi(g.y) + b0[3]);
;                     float r4 = v1[0] * sigm(bflo(g.z) + b1[0]), r5 = v1[1] * sigm(bfhi(g.z) + b1[1]), r6 = v1[2] * sigm(bflo(g.w) + b1[2]), r7 = v1[3] * sigm(bfhi(g.w) + b1[3]);
;                     bf16_t* op = Mo + row * 1024 + col0 + bj * HALF;
;                     if (accum) { const u32x4 p = *(const u32x4*)op; r0 += bflo(p.x); r1 += bfhi(p.x); r2 += bflo(p.y); r3 += bfhi(p.y); r4 += bflo(p.z); r5 += bfhi(p.z); r6 += bflo(p.w); r7 += bfhi(p.w); }
;                     u32x4 w; w.x = cvt_pk_bf16(r0, r1); w.y = cvt_pk_bf16(r2, r3); w.z = cvt_pk_bf16(r4, r5); w.w = cvt_pk_bf16(r6, r7);
;                     *(u32x4*)op = w; }
	v_lshlrev_b32_e32 v240, 16, v188
	v_and_b32_e32 v241, 0xffff0000, v188
	v_pk_add_f32 v[240:241], v[240:241], v[114:115]
	v_pk_mul_f32 v[240:241], v[240:241], v[244:245]
	v_exp_f32_e32 v240, v240
	v_exp_f32_e32 v241, v241
	s_nop 0
	v_min_f32_e32 v240, v240, v248
	v_min_f32_e32 v241, v241, v248
	v_pk_add_f32 v[240:241], v[240:241], v[242:243]
	v_rcp_f32_e32 v240, v240
	v_rcp_f32_e32 v241, v241
	s_nop 0
	v_pk_mul_f32 v[240:241], v[240:241], v[70:71]
	v_cvt_pk_bf16_f32 v176, v240, v241
	v_lshlrev_b32_e32 v240, 16, v189
	v_and_b32_e32 v241, 0xffff0000, v189
	v_pk_add_f32 v[240:241], v[240:241], v[116:117]
	v_pk_mul_f32 v[240:241], v[240:241], v[244:245]
	v_exp_f32_e32 v240, v240
	v_exp_f32_e32 v241, v241
	s_nop 0
	v_min_f32_e32 v240, v240, v248
	v_min_f32_e32 v241, v241, v248
	v_pk_add_f32 v[240:241], v[240:241], v[242:243]
	v_rcp_f32_e32 v240, v240
	v_rcp_f32_e32 v241, v241
	s_nop 0
	v_pk_mul_f32 v[240:241], v[240:241], v[72:73]
	v_cvt_pk_bf16_f32 v177, v240, v241
	v_lshlrev_b32_e32 v240, 16, v190
	v_and_b32_e32 v241, 0xffff0000, v190
	v_pk_add_f32 v[240:241], v[240:241], v[118:119]
	v_pk_mul_f32 v[240:241], v[240:241], v[244:245]
	v_exp_f32_e32 v240, v240
	v_exp_f32_e32 v241, v241
	s_nop 0
	v_min_f32_e32 v240, v240, v248
	v_min_f32_e32 v241, v241, v248
	v_pk_add_f32 v[240:241], v[240:241], v[242:243]
	v_rcp_f32_e32 v240, v240
	v_rcp_f32_e32 v241, v241
	s_nop 0
	v_pk_mul_f32 v[240:241], v[240:241], v[66:67]
	v_cvt_pk_bf16_f32 v178, v240, v241
	v_lshlrev_b32_e32 v240, 16, v191
	v_and_b32_e32 v241, 0xffff0000, v191
	v_pk_add_f32 v[240:241], v[240:241], v[120:121]
	v_pk_mul_f32 v[240:241], v[240:241], v[244:245]
	v_exp_f32_e32 v240, v240
	v_exp_f32_e32 v241, v241
	s_nop 0
	v_min_f32_e32 v240, v240, v248
	v_min_f32_e32 v241, v241, v248
	v_pk_add_f32 v[240:241], v[240:241], v[242:243]
	v_rcp_f32_e32 v240, v240
	v_rcp_f32_e32 v241, v241
	s_nop 0
	v_pk_mul_f32 v[240:241], v[240:241], v[68:69]
	v_cvt_pk_bf16_f32 v179, v240, v241
	s_mov_b64 s[98:99], 0x58000
	v_lshl_add_u64 v[254:255], v[252:253], 0, s[98:99]
	global_store_dwordx4 v[254:255], v[176:179], off
	s_waitcnt vmcnt(15)
	v_lshlrev_b32_e32 v240, 16, v184
	v_and_b32_e32 v241, 0xffff0000, v184
	v_pk_add_f32 v[240:241], v[240:241], v[154:155]
	v_pk_mul_f32 v[240:241], v[240:241], v[244:245]
	v_exp_f32_e32 v240, v240
	v_exp_f32_e32 v241, v241
	s_nop 0
	v_min_f32_e32 v240, v240, v248
	v_min_f32_e32 v241, v241, v248
	v_pk_add_f32 v[240:241], v[240:241], v[242:243]
	v_rcp_f32_e32 v240, v240
	v_rcp_f32_e32 v241, v241
	s_nop 0
	v_pk_mul_f32 v[240:241], v[240:241], v[62:63]
	v_cvt_pk_bf16_f32 v176, v240, v241
	v_lshlrev_b32_e32 v240, 16, v185
	v_and_b32_e32 v241, 0xffff0000, v185
	v_pk_add_f32 v[240:241], v[240:241], v[156:157]
	v_pk_mul_f32 v[240:241], v[240:241], v[244:245]
	v_exp_f32_e32 v240, v240
	v_exp_f32_e32 v241, v241
	s_nop 0
	v_min_f32_e32 v240, v240, v248
	v_min_f32_e32 v241, v241, v248
	v_pk_add_f32 v[240:241], v[240:241], v[242:243]
	v_rcp_f32_e32 v240, v240
	v_rcp_f32_e32 v241, v241
	s_nop 0
	v_pk_mul_f32 v[240:241], v[240:241], v[64:65]
	v_cvt_pk_bf16_f32 v177, v240, v241
	v_lshlrev_b32_e32 v240, 16, v186
	v_and_b32_e32 v241, 0xffff0000, v186
	v_pk_add_f32 v[240:241], v[240:241], v[158:159]
	v_pk_mul_f32 v[240:241], v[240:241], v[244:245]
	v_exp_f32_e32 v240, v240
	v_exp_f32_e32 v241, v241
	s_nop 0
	v_min_f32_e32 v240, v240, v248
	v_min_f32_e32 v241, v241, v248
	v_pk_add_f32 v[240:241], v[240:241], v[242:243]
	v_rcp_f32_e32 v240, v240
	v_rcp_f32_e32 v241, v241
	s_nop 0
	v_pk_mul_f32 v[240:241], v[240:241], v[58:59]
	v_cvt_pk_bf16_f32 v178, v240, v241
	v_lshlrev_b32_e32 v240, 16, v187
	v_and_b32_e32 v241, 0xffff0000, v187
	v_pk_add_f32 v[240:241], v[240:241], v[160:161]
	v_pk_mul_f32 v[240:241], v[240:241], v[244:245]
	v_exp_f32_e32 v240, v240
	v_exp_f32_e32 v241, v241
	s_nop 0
	v_min_f32_e32 v240, v240, v248
	v_min_f32_e32 v241, v241, v248
	v_pk_add_f32 v[240:241], v[240:241], v[242:243]
	v_rcp_f32_e32 v240, v240
	v_rcp_f32_e32 v241, v241
	s_nop 0
	v_pk_mul_f32 v[240:241], v[240:241], v[60:61]
	v_cvt_pk_bf16_f32 v179, v240, v241
	global_store_dwordx4 v[252:253], v[176:179], off offset:256
	s_waitcnt vmcnt(15)
	v_lshlrev_b32_e32 v240, 16, v204
	v_and_b32_e32 v241, 0xffff0000, v204
	v_pk_add_f32 v[240:241], v[240:241], v[154:155]
	v_pk_mul_f32 v[240:241], v[240:241], v[244:245]
	v_exp_f32_e32 v240, v240
	v_exp_f32_e32 v241, v241
	s_nop 0
	v_min_f32_e32 v240, v240, v248
	v_min_f32_e32 v241, v241, v248
	v_pk_add_f32 v[240:241], v[240:241], v[242:243]
	v_rcp_f32_e32 v240, v240
	v_rcp_f32_e32 v241, v241
	s_nop 0
	v_pk_mul_f32 v[240:241], v[240:241], v[54:55]
	v_cvt_pk_bf16_f32 v176, v240, v241
	v_lshlrev_b32_e32 v240, 16, v205
	v_and_b32_e32 v241, 0xffff0000, v205
	v_pk_add_f32 v[240:241], v[240:241], v[156:157]
	v_pk_mul_f32 v[240:241], v[240:241], v[244:245]
	v_exp_f32_e32 v240, v240
	v_exp_f32_e32 v241, v241
	s_nop 0
	v_min_f32_e32 v240, v240, v248
	v_min_f32_e32 v241, v241, v248
	v_pk_add_f32 v[240:241], v[240:241], v[242:243]
	v_rcp_f32_e32 v240, v240
	v_rcp_f32_e32 v241, v241
	s_nop 0
	v_pk_mul_f32 v[240:241], v[240:241], v[56:57]
	v_cvt_pk_bf16_f32 v177, v240, v241
	v_lshlrev_b32_e32 v240, 16, v206
	v_and_b32_e32 v241, 0xffff0000, v206
	v_pk_add_f32 v[240:241], v[240:241], v[158:159]
	v_pk_mul_f32 v[240:241], v[240:241], v[244:245]
	v_exp_f32_e32 v240, v240
	v_exp_f32_e32 v241, v241
	s_nop 0
	v_min_f32_e32 v240, v240, v248
	v_min_f32_e32 v241, v241, v248
	v_pk_add_f32 v[240:241], v[240:241], v[242:243]
	v_rcp_f32_e32 v240, v240
	v_rcp_f32_e32 v241, v241
	s_nop 0
	v_pk_mul_f32 v[240:241], v[240:241], v[50:51]
	v_cvt_pk_bf16_f32 v178, v240, v241
	v_lshlrev_b32_e32 v240, 16, v207
	v_and_b32_e32 v241, 0xffff0000, v207
	v_pk_add_f32 v[240:241], v[240:241], v[160:161]
	v_pk_mul_f32 v[240:241], v[240:241], v[244:245]
	v_exp_f32_e32 v240, v240
	v_exp_f32_e32 v241, v241
	s_nop 0
	v_min_f32_e32 v240, v240, v248
	v_min_f32_e32 v241, v241, v248
	v_pk_add_f32 v[240:241], v[240:241], v[242:243]
	v_rcp_f32_e32 v240, v240
	v_rcp_f32_e32 v241, v241
	s_nop 0
	v_pk_mul_f32 v[240:241], v[240:241], v[52:53]
	v_cvt_pk_bf16_f32 v179, v240, v241
	s_mov_b64 s[98:99], 0x8000
	v_lshl_add_u64 v[254:255], v[252:253], 0, s[98:99]
	global_store_dwordx4 v[254:255], v[176:179], off offset:256
	s_waitcnt vmcnt(14)
; __device__ __forceinline__ unsigned cvt_pk_bf16(float lo, float hi) { unsigned r; asm volatile("v_cvt_pk_bf16_f32 %0, %1, %2" : "=v"(r) : "v"(lo), "v"(hi)); return r; }
; __device__ __forceinline__ float bflo(unsigned u) { return __uint_as_float(u << 16); }
; __device__ __forceinline__ float bfhi(unsigned u) { return __uint_as_float(u & 0xffff0000u); }
; __device__ __forceinline__ float sigm(float v) { return __builtin_amdgcn_rcpf(1.0f + __expf(-v)); }
; DI float bflo(unsigned u) { return __uint_as_float(u << 16); }
; DI float bfhi(unsigned u) { return __uint_as_float(u & 0xffff0000u); }
;     __device__ __forceinline__ void operator()(const f32x4 (&acc)[2][2][4][2], const Unit& u, int wr, int wc, int fr, int fq) const {
;         const int row0 = u.pm * BM + wr * 64 + fr; const int colt = u.pn * BM; const int t = colt / 512;
;         const bf16_t* gbase = G0 + (size_t)t * split_stride; const int col0 = colt + wc * 32 + 8 * fq, gcol0 = col0 - t * 512;
; #pragma unroll
;         for (int bj = 0; bj < 2; ++bj) {
;             const f32x4 b0 = *(const f32x4*)(gb + col0 + bj * HALF), b1 = *(const f32x4*)(gb + col0 + bj * HALF + 4);
; #pragma unroll
;             for (int ai = 0; ai < 2; ++ai)
; #pragma unroll
;                 for (int m = 0; m < 4; ++m) { const size_t row = (size_t)(row0 + ai * HALF + m * 16);
;                     const u32x4 g = *(const u32x4*)(gbase + row * 512 + gcol0 + bj * HALF);
;                     const f32x4 v0 = acc[ai][bj][m][0], v1 = acc[ai][bj][m][1];
;                     float r0 = v0[0] * sigm(bflo(g.x) + b0[0]), r1 = v0[1] * sigm(bfhi(g.x) + b0[1]), r2 = v0[2] * sigm(bflo(g.y) + b0[2]), r3 = v0[3] * sigm(bfhi(g.y) + b0[3]);
;                     float r4 = v1[0] * sigm(bflo(g.z) + b1[0]), r5 = v1[1] * sigm(bfhi(g.z) + b1[1]), r6 = v1[2] * sigm(bflo(g.w) + b1[2]), r7 = v1[3] * sigm(bfhi(g.w) + b1[3]);
;                     bf16_t* op = Mo + row * 1024 + col0 + bj * HALF;
;                     if (accum) { const u32x4 p = *(const u32x4*)op; r0 += bflo(p.x); r1 += bfhi(p.x); r2 += bflo(p.y); r3 += bfhi(p.y); r4 += bflo(p.z); r5 += bfhi(p.z); r6 += bflo(p.w); r7 += bfhi(p.w); }
;                     u32x4 w; w.x = cvt_pk_bf16(r0, r1); w.y = cvt_pk_bf16(r2, r3); w.z = cvt_pk_bf16(r4, r5); w.w = cvt_pk_bf16(r6, r7);
;                     *(u32x4*)op = w; }
	v_lshlrev_b32_e32 v240, 16, v208
	v_and_b32_e32 v241, 0xffff0000, v208
	v_pk_add_f32 v[240:241], v[240:241], v[154:155]
	v_pk_mul_f32 v[240:241], v[240:241], v[244:245]
	v_exp_f32_e32 v240, v240
	v_exp_f32_e32 v241, v241
	s_nop 0
	v_min_f32_e32 v240, v240, v248
	v_min_f32_e32 v241, v241, v248
	v_pk_add_f32 v[240:241], v[240:241], v[242:243]
	v_rcp_f32_e32 v240, v240
	v_rcp_f32_e32 v241, v241
	s_nop 0
	v_pk_mul_f32 v[240:241], v[240:241], v[46:47]
	v_cvt_pk_bf16_f32 v176, v240, v241
	v_lshlrev_b32_e32 v240, 16, v209
	v_and_b32_e32 v241, 0xffff0000, v209
	v_pk_add_f32 v[240:241], v[240:241], v[156:157]
	v_pk_mul_f32 v[240:241], v[240:241], v[244:245]
	v_exp_f32_e32 v240, v240
	v_exp_f32_e32 v241, v241
	s_nop 0
	v_min_f32_e32 v240, v240, v248
	v_min_f32_e32 v241, v241, v248
	v_pk_add_f32 v[240:241], v[240:241], v[242:243]
	v_rcp_f32_e32 v240, v240
	v_rcp_f32_e32 v241, v241
	s_nop 0
	v_pk_mul_f32 v[240:241], v[240:241], v[48:49]
	v_cvt_pk_bf16_f32 v177, v240, v241
	v_lshlrev_b32_e32 v240, 16, v210
	v_and_b32_e32 v241, 0xffff0000, v210
	v_pk_add_f32 v[240:241], v[240:241], v[158:159]
	v_pk_mul_f32 v[240:241], v[240:241], v[244:245]
	v_exp_f32_e32 v240, v240
	v_exp_f32_e32 v241, v241
	s_nop 0
	v_min_f32_e32 v240, v240, v248
	v_min_f32_e32 v241, v241, v248
	v_pk_add_f32 v[240:241], v[240:241], v[242:243]
	v_rcp_f32_e32 v240, v240
	v_rcp_f32_e32 v241, v241
	s_nop 0
	v_pk_mul_f32 v[240:241], v[240:241], v[42:43]
	v_cvt_pk_bf16_f32 v178, v240, v241
	v_lshlrev_b32_e32 v240, 16, v211
	v_and_b32_e32 v241, 0xffff0000, v211
	v_pk_add_f32 v[240:241], v[240:241], v[160:161]
	v_pk_mul_f32 v[240:241], v[240:241], v[244:245]
	v_exp_f32_e32 v240, v240
	v_exp_f32_e32 v241, v241
	s_nop 0
	v_min_f32_e32 v240, v240, v248
	v_min_f32_e32 v241, v241, v248
	v_pk_add_f32 v[240:241], v[240:241], v[242:243]
	v_rcp_f32_e32 v240, v240
	v_rcp_f32_e32 v241, v241
	s_nop 0
	v_pk_mul_f32 v[240:241], v[240:241], v[44:45]
	v_cvt_pk_bf16_f32 v179, v240, v241
	s_mov_b64 s[98:99], 0x10000
	v_lshl_add_u64 v[254:255], v[252:253], 0, s[98:99]
	global_store_dwordx4 v[254:255], v[176:179], off offset:256
	s_waitcnt vmcnt(13)
	v_lshlrev_b32_e32 v240, 16, v212
	v_and_b32_e32 v241, 0xffff0000, v212
	v_pk_add_f32 v[240:241], v[240:241], v[154:155]
	v_pk_mul_f32 v[240:241], v[240:241], v[244:245]
	v_exp_f32_e32 v240, v240
	v_exp_f32_e32 v241, v241
	s_nop 0
	v_min_f32_e32 v240, v240, v248
	v_min_f32_e32 v241, v241, v248
	v_pk_add_f32 v[240:241], v[240:241], v[242:243]
	v_rcp_f32_e32 v240, v240
	v_rcp_f32_e32 v241, v241
	s_nop 0
	v_pk_mul_f32 v[240:241], v[240:241], v[38:39]
	v_cvt_pk_bf16_f32 v176, v240, v241
	v_lshlrev_b32_e32 v240, 16, v213
	v_and_b32_e32 v241, 0xffff0000, v213
	v_pk_add_f32 v[240:241], v[240:241], v[156:157]
	v_pk_mul_f32 v[240:241], v[240:241], v[244:245]
	v_exp_f32_e32 v240, v240
	v_exp_f32_e32 v241, v241
	s_nop 0
	v_min_f32_e32 v240, v240, v248
	v_min_f32_e32 v241, v241, v248
	v_pk_add_f32 v[240:241], v[240:241], v[242:243]
	v_rcp_f32_e32 v240, v240
	v_rcp_f32_e32 v241, v241
	s_nop 0
	v_pk_mul_f32 v[240:241], v[240:241], v[40:41]
	v_cvt_pk_bf16_f32 v177, v240, v241
	v_lshlrev_b32_e32 v240, 16, v214
	v_and_b32_e32 v241, 0xffff0000, v214
	v_pk_add_f32 v[240:241], v[240:241], v[158:159]
	v_pk_mul_f32 v[240:241], v[240:241], v[244:245]
	v_exp_f32_e32 v240, v240
	v_exp_f32_e32 v241, v241
	s_nop 0
	v_min_f32_e32 v240, v240, v248
	v_min_f32_e32 v241, v241, v248
	v_pk_add_f32 v[240:241], v[240:241], v[242:243]
	v_rcp_f32_e32 v240, v240
	v_rcp_f32_e32 v241, v241
	s_nop 0
	v_pk_mul_f32 v[240:241], v[240:241], v[34:35]
	v_cvt_pk_bf16_f32 v178, v240, v241
	v_lshlrev_b32_e32 v240, 16, v215
	v_and_b32_e32 v241, 0xffff0000, v215
	v_pk_add_f32 v[240:241], v[240:241], v[160:161]
	v_pk_mul_f32 v[240:241], v[240:241], v[244:245]
	v_exp_f32_e32 v240, v240
	v_exp_f32_e32 v241, v241
	s_nop 0
	v_min_f32_e32 v240, v240, v248
	v_min_f32_e32 v241, v241, v248
	v_pk_add_f32 v[240:241], v[240:241], v[242:243]
	v_rcp_f32_e32 v240, v240
	v_rcp_f32_e32 v241, v241
	s_nop 0
	v_pk_mul_f32 v[240:241], v[240:241], v[36:37]
	v_cvt_pk_bf16_f32 v179, v240, v241
	s_mov_b64 s[98:99], 0x18000
	v_lshl_add_u64 v[254:255], v[252:253], 0, s[98:99]
	global_store_dwordx4 v[254:255], v[176:179], off offset:256
	s_waitcnt vmcnt(12)
	v_lshlrev_b32_e32 v240, 16, v216
	v_and_b32_e32 v241, 0xffff0000, v216
	v_pk_add_f32 v[240:241], v[240:241], v[154:155]
	v_pk_mul_f32 v[240:241], v[240:241], v[244:245]
	v_exp_f32_e32 v240, v240
	v_exp_f32_e32 v241, v241
	s_nop 0
	v_min_f32_e32 v240, v240, v248
	v_min_f32_e32 v241, v241, v248
	v_pk_add_f32 v[240:241], v[240:241], v[242:243]
	v_rcp_f32_e32 v240, v240
	v_rcp_f32_e32 v241, v241
	s_nop 0
	v_pk_mul_f32 v[240:241], v[240:241], v[30:31]
	v_cvt_pk_bf16_f32 v176, v240, v241
	v_lshlrev_b32_e32 v240, 16, v217
	v_and_b32_e32 v241, 0xffff0000, v217
	v_pk_add_f32 v[240:241], v[240:241], v[156:157]
	v_pk_mul_f32 v[240:241], v[240:241], v[244:245]
	v_exp_f32_e32 v240, v240
	v_exp_f32_e32 v241, v241
	s_nop 0
	v_min_f32_e32 v240, v240, v248
	v_min_f32_e32 v241, v241, v248
	v_pk_add_f32 v[240:241], v[240:241], v[242:243]
	v_rcp_f32_e32 v240, v240
	v_rcp_f32_e32 v241, v241
	s_nop 0
	v_pk_mul_f32 v[240:241], v[240:241], v[32:33]
	v_cvt_pk_bf16_f32 v177, v240, v241
	v_lshlrev_b32_e32 v240, 16, v218
	v_and_b32_e32 v241, 0xffff0000, v218
	v_pk_add_f32 v[240:241], v[240:241], v[158:159]
	v_pk_mul_f32 v[240:241], v[240:241], v[244:245]
	v_exp_f32_e32 v240, v240
	v_exp_f32_e32 v241, v241
	s_nop 0
	v_min_f32_e32 v240, v240, v248
	v_min_f32_e32 v241, v241, v248
	v_pk_add_f32 v[240:241], v[240:241], v[242:243]
	v_rcp_f32_e32 v240, v240
	v_rcp_f32_e32 v241, v241
	s_nop 0
	v_pk_mul_f32 v[240:241], v[240:241], v[26:27]
	v_cvt_pk_bf16_f32 v178, v240, v241
	v_lshlrev_b32_e32 v240, 16, v219
	v_and_b32_e32 v241, 0xffff0000, v219
	v_pk_add_f32 v[240:241], v[240:241], v[160:161]
	v_pk_mul_f32 v[240:241], v[240:241], v[244:245]
	v_exp_f32_e32 v240, v240
	v_exp_f32_e32 v241, v241
	s_nop 0
	v_min_f32_e32 v240, v240, v248
	v_min_f32_e32 v241, v241, v248
	v_pk_add_f32 v[240:241], v[240:241], v[242:243]
	v_rcp_f32_e32 v240, v240
	v_rcp_f32_e32 v241, v241
	s_nop 0
	v_pk_mul_f32 v[240:241], v[240:241], v[28:29]
	v_cvt_pk_bf16_f32 v179, v240, v241
	s_mov_b64 s[98:99], 0x40000
	v_lshl_add_u64 v[254:255], v[252:253], 0, s[98:99]
	global_store_dwordx4 v[254:255], v[176:179], off offset:256
	s_waitcnt vmcnt(11)
; __device__ __forceinline__ unsigned cvt_pk_bf16(float lo, float hi) { unsigned r; asm volatile("v_cvt_pk_bf16_f32 %0, %1, %2" : "=v"(r) : "v"(lo), "v"(hi)); return r; }
; __device__ __forceinline__ float bflo(unsigned u) { return __uint_as_float(u << 16); }
; __device__ __forceinline__ float bfhi(unsigned u) { return __uint_as_float(u & 0xffff0000u); }
; __device__ __forceinline__ float sigm(float v) { return __builtin_amdgcn_rcpf(1.0f + __expf(-v)); }
; DI float bflo(unsigned u) { return __uint_as_float(u << 16); }
; DI float bfhi(unsigned u) { return __uint_as_float(u & 0xffff0000u); }
;     __device__ __forceinline__ void operator()(const f32x4 (&acc)[2][2][4][2], const Unit& u, int wr, int wc, int fr, int fq) const {
;         const int row0 = u.pm * BM + wr * 64 + fr; const int colt = u.pn * BM; const int t = colt / 512;
;         const bf16_t* gbase = G0 + (size_t)t * split_stride; const int col0 = colt + wc * 32 + 8 * fq, gcol0 = col0 - t * 512;
; #pragma unroll
;         for (int bj = 0; bj < 2; ++bj) {
;             const f32x4 b0 = *(const f32x4*)(gb + col0 + bj * HALF), b1 = *(const f32x4*)(gb + col0 + bj * HALF + 4);
; #pragma unroll
;             for (int ai = 0; ai < 2; ++ai)
; #pragma unroll
;                 for (int m = 0; m < 4; ++m) { const size_t row = (size_t)(row0 + ai * HALF + m * 16);
;                     const u32x4 g = *(const u32x4*)(gbase + row * 512 + gcol0 + bj * HALF);
;                     const f32x4 v0 = acc[ai][bj][m][0], v1 = acc[ai][bj][m][1];
;                     float r0 = v0[0] * sigm(bflo(g.x) + b0[0]), r1 = v0[1] * sigm(bfhi(g.x) + b0[1]), r2 = v0[2] * sigm(bflo(g.y) + b0[2]), r3 = v0[3] * sigm(bfhi(g.y) + b0[3]);
;                     float r4 = v1[0] * sigm(bflo(g.z) + b1[0]), r5 = v1[1] * sigm(bfhi(g.z) + b1[1]), r6 = v1[2] * sigm(bflo(g.w) + b1[2]), r7 = v1[3] * sigm(bfhi(g.w) + b1[3]);
;                     bf16_t* op = Mo + row * 1024 + col0 + bj * HALF;
;                     if (accum) { const u32x4 p = *(const u32x4*)op; r0 += bflo(p.x); r1 += bfhi(p.x); r2 += bflo(p.y); r3 += bfhi(p.y); r4 += bflo(p.z); r5 += bfhi(p.z); r6 += bflo(p.w); r7 += bfhi(p.w); }
;                     u32x4 w; w.x = cvt_pk_bf16(r0, r1); w.y = cvt_pk_bf16(r2, r3); w.z = cvt_pk_bf16(r4, r5); w.w = cvt_pk_bf16(r6, r7);
;                     *(u32x4*)op = w; }
	v_lshlrev_b32_e32 v240, 16, v220
	v_and_b32_e32 v241, 0xffff0000, v220
	v_pk_add_f32 v[240:241], v[240:241], v[154:155]
	v_pk_mul_f32 v[240:241], v[240:241], v[244:245]
	v_exp_f32_e32 v240, v240
	v_exp_f32_e32 v241, v241
	s_nop 0
	v_min_f32_e32 v240, v240, v248
	v_min_f32_e32 v241, v241, v248
	v_pk_add_f32 v[240:241], v[240:241], v[242:243]
	v_rcp_f32_e32 v240, v240
	v_rcp_f32_e32 v241, v241
	s_nop 0
	v_pk_mul_f32 v[240:241], v[240:241], v[22:23]
	v_cvt_pk_bf16_f32 v176, v240, v241
	v_lshlrev_b32_e32 v240, 16, v221
	v_and_b32_e32 v241, 0xffff0000, v221
	v_pk_add_f32 v[240:241], v[240:241], v[156:157]
	v_pk_mul_f32 v[240:241], v[240:241], v[244:245]
	v_exp_f32_e32 v240, v240
	v_exp_f32_e32 v241, v241
	s_nop 0
	v_min_f32_e32 v240, v240, v248
	v_min_f32_e32 v241, v241, v248
	v_pk_add_f32 v[240:241], v[240:241], v[242:243]
	v_rcp_f32_e32 v240, v240
	v_rcp_f32_e32 v241, v241
	s_nop 0
	v_pk_mul_f32 v[240:241], v[240:241], v[24:25]
	v_cvt_pk_bf16_f32 v177, v240, v241
	v_lshlrev_b32_e32 v240, 16, v222
	v_and_b32_e32 v241, 0xffff0000, v222
	v_pk_add_f32 v[240:241], v[240:241], v[158:159]
	v_pk_mul_f32 v[240:241], v[240:241], v[244:245]
	v_exp_f32_e32 v240, v240
	v_exp_f32_e32 v241, v241
	s_nop 0
	v_min_f32_e32 v240, v240, v248
	v_min_f32_e32 v241, v241, v248
	v_pk_add_f32 v[240:241], v[240:241], v[242:243]
	v_rcp_f32_e32 v240, v240
	v_rcp_f32_e32 v241, v241
	s_nop 0
	v_pk_mul_f32 v[240:241], v[240:241], v[18:19]
	v_cvt_pk_bf16_f32 v178, v240, v241
	v_lshlrev_b32_e32 v240, 16, v223
	v_and_b32_e32 v241, 0xffff0000, v223
	v_pk_add_f32 v[240:241], v[240:241], v[160:161]
	v_pk_mul_f32 v[240:241], v[240:241], v[244:245]
	v_exp_f32_e32 v240, v240
	v_exp_f32_e32 v241, v241
	s_nop 0
	v_min_f32_e32 v240, v240, v248
	v_min_f32_e32 v241, v241, v248
	v_pk_add_f32 v[240:241], v[240:241], v[242:243]
	v_rcp_f32_e32 v240, v240
	v_rcp_f32_e32 v241, v241
	s_nop 0
	v_pk_mul_f32 v[240:241], v[240:241], v[20:21]
	v_cvt_pk_bf16_f32 v179, v240, v241
	s_mov_b64 s[98:99], 0x48000
	v_lshl_add_u64 v[254:255], v[252:253], 0, s[98:99]
	global_store_dwordx4 v[254:255], v[176:179], off offset:256
	s_waitcnt vmcnt(10)
	v_lshlrev_b32_e32 v240, 16, v224
	v_and_b32_e32 v241, 0xffff0000, v224
	v_pk_add_f32 v[240:241], v[240:241], v[154:155]
	v_pk_mul_f32 v[240:241], v[240:241], v[244:245]
	v_exp_f32_e32 v240, v240
	v_exp_f32_e32 v241, v241
	s_nop 0
	v_min_f32_e32 v240, v240, v248
	v_min_f32_e32 v241, v241, v248
	v_pk_add_f32 v[240:241], v[240:241], v[242:243]
	v_rcp_f32_e32 v240, v240
	v_rcp_f32_e32 v241, v241
	s_nop 0
	v_pk_mul_f32 v[240:241], v[240:241], v[14:15]
	v_cvt_pk_bf16_f32 v176, v240, v241
	v_lshlrev_b32_e32 v240, 16, v225
	v_and_b32_e32 v241, 0xffff0000, v225
	v_pk_add_f32 v[240:241], v[240:241], v[156:157]
	v_pk_mul_f32 v[240:241], v[240:241], v[244:245]
	v_exp_f32_e32 v240, v240
	v_exp_f32_e32 v241, v241
	s_nop 0
	v_min_f32_e32 v240, v240, v248
	v_min_f32_e32 v241, v241, v248
	v_pk_add_f32 v[240:241], v[240:241], v[242:243]
	v_rcp_f32_e32 v240, v240
	v_rcp_f32_e32 v241, v241
	s_nop 0
	v_pk_mul_f32 v[240:241], v[240:241], v[16:17]
	v_cvt_pk_bf16_f32 v177, v240, v241
	v_lshlrev_b32_e32 v240, 16, v226
	v_and_b32_e32 v241, 0xffff0000, v226
	v_pk_add_f32 v[240:241], v[240:241], v[158:159]
	v_pk_mul_f32 v[240:241], v[240:241], v[244:245]
	v_exp_f32_e32 v240, v240
	v_exp_f32_e32 v241, v241
	s_nop 0
	v_min_f32_e32 v240, v240, v248
	v_min_f32_e32 v241, v241, v248
	v_pk_add_f32 v[240:241], v[240:241], v[242:243]
	v_rcp_f32_e32 v240, v240
	v_rcp_f32_e32 v241, v241
	s_nop 0
	v_pk_mul_f32 v[240:241], v[240:241], v[10:11]
	v_cvt_pk_bf16_f32 v178, v240, v241
	v_lshlrev_b32_e32 v240, 16, v227
	v_and_b32_e32 v241, 0xffff0000, v227
	v_pk_add_f32 v[240:241], v[240:241], v[160:161]
	v_pk_mul_f32 v[240:241], v[240:241], v[244:245]
	v_exp_f32_e32 v240, v240
	v_exp_f32_e32 v241, v241
	s_nop 0
	v_min_f32_e32 v240, v240, v248
	v_min_f32_e32 v241, v241, v248
	v_pk_add_f32 v[240:241], v[240:241], v[242:243]
	v_rcp_f32_e32 v240, v240
	v_rcp_f32_e32 v241, v241
	s_nop 0
	v_pk_mul_f32 v[240:241], v[240:241], v[12:13]
	v_cvt_pk_bf16_f32 v179, v240, v241
	s_mov_b64 s[98:99], 0x50000
	v_lshl_add_u64 v[254:255], v[252:253], 0, s[98:99]
	global_store_dwordx4 v[254:255], v[176:179], off offset:256
	s_waitcnt vmcnt(9)
	v_lshlrev_b32_e32 v240, 16, v192
	v_and_b32_e32 v241, 0xffff0000, v192
	v_pk_add_f32 v[240:241], v[240:241], v[154:155]
	v_pk_mul_f32 v[240:241], v[240:241], v[244:245]
	v_exp_f32_e32 v240, v240
	v_exp_f32_e32 v241, v241
	s_nop 0
	v_min_f32_e32 v240, v240, v248
	v_min_f32_e32 v241, v241, v248
	v_pk_add_f32 v[240:241], v[240:241], v[242:243]
	v_rcp_f32_e32 v240, v240
	v_rcp_f32_e32 v241, v241
	s_nop 0
	v_pk_mul_f32 v[240:241], v[240:241], v[6:7]
	v_cvt_pk_bf16_f32 v176, v240, v241
	v_lshlrev_b32_e32 v240, 16, v193
	v_and_b32_e32 v241, 0xffff0000, v193
	v_pk_add_f32 v[240:241], v[240:241], v[156:157]
	v_pk_mul_f32 v[240:241], v[240:241], v[244:245]
	v_exp_f32_e32 v240, v240
	v_exp_f32_e32 v241, v241
	s_nop 0
	v_min_f32_e32 v240, v240, v248
	v_min_f32_e32 v241, v241, v248
	v_pk_add_f32 v[240:241], v[240:241], v[242:243]
	v_rcp_f32_e32 v240, v240
	v_rcp_f32_e32 v241, v241
	s_nop 0
	v_pk_mul_f32 v[240:241], v[240:241], v[8:9]
	v_cvt_pk_bf16_f32 v177, v240, v241
	v_lshlrev_b32_e32 v240, 16, v194
	v_and_b32_e32 v241, 0xffff0000, v194
	v_pk_add_f32 v[240:241], v[240:241], v[158:159]
	v_pk_mul_f32 v[240:241], v[240:241], v[244:245]
	v_exp_f32_e32 v240, v240
	v_exp_f32_e32 v241, v241
	s_nop 0
	v_min_f32_e32 v240, v240, v248
	v_min_f32_e32 v241, v241, v248
	v_pk_add_f32 v[240:241], v[240:241], v[242:243]
	v_rcp_f32_e32 v240, v240
	v_rcp_f32_e32 v241, v241
	s_nop 0
	v_pk_mul_f32 v[240:241], v[240:241], v[2:3]
	v_cvt_pk_bf16_f32 v178, v240, v241
	v_lshlrev_b32_e32 v240, 16, v195
	v_and_b32_e32 v241, 0xffff0000, v195
	v_pk_add_f32 v[240:241], v[240:241], v[160:161]
	v_pk_mul_f32 v[240:241], v[240:241], v[244:245]
	v_exp_f32_e32 v240, v240
	v_exp_f32_e32 v241, v241
	s_nop 0
	v_min_f32_e32 v240, v240, v248
	v_min_f32_e32 v241, v241, v248
	v_pk_add_f32 v[240:241], v[240:241], v[242:243]
	v_rcp_f32_e32 v240, v240
	v_rcp_f32_e32 v241, v241
	s_nop 0
	v_pk_mul_f32 v[240:241], v[240:241], v[4:5]
	v_cvt_pk_bf16_f32 v179, v240, v241
	s_mov_b64 s[98:99], 0x58000
	v_lshl_add_u64 v[254:255], v[252:253], 0, s[98:99]
	global_store_dwordx4 v[254:255], v[176:179], off offset:256
	s_branch .Lg2_exit

; __global__ void __launch_bounds__(512, 2) mega_fwd(Params P) {
;     extern __shared__ __attribute__((aligned(16))) unsigned char lds[];
	.amdhsa_kernel _Z8mega_fwd6Params
		.amdhsa_group_segment_fixed_size 0
		.amdhsa_private_segment_fixed_size 0
		.amdhsa_kernarg_size 400
		.amdhsa_user_sgpr_count 2
		.amdhsa_user_sgpr_dispatch_ptr 0
		.amdhsa_user_sgpr_queue_ptr 0
		.amdhsa_user_sgpr_kernarg_segment_ptr 1
		.amdhsa_user_sgpr_dispatch_id 0
		.amdhsa_user_sgpr_kernarg_preload_length 0
		.amdhsa_user_sgpr_kernarg_preload_offset 0
		.amdhsa_user_sgpr_private_segment_size 0
		.amdhsa_uses_dynamic_stack 0
		.amdhsa_enable_private_segment 0
		.amdhsa_system_sgpr_workgroup_id_x 1
		.amdhsa_system_sgpr_workgroup_id_y 0
		.amdhsa_system_sgpr_workgroup_id_z 0
		.amdhsa_system_sgpr_workgroup_info 0
		.amdhsa_system_vgpr_workitem_id 2
		.amdhsa_next_free_vgpr 256
		.amdhsa_next_free_sgpr 102
		.amdhsa_accum_offset 256
		.amdhsa_reserve_vcc 1
		.amdhsa_float_round_mode_32 0
		.amdhsa_float_round_mode_16_64 0
		.amdhsa_float_denorm_mode_32 3
		.amdhsa_float_denorm_mode_16_64 3
		.amdhsa_dx10_clamp 1
		.amdhsa_ieee_mode 1
		.amdhsa_fp16_overflow 0
		.amdhsa_tg_split 0
		.amdhsa_exception_fp_ieee_invalid_op 0
		.amdhsa_exception_fp_denorm_src 0
		.amdhsa_exception_fp_ieee_div_zero 0
		.amdhsa_exception_fp_ieee_overflow 0
		.amdhsa_exception_fp_ieee_underflow 0
		.amdhsa_exception_fp_ieee_inexact 0
		.amdhsa_exception_int_div_zero 0
	.end_amdhsa_kernel

; __global__ void __launch_bounds__(512, 2) mega_fwd(Params P) {
;     extern __shared__ __attribute__((aligned(16))) unsigned char lds[];
amdhsa.kernels:
  - .agpr_count:     0
    .args:
      - .offset:         0
        .size:           144
        .value_kind:     by_value
      - .offset:         144
        .size:           4
        .value_kind:     hidden_block_count_x
      - .offset:         148
        .size:           4
        .value_kind:     hidden_block_count_y
      - .offset:         152
        .size:           4
        .value_kind:     hidden_block_count_z
      - .offset:         156
        .size:           2
        .value_kind:     hidden_group_size_x
      - .offset:         158
        .size:           2
        .value_kind:     hidden_group_size_y
      - .offset:         160
        .size:           2
        .value_kind:     hidden_group_size_z
      - .offset:         162
        .size:           2
        .value_kind:     hidden_remainder_x
      - .offset:         164
        .size:           2
        .value_kind:     hidden_remainder_y
      - .offset:         166
        .size:           2
        .value_kind:     hidden_remainder_z
      - .offset:         184
        .size:           8
        .value_kind:     hidden_global_offset_x
      - .offset:         192
        .size:           8
        .value_kind:     hidden_global_offset_y
      - .offset:         200
        .size:           8
        .value_kind:     hidden_global_offset_z
      - .offset:         208
        .size:           2
        .value_kind:     hidden_grid_dims
      - .offset:         232
        .size:           8
        .value_kind:     hidden_multigrid_sync_arg
      - .offset:         264
        .size:           4
        .value_kind:     hidden_dynamic_lds_size
    .group_segment_fixed_size: 0
    .kernarg_segment_align: 8
    .kernarg_segment_size: 400
    .language:       OpenCL C
    .language_version:
      - 2
      - 0
    .max_flat_workgroup_size: 512
    .name:           _Z8mega_fwd6Params
    .private_segment_fixed_size: 0
    .sgpr_count:     108
    .sgpr_spill_count: 85
    .symbol:         _Z8mega_fwd6Params.kd
    .uniform_work_group_size: 1
    .uses_dynamic_stack: false
    .vgpr_count:     256
    .vgpr_spill_count: 0
    .wavefront_size: 64
